# GEMM k-loops: second barrier after the up-front fragment reads frees the LDS stage early; loads of k-step k+2 issued during the MFMAs of k (two k-steps of LDS-DMA in flight)
# baseline (speedup 1.0000x reference)
.LBB0_230:
	s_ashr_i32 s24, s26, 3
	s_add_i32 s27, s27, s24
	s_mul_hi_i32 s24, s27, 0x4bda12f7
	s_lshr_b32 s25, s24, 31
	s_ashr_i32 s24, s24, 6
	s_add_i32 s24, s24, s25
	s_lshl_b32 s49, s24, 3
	s_mul_i32 s47, s24, 0xd8
	s_sub_i32 s24, 0x84, s49
	s_min_u32 s48, s24, 8
	s_sub_i32 s46, s27, s47
	v_cvt_f32_ubyte0_e32 v1, s48
	v_cvt_f32_i32_e32 v0, s46
	v_rcp_iflag_f32_e32 v2, v1
	s_ashr_i32 s24, s46, 30
	s_or_b32 s26, s24, 1
	v_mul_f32_e32 v2, v0, v2
	v_trunc_f32_e32 v2, v2
	v_fma_f32 v0, -v2, v1, v0
	v_cvt_i32_f32_e32 v2, v2
	v_cmp_ge_f32_e64 s[24:25], |v0|, v1
	s_and_b64 s[24:25], s[24:25], exec
	s_cselect_b32 s24, s26, 0
	v_readfirstlane_b32 s45, v2
	s_add_i32 s45, s45, s24
	s_mul_i32 s50, s45, s48
	s_sub_i32 s24, s46, s50
	s_sext_i32_i16 s24, s24
	s_sext_i32_i16 s26, s45
	s_add_i32 s46, s49, s24
	v_mad_i64_i32 v[0:1], s[24:25], s46, v91, v[66:67]
	v_mad_i64_i32 v[2:3], s[24:25], s26, v91, v[68:69]
	v_readfirstlane_b32 s24, v92
	s_mov_b32 m0, s24
	v_readfirstlane_b32 s24, v93
	s_barrier
	global_load_lds_dwordx4 v[0:1], off
	s_mov_b32 m0, s24
	v_readfirstlane_b32 s24, v94
	global_load_lds_dwordx4 v[2:3], off
	v_lshl_add_u64 v[4:5], v[0:1], 0, s[4:5]
	s_mov_b32 m0, s24
	v_readfirstlane_b32 s24, v95
	global_load_lds_dwordx4 v[4:5], off
	v_lshl_add_u64 v[4:5], v[2:3], 0, s[4:5]
	s_mov_b32 m0, s24
	v_readfirstlane_b32 s24, v96
	global_load_lds_dwordx4 v[4:5], off
	v_lshl_add_u64 v[4:5], v[0:1], 0, s[6:7]
	s_mov_b32 m0, s24
	v_readfirstlane_b32 s24, v97
	global_load_lds_dwordx4 v[4:5], off
	v_lshl_add_u64 v[4:5], v[2:3], 0, s[6:7]
	s_mov_b32 m0, s24
	v_readfirstlane_b32 s24, v98
	global_load_lds_dwordx4 v[4:5], off
	v_lshl_add_u64 v[0:1], v[0:1], 0, s[8:9]
	s_mov_b32 m0, s24
	v_readfirstlane_b32 s24, v99
	global_load_lds_dwordx4 v[0:1], off
	v_lshl_add_u64 v[0:1], v[2:3], 0, s[8:9]
	s_mov_b32 m0, s24
	s_sub_i32 s24, s27, s50
	global_load_lds_dwordx4 v[0:1], off
	s_sub_i32 s24, s24, s47
	s_sext_i32_i16 s24, s24
	s_add_i32 s49, s49, s24
	v_mov_b32_e32 v28, 0
	s_mov_b32 s48, 0
	s_mov_b64 s[24:25], 0
	v_mov_b32_e32 v29, v28
	v_mov_b32_e32 v30, v28
	v_mov_b32_e32 v31, v28
	v_mov_b32_e32 v0, v28
	v_mov_b32_e32 v1, v28
	v_mov_b32_e32 v2, v28
	v_mov_b32_e32 v3, v28
	v_mov_b32_e32 v4, v28
	v_mov_b32_e32 v5, v28
	v_mov_b32_e32 v6, v28
	v_mov_b32_e32 v7, v28
	v_mov_b32_e32 v8, v28
	v_mov_b32_e32 v9, v28
	v_mov_b32_e32 v10, v28
	v_mov_b32_e32 v11, v28
	v_mov_b32_e32 v12, v28
	v_mov_b32_e32 v13, v28
	v_mov_b32_e32 v14, v28
	v_mov_b32_e32 v15, v28
	v_mov_b32_e32 v16, v28
	v_mov_b32_e32 v17, v28
	v_mov_b32_e32 v18, v28
	v_mov_b32_e32 v19, v28
	v_mov_b32_e32 v20, v28
	v_mov_b32_e32 v21, v28
	v_mov_b32_e32 v22, v28
	v_mov_b32_e32 v23, v28
	v_mov_b32_e32 v24, v28
	v_mov_b32_e32 v25, v28
	v_mov_b32_e32 v26, v28
	v_mov_b32_e32 v27, v28
	v_mov_b32_e32 v32, v28
	v_mov_b32_e32 v33, v28
	v_mov_b32_e32 v34, v28
	v_mov_b32_e32 v35, v28
	v_mov_b32_e32 v36, v28
	v_mov_b32_e32 v37, v28
	v_mov_b32_e32 v38, v28
	v_mov_b32_e32 v39, v28
	v_mov_b32_e32 v40, v28
	v_mov_b32_e32 v41, v28
	v_mov_b32_e32 v42, v28
	v_mov_b32_e32 v43, v28
	v_mov_b32_e32 v44, v28
	v_mov_b32_e32 v45, v28
	v_mov_b32_e32 v46, v28
	v_mov_b32_e32 v47, v28
	v_mov_b32_e32 v48, v28
	v_mov_b32_e32 v49, v28
	v_mov_b32_e32 v50, v28
	v_mov_b32_e32 v51, v28
	v_mov_b32_e32 v52, v28
	v_mov_b32_e32 v53, v28
	v_mov_b32_e32 v54, v28
	v_mov_b32_e32 v55, v28
	v_mov_b32_e32 v56, v28
	v_mov_b32_e32 v57, v28
	v_mov_b32_e32 v58, v28
	v_mov_b32_e32 v59, v28
	v_mov_b32_e32 v60, v28
	v_mov_b32_e32 v61, v28
	v_mov_b32_e32 v62, v28
	v_mov_b32_e32 v63, v28
	v_mad_i64_i32 v[80:81], s[50:51], s49, v91, v[76:77]
	v_mad_i64_i32 v[82:83], s[50:51], s26, v91, v[78:79]
	v_readfirstlane_b32 s96, v80
	v_readfirstlane_b32 s97, v81
	v_readfirstlane_b32 s72, v82
	v_readfirstlane_b32 s73, v83
	v_readfirstlane_b32 s71, v84
	s_nop 1
	v_subrev_u32_e32 v244, s96, v80
	v_subrev_u32_e32 v245, s72, v82
	v_add_u32_e32 v246, 0x11000, v244
	v_add_u32_e32 v247, 0x11000, v245
	v_add_u32_e32 v248, 0x22000, v244
	v_add_u32_e32 v249, 0x22000, v245
	v_add_u32_e32 v250, 0x33000, v244
	v_add_u32_e32 v251, 0x33000, v245
	s_add_u32 s96, s96, 0x2200080
	s_addc_u32 s97, s97, 0
	s_add_u32 s72, s72, 0x700080
	s_addc_u32 s73, s73, 0
	s_add_u32 s70, s71, 0x8000
	s_mov_b32 m0, s70
	s_nop 0
	global_load_lds_dwordx4 v244, s[96:97]
	s_add_u32 m0, s70, 0x4000
	s_nop 0
	global_load_lds_dwordx4 v245, s[72:73]
	s_add_u32 m0, s70, 0x1000
	s_nop 0
	global_load_lds_dwordx4 v246, s[96:97]
	s_add_u32 m0, s70, 0x5000
	s_nop 0
	global_load_lds_dwordx4 v247, s[72:73]
	s_add_u32 m0, s70, 0x2000
	s_nop 0
	global_load_lds_dwordx4 v248, s[96:97]
	s_add_u32 m0, s70, 0x6000
	s_nop 0
	global_load_lds_dwordx4 v249, s[72:73]
	s_add_u32 m0, s70, 0x3000
	s_nop 0
	global_load_lds_dwordx4 v250, s[96:97]
	s_add_u32 m0, s70, 0x7000
	s_nop 0
	global_load_lds_dwordx4 v251, s[72:73]
	s_add_u32 s96, s96, 0x80
	s_addc_u32 s97, s97, 0
	s_add_u32 s72, s72, 0x80
	s_addc_u32 s73, s73, 0
.LBB0_231:
	s_add_i32 s47, s48, 0x8000
	s_and_b32 s27, s48, 0x8000
	s_and_b32 s50, s47, 0x8000
	s_add_i32 s48, s27, 0
	s_add_i32 s27, s50, 0
	s_add_u32 s70, s48, s71
	s_waitcnt vmcnt(8)
	s_barrier
	v_add3_u32 v145, s48, v86, v87
	v_add3_u32 v208, s48, v87, v88
	v_add3_u32 v209, s48, v86, v89
	v_add3_u32 v210, s48, v88, v89
	ds_read_b128 v[104:107], v208
	ds_read_b128 v[100:103], v145 offset:16384
	ds_read_b128 v[108:111], v145 offset:18432
	ds_read_b128 v[164:167], v208 offset:2048
	ds_read_b128 v[112:115], v145 offset:20480
	ds_read_b128 v[116:119], v145 offset:22528
	ds_read_b128 v[120:123], v145 offset:24576
	ds_read_b128 v[124:127], v145 offset:26624
	ds_read_b128 v[128:131], v145 offset:28672
	ds_read_b128 v[132:135], v145 offset:30720
	ds_read_b128 v[200:203], v210
	ds_read_b128 v[168:171], v209 offset:16384
	ds_read_b128 v[172:175], v209 offset:18432
	ds_read_b128 v[204:207], v210 offset:2048
	ds_read_b128 v[176:179], v209 offset:20480
	ds_read_b128 v[180:183], v209 offset:22528
	ds_read_b128 v[184:187], v209 offset:24576
	ds_read_b128 v[188:191], v209 offset:26624
	ds_read_b128 v[192:195], v209 offset:28672
	ds_read_b128 v[196:199], v209 offset:30720
	s_waitcnt lgkmcnt(0)
	s_barrier
	s_cmpk_eq_i32 s24, 0x700
	s_cbranch_scc1 .Lgskip_231
	s_mov_b32 m0, s70
	s_nop 0
	global_load_lds_dwordx4 v244, s[96:97]
	s_add_u32 m0, s70, 0x4000
	s_nop 0
	global_load_lds_dwordx4 v245, s[72:73]
	s_add_u32 m0, s70, 0x1000
	s_nop 0
	global_load_lds_dwordx4 v246, s[96:97]
	s_add_u32 m0, s70, 0x5000
	s_nop 0
	global_load_lds_dwordx4 v247, s[72:73]
	s_add_u32 m0, s70, 0x2000
	s_nop 0
	global_load_lds_dwordx4 v248, s[96:97]
	s_add_u32 m0, s70, 0x6000
	s_nop 0
	global_load_lds_dwordx4 v249, s[72:73]
	s_add_u32 m0, s70, 0x3000
	s_nop 0
	global_load_lds_dwordx4 v250, s[96:97]
	s_add_u32 m0, s70, 0x7000
	s_nop 0
	global_load_lds_dwordx4 v251, s[72:73]
	s_add_u32 s96, s96, 0x80
	s_addc_u32 s97, s97, 0
	s_add_u32 s72, s72, 0x80
	s_addc_u32 s73, s73, 0
.Lgskip_231:
	s_add_u32 s24, s24, 0x80
	s_addc_u32 s25, s25, 0
	s_cmpk_eq_i32 s24, 0x780
	s_mov_b32 s48, s47
	v_mfma_f32_16x16x32_bf16 v[60:63], v[100:103], v[104:107], v[60:63]
	v_mfma_f32_16x16x32_bf16 v[56:59], v[108:111], v[104:107], v[56:59]
	v_mfma_f32_16x16x32_bf16 v[24:27], v[100:103], v[164:167], v[24:27]
	v_mfma_f32_16x16x32_bf16 v[20:23], v[108:111], v[164:167], v[20:23]
	v_mfma_f32_16x16x32_bf16 v[52:55], v[112:115], v[104:107], v[52:55]
	v_mfma_f32_16x16x32_bf16 v[16:19], v[112:115], v[164:167], v[16:19]
	v_mfma_f32_16x16x32_bf16 v[48:51], v[116:119], v[104:107], v[48:51]
	v_mfma_f32_16x16x32_bf16 v[12:15], v[116:119], v[164:167], v[12:15]
	v_mfma_f32_16x16x32_bf16 v[44:47], v[120:123], v[104:107], v[44:47]
	v_mfma_f32_16x16x32_bf16 v[8:11], v[120:123], v[164:167], v[8:11]
	v_mfma_f32_16x16x32_bf16 v[40:43], v[124:127], v[104:107], v[40:43]
	v_mfma_f32_16x16x32_bf16 v[4:7], v[124:127], v[164:167], v[4:7]
	v_mfma_f32_16x16x32_bf16 v[36:39], v[128:131], v[104:107], v[36:39]
	v_mfma_f32_16x16x32_bf16 v[0:3], v[128:131], v[164:167], v[0:3]
	v_mfma_f32_16x16x32_bf16 v[32:35], v[132:135], v[104:107], v[32:35]
	v_mfma_f32_16x16x32_bf16 v[28:31], v[132:135], v[164:167], v[28:31]
	v_mfma_f32_16x16x32_bf16 v[60:63], v[168:171], v[200:203], v[60:63]
	v_mfma_f32_16x16x32_bf16 v[56:59], v[172:175], v[200:203], v[56:59]
	v_mfma_f32_16x16x32_bf16 v[24:27], v[168:171], v[204:207], v[24:27]
	v_mfma_f32_16x16x32_bf16 v[20:23], v[172:175], v[204:207], v[20:23]
	v_mfma_f32_16x16x32_bf16 v[52:55], v[176:179], v[200:203], v[52:55]
	v_mfma_f32_16x16x32_bf16 v[16:19], v[176:179], v[204:207], v[16:19]
	v_mfma_f32_16x16x32_bf16 v[48:51], v[180:183], v[200:203], v[48:51]
	v_mfma_f32_16x16x32_bf16 v[12:15], v[180:183], v[204:207], v[12:15]
	v_mfma_f32_16x16x32_bf16 v[44:47], v[184:187], v[200:203], v[44:47]
	v_mfma_f32_16x16x32_bf16 v[8:11], v[184:187], v[204:207], v[8:11]
	v_mfma_f32_16x16x32_bf16 v[40:43], v[188:191], v[200:203], v[40:43]
	v_mfma_f32_16x16x32_bf16 v[4:7], v[188:191], v[204:207], v[4:7]
	v_mfma_f32_16x16x32_bf16 v[36:39], v[192:195], v[200:203], v[36:39]
	v_mfma_f32_16x16x32_bf16 v[0:3], v[192:195], v[204:207], v[0:3]
	v_mfma_f32_16x16x32_bf16 v[32:35], v[196:199], v[200:203], v[32:35]
	v_mfma_f32_16x16x32_bf16 v[28:31], v[196:199], v[204:207], v[28:31]
	s_cbranch_scc0 .LBB0_231
	v_add_u32_e32 v64, s27, v86
	v_add_u32_e32 v136, v64, v87
	v_add3_u32 v108, s27, v87, v88
	s_waitcnt vmcnt(0)
	s_barrier
	ds_read_b128 v[80:83], v136 offset:16384
	ds_read_b128 v[100:103], v136 offset:18432
	ds_read_b128 v[104:107], v108
	ds_read_b128 v[108:111], v108 offset:2048
	ds_read_b128 v[112:115], v136 offset:20480
	ds_read_b128 v[116:119], v136 offset:22528
	ds_read_b128 v[128:131], v136 offset:28672
	s_waitcnt lgkmcnt(2)
	v_mfma_f32_16x16x32_bf16 v[120:123], v[112:115], v[104:107], v[52:55]
	s_nop 2
	ds_read_b128 v[52:55], v136 offset:24576
	ds_read_b128 v[124:127], v136 offset:26624
	s_cmp_gt_i32 s26, 11
	s_waitcnt lgkmcnt(0)
	v_mfma_f32_16x16x32_bf16 v[132:135], v[124:127], v[104:107], v[40:43]
	s_nop 2
	ds_read_b128 v[40:43], v136 offset:30720
	s_cselect_b64 s[24:25], -1, 0
	s_cmp_lt_i32 s26, 12
	v_mfma_f32_16x16x32_bf16 v[60:63], v[80:83], v[104:107], v[60:63]
	s_cselect_b64 s[48:49], -1, 0
	v_mfma_f32_16x16x32_bf16 v[56:59], v[100:103], v[104:107], v[56:59]
	v_mfma_f32_16x16x32_bf16 v[48:51], v[116:119], v[104:107], v[48:51]
	v_mfma_f32_16x16x32_bf16 v[44:47], v[52:55], v[104:107], v[44:47]
	v_mfma_f32_16x16x32_bf16 v[136:139], v[128:131], v[104:107], v[36:39]
	s_waitcnt lgkmcnt(0)
	v_mfma_f32_16x16x32_bf16 v[32:35], v[40:43], v[104:107], v[32:35]
	v_mfma_f32_16x16x32_bf16 v[104:107], v[52:55], v[108:111], v[8:11]
	s_nop 2
	v_add_u32_e32 v8, v64, v89
	v_mfma_f32_16x16x32_bf16 v[24:27], v[80:83], v[108:111], v[24:27]
	v_add3_u32 v9, s27, v89, v88
	v_lshl_or_b32 v64, s26, 7, v90
	s_sub_i32 s26, s26, 18
	v_mfma_f32_16x16x32_bf16 v[80:83], v[112:115], v[108:111], v[16:19]
	s_cmp_lt_u32 s26, 8
	s_cselect_b64 s[26:27], -1, 0
	s_or_b64 s[48:49], s[48:49], s[26:27]
	v_mfma_f32_16x16x32_bf16 v[112:115], v[124:127], v[108:111], v[4:7]
	s_mov_b64 s[26:27], -1
	s_andn2_b64 vcc, exec, s[48:49]
	s_nop 0
	ds_read_b128 v[4:7], v8 offset:16384
	v_mfma_f32_16x16x32_bf16 v[20:23], v[100:103], v[108:111], v[20:23]
	v_mfma_f32_16x16x32_bf16 v[100:103], v[116:119], v[108:111], v[12:15]
	v_mfma_f32_16x16x32_bf16 v[116:119], v[128:131], v[108:111], v[0:3]
	ds_read_b128 v[124:127], v8 offset:18432
	s_nop 1
	ds_read_b128 v[0:3], v9
	ds_read_b128 v[128:131], v9 offset:2048
	ds_read_b128 v[140:143], v8 offset:22528
	ds_read_b128 v[146:149], v8 offset:28672
	s_waitcnt lgkmcnt(3)
	v_mfma_f32_16x16x32_bf16 v[52:55], v[4:7], v[0:3], v[60:63]
	s_nop 2
	ds_read_b128 v[60:63], v8 offset:20480
	v_mfma_f32_16x16x32_bf16 v[108:111], v[40:43], v[108:111], v[28:31]
	s_waitcnt lgkmcnt(0)
	v_mfma_f32_16x16x32_bf16 v[36:39], v[60:63], v[0:3], v[120:123]
	s_nop 2
	ds_read_b128 v[120:123], v8 offset:24576
	v_mfma_f32_16x16x32_bf16 v[40:43], v[140:143], v[0:3], v[48:51]
	s_nop 2
	ds_read_b128 v[48:51], v8 offset:26624
	s_waitcnt lgkmcnt(0)
	v_mfma_f32_16x16x32_bf16 v[16:19], v[48:51], v[0:3], v[132:135]
	s_nop 2
	ds_read_b128 v[132:135], v8 offset:30720
	v_mfma_f32_16x16x32_bf16 v[56:59], v[124:127], v[0:3], v[56:59]
	v_mfma_f32_16x16x32_bf16 v[12:15], v[120:123], v[0:3], v[44:47]
	v_mfma_f32_16x16x32_bf16 v[8:11], v[146:149], v[0:3], v[136:139]
	s_waitcnt lgkmcnt(0)
	v_mfma_f32_16x16x32_bf16 v[0:3], v[132:135], v[0:3], v[32:35]
	v_mfma_f32_16x16x32_bf16 v[28:31], v[4:7], v[128:131], v[24:27]
	v_mfma_f32_16x16x32_bf16 v[20:23], v[124:127], v[128:131], v[20:23]
	v_mfma_f32_16x16x32_bf16 v[4:7], v[60:63], v[128:131], v[80:83]
	v_mfma_f32_16x16x32_bf16 v[24:27], v[140:143], v[128:131], v[100:103]
	s_nop 1
	v_lshl_add_u32 v80, s46, 7, v85
	v_mfma_f32_16x16x32_bf16 v[32:35], v[120:123], v[128:131], v[104:107]
	v_mfma_f32_16x16x32_bf16 v[44:47], v[48:51], v[128:131], v[112:115]
	v_mfma_f32_16x16x32_bf16 v[48:51], v[146:149], v[128:131], v[116:119]
	v_mfma_f32_16x16x32_bf16 v[60:63], v[132:135], v[128:131], v[108:111]
	s_cbranch_vccz .LBB0_240
	s_and_b32 s47, 0xffff, s45
	s_cmp_gt_u32 s47, 17
	s_cbranch_scc0 .LBB0_237
	s_cmp_eq_u32 s47, 26
	s_cselect_b64 s[26:27], -1, 0
	s_and_b64 s[48:49], s[10:11], s[26:27]
	s_and_saveexec_b64 s[26:27], s[48:49]
	s_cbranch_execz .LBB0_236
	global_load_dwordx4 v[100:103], v[72:73], off
	v_mad_i64_i32 v[82:83], s[48:49], v80, s28, v[70:71]
	v_or_b32_e32 v81, 16, v80
	s_waitcnt vmcnt(0)
	v_pk_add_f32 v[102:103], v[54:55], v[102:103]
	v_pk_add_f32 v[100:101], v[52:53], v[100:101]
	global_store_dwordx4 v[82:83], v[100:103], off
	global_load_dwordx4 v[100:103], v[72:73], off offset:16
	v_mad_i64_i32 v[82:83], s[48:49], v80, s28, v[74:75]
	s_waitcnt vmcnt(0)
	v_pk_add_f32 v[102:103], v[58:59], v[102:103]
	v_pk_add_f32 v[100:101], v[56:57], v[100:101]
	global_store_dwordx4 v[82:83], v[100:103], off
	global_load_dwordx4 v[100:103], v[72:73], off
	v_mad_i64_i32 v[82:83], s[48:49], v81, s28, v[70:71]
	s_waitcnt vmcnt(0)
	v_pk_add_f32 v[102:103], v[30:31], v[102:103]
	v_pk_add_f32 v[100:101], v[28:29], v[100:101]
	global_store_dwordx4 v[82:83], v[100:103], off
	global_load_dwordx4 v[100:103], v[72:73], off offset:16
	v_mad_i64_i32 v[82:83], s[48:49], v81, s28, v[74:75]
	s_waitcnt vmcnt(0)
	v_pk_add_f32 v[102:103], v[22:23], v[102:103]
	v_pk_add_f32 v[100:101], v[20:21], v[100:101]
	global_store_dwordx4 v[82:83], v[100:103], off

.LBB0_854:
	s_ashr_i32 s34, s41, 3
	s_add_i32 s34, s43, s34
	s_ashr_i32 s35, s34, 31
	s_lshr_b32 s35, s35, 26
	s_add_i32 s35, s34, s35
	s_ashr_i32 s42, s35, 6
	s_and_b32 s35, s35, 0xffc0
	s_sub_i32 s34, s34, s35
	s_bfe_i32 s35, s34, 0x80000
	s_bfe_u32 s35, s35, 0x3000c
	s_add_i32 s35, s34, s35
	s_bfe_i32 s41, s35, 0x80000
	s_and_b32 s35, s35, 0xf8
	s_sub_i32 s34, s34, s35
	s_lshl_b32 s42, s42, 3
	s_sext_i32_i8 s34, s34
	s_add_i32 s34, s42, s34
	s_ashr_i32 s35, s34, 31
	s_lshr_b32 s35, s35, 26
	s_add_i32 s35, s34, s35
	s_sext_i32_i16 s41, s41
	s_ashr_i32 s42, s35, 6
	s_andn2_b32 s35, s35, 63
	s_ashr_i32 s41, s41, 3
	s_mulk_i32 s42, 0x42
	s_sub_i32 s34, s34, s35
	s_add_i32 s42, s34, s42
	s_mul_i32 s34, s41, 0x22000
	s_add_i32 s42, s42, 2
	s_ashr_i32 s35, s34, 31
	v_readfirstlane_b32 s43, v94
	v_mad_i64_i32 v[0:1], s[44:45], s42, v93, v[64:65]
	s_lshl_b64 s[34:35], s[34:35], 1
	s_mov_b32 m0, s43
	v_readfirstlane_b32 s43, v95
	v_lshl_add_u64 v[2:3], v[66:67], 0, s[34:35]
	s_waitcnt vmcnt(63) expcnt(7) lgkmcnt(15)
	s_barrier
	global_load_lds_dwordx4 v[0:1], off
	s_mov_b32 m0, s43
	v_readfirstlane_b32 s43, v96
	global_load_lds_dwordx4 v[2:3], off
	v_lshl_add_u64 v[4:5], v[0:1], 0, s[8:9]
	s_mov_b32 m0, s43
	v_readfirstlane_b32 s43, v97
	global_load_lds_dwordx4 v[4:5], off
	v_lshl_add_u64 v[4:5], v[2:3], 0, s[8:9]
	s_mov_b32 m0, s43
	v_readfirstlane_b32 s43, v98
	global_load_lds_dwordx4 v[4:5], off
	v_lshl_add_u64 v[4:5], v[0:1], 0, s[10:11]
	s_mov_b32 m0, s43
	v_readfirstlane_b32 s43, v99
	global_load_lds_dwordx4 v[4:5], off
	v_lshl_add_u64 v[4:5], v[2:3], 0, s[10:11]
	s_mov_b32 m0, s43
	v_readfirstlane_b32 s43, v100
	global_load_lds_dwordx4 v[4:5], off
	v_lshl_add_u64 v[0:1], v[0:1], 0, s[12:13]
	s_mov_b32 m0, s43
	v_readfirstlane_b32 s43, v101
	global_load_lds_dwordx4 v[0:1], off
	v_lshl_add_u64 v[0:1], v[2:3], 0, s[12:13]
	s_mov_b32 m0, s43
	v_mov_b32_e32 v36, 0
	global_load_lds_dwordx4 v[0:1], off
	v_mad_i64_i32 v[72:73], s[44:45], s42, v93, v[68:69]
	v_lshl_add_u64 v[74:75], v[70:71], 0, s[34:35]
	s_mov_b64 s[34:35], 0
	s_mov_b32 s43, 0
	v_mov_b32_e32 v37, v36
	v_mov_b32_e32 v38, v36
	v_mov_b32_e32 v39, v36
	v_mov_b32_e32 v0, v36
	v_mov_b32_e32 v1, v36
	v_mov_b32_e32 v2, v36
	v_mov_b32_e32 v3, v36
	v_mov_b32_e32 v4, v36
	v_mov_b32_e32 v5, v36
	v_mov_b32_e32 v6, v36
	v_mov_b32_e32 v7, v36
	v_mov_b32_e32 v8, v36
	v_mov_b32_e32 v9, v36
	v_mov_b32_e32 v10, v36
	v_mov_b32_e32 v11, v36
	v_mov_b32_e32 v12, v36
	v_mov_b32_e32 v13, v36
	v_mov_b32_e32 v14, v36
	v_mov_b32_e32 v15, v36
	v_mov_b32_e32 v16, v36
	v_mov_b32_e32 v17, v36
	v_mov_b32_e32 v18, v36
	v_mov_b32_e32 v19, v36
	v_mov_b32_e32 v20, v36
	v_mov_b32_e32 v21, v36
	v_mov_b32_e32 v22, v36
	v_mov_b32_e32 v23, v36
	v_mov_b32_e32 v24, v36
	v_mov_b32_e32 v25, v36
	v_mov_b32_e32 v26, v36
	v_mov_b32_e32 v27, v36
	v_mov_b32_e32 v28, v36
	v_mov_b32_e32 v29, v36
	v_mov_b32_e32 v30, v36
	v_mov_b32_e32 v31, v36
	v_mov_b32_e32 v32, v36
	v_mov_b32_e32 v33, v36
	v_mov_b32_e32 v34, v36
	v_mov_b32_e32 v35, v36
	v_mov_b32_e32 v40, v36
	v_mov_b32_e32 v41, v36
	v_mov_b32_e32 v42, v36
	v_mov_b32_e32 v43, v36
	v_mov_b32_e32 v44, v36
	v_mov_b32_e32 v45, v36
	v_mov_b32_e32 v46, v36
	v_mov_b32_e32 v47, v36
	v_mov_b32_e32 v48, v36
	v_mov_b32_e32 v49, v36
	v_mov_b32_e32 v50, v36
	v_mov_b32_e32 v51, v36
	v_mov_b32_e32 v52, v36
	v_mov_b32_e32 v53, v36
	v_mov_b32_e32 v54, v36
	v_mov_b32_e32 v55, v36
	v_mov_b32_e32 v56, v36
	v_mov_b32_e32 v57, v36
	v_mov_b32_e32 v58, v36
	v_mov_b32_e32 v59, v36
	v_mov_b32_e32 v60, v36
	v_mov_b32_e32 v61, v36
	v_mov_b32_e32 v62, v36
	v_mov_b32_e32 v63, v36
	v_readfirstlane_b32 s96, v72
	v_readfirstlane_b32 s97, v73
	v_readfirstlane_b32 s88, v74
	v_readfirstlane_b32 s89, v75
	v_readfirstlane_b32 s87, v87
	s_nop 1
	v_subrev_u32_e32 v244, s96, v72
	v_subrev_u32_e32 v245, s88, v74
	v_add_u32_e32 v246, 0x11000, v244
	v_add_u32_e32 v247, 0x11000, v245
	v_add_u32_e32 v248, 0x22000, v244
	v_add_u32_e32 v249, 0x22000, v245
	v_add_u32_e32 v250, 0x33000, v244
	v_add_u32_e32 v251, 0x33000, v245
	s_add_u32 s96, s96, 0x2200080
	s_addc_u32 s97, s97, 0
	s_add_u32 s88, s88, 0xe70080
	s_addc_u32 s89, s89, 0
	s_add_u32 s86, s87, 0x8000
	s_mov_b32 m0, s86
	s_nop 0
	global_load_lds_dwordx4 v244, s[96:97]
	s_add_u32 m0, s86, 0x4000
	s_nop 0
	global_load_lds_dwordx4 v245, s[88:89]
	s_add_u32 m0, s86, 0x1000
	s_nop 0
	global_load_lds_dwordx4 v246, s[96:97]
	s_add_u32 m0, s86, 0x5000
	s_nop 0
	global_load_lds_dwordx4 v247, s[88:89]
	s_add_u32 m0, s86, 0x2000
	s_nop 0
	global_load_lds_dwordx4 v248, s[96:97]
	s_add_u32 m0, s86, 0x6000
	s_nop 0
	global_load_lds_dwordx4 v249, s[88:89]
	s_add_u32 m0, s86, 0x3000
	s_nop 0
	global_load_lds_dwordx4 v250, s[96:97]
	s_add_u32 m0, s86, 0x7000
	s_nop 0
	global_load_lds_dwordx4 v251, s[88:89]
	s_add_u32 s96, s96, 0x80
	s_addc_u32 s97, s97, 0
	s_add_u32 s88, s88, 0x80
	s_addc_u32 s89, s89, 0
.LBB0_855:
	s_add_i32 s45, s43, 0x8000
	s_and_b32 s44, s45, 0x8000
	s_add_i32 s44, s44, 0
	s_and_b32 s43, s43, 0x8000
	s_add_i32 s43, s43, 0
	s_add_u32 s86, s43, s87
	s_waitcnt vmcnt(8)
	s_barrier
	v_add3_u32 v212, s43, v88, v89
	v_add3_u32 v213, s43, v89, v90
	v_add3_u32 v214, s43, v88, v91
	v_add3_u32 v215, s43, v90, v91
	ds_read_b128 v[106:109], v213
	ds_read_b128 v[76:79], v212 offset:16384
	ds_read_b128 v[102:105], v212 offset:18432
	ds_read_b128 v[110:113], v213 offset:2048
	ds_read_b128 v[114:117], v212 offset:20480
	ds_read_b128 v[118:121], v212 offset:22528
	ds_read_b128 v[122:125], v212 offset:24576
	ds_read_b128 v[126:129], v212 offset:26624
	ds_read_b128 v[130:133], v212 offset:28672
	ds_read_b128 v[134:137], v212 offset:30720
	ds_read_b128 v[180:183], v215
	ds_read_b128 v[172:175], v214 offset:16384
	ds_read_b128 v[176:179], v214 offset:18432
	ds_read_b128 v[184:187], v215 offset:2048
	ds_read_b128 v[188:191], v214 offset:20480
	ds_read_b128 v[192:195], v214 offset:22528
	ds_read_b128 v[196:199], v214 offset:24576
	ds_read_b128 v[200:203], v214 offset:26624
	ds_read_b128 v[204:207], v214 offset:28672
	ds_read_b128 v[208:211], v214 offset:30720
	s_waitcnt lgkmcnt(0)
	s_barrier
	s_cmpk_eq_i32 s34, 0x700
	s_cbranch_scc1 .Lgskip_855
	s_mov_b32 m0, s86
	s_nop 0
	global_load_lds_dwordx4 v244, s[96:97]
	s_add_u32 m0, s86, 0x4000
	s_nop 0
	global_load_lds_dwordx4 v245, s[88:89]
	s_add_u32 m0, s86, 0x1000
	s_nop 0
	global_load_lds_dwordx4 v246, s[96:97]
	s_add_u32 m0, s86, 0x5000
	s_nop 0
	global_load_lds_dwordx4 v247, s[88:89]
	s_add_u32 m0, s86, 0x2000
	s_nop 0
	global_load_lds_dwordx4 v248, s[96:97]
	s_add_u32 m0, s86, 0x6000
	s_nop 0
	global_load_lds_dwordx4 v249, s[88:89]
	s_add_u32 m0, s86, 0x3000
	s_nop 0
	global_load_lds_dwordx4 v250, s[96:97]
	s_add_u32 m0, s86, 0x7000
	s_nop 0
	global_load_lds_dwordx4 v251, s[88:89]
	s_add_u32 s96, s96, 0x80
	s_addc_u32 s97, s97, 0
	s_add_u32 s88, s88, 0x80
	s_addc_u32 s89, s89, 0
.Lgskip_855:
	s_add_u32 s34, s34, 0x80
	s_addc_u32 s35, s35, 0
	s_cmpk_eq_i32 s34, 0x780
	s_mov_b32 s43, s45
	v_mfma_f32_16x16x32_bf16 v[60:63], v[76:79], v[106:109], v[60:63]
	v_mfma_f32_16x16x32_bf16 v[56:59], v[102:105], v[106:109], v[56:59]
	v_mfma_f32_16x16x32_bf16 v[24:27], v[76:79], v[110:113], v[24:27]
	v_mfma_f32_16x16x32_bf16 v[20:23], v[102:105], v[110:113], v[20:23]
	v_mfma_f32_16x16x32_bf16 v[52:55], v[114:117], v[106:109], v[52:55]
	v_mfma_f32_16x16x32_bf16 v[16:19], v[114:117], v[110:113], v[16:19]
	v_mfma_f32_16x16x32_bf16 v[48:51], v[118:121], v[106:109], v[48:51]
	v_mfma_f32_16x16x32_bf16 v[12:15], v[118:121], v[110:113], v[12:15]
	v_mfma_f32_16x16x32_bf16 v[44:47], v[122:125], v[106:109], v[44:47]
	v_mfma_f32_16x16x32_bf16 v[8:11], v[122:125], v[110:113], v[8:11]
	v_mfma_f32_16x16x32_bf16 v[40:43], v[126:129], v[106:109], v[40:43]
	v_mfma_f32_16x16x32_bf16 v[4:7], v[126:129], v[110:113], v[4:7]
	v_mfma_f32_16x16x32_bf16 v[32:35], v[130:133], v[106:109], v[32:35]
	v_mfma_f32_16x16x32_bf16 v[0:3], v[130:133], v[110:113], v[0:3]
	v_mfma_f32_16x16x32_bf16 v[28:31], v[134:137], v[106:109], v[28:31]
	v_mfma_f32_16x16x32_bf16 v[36:39], v[134:137], v[110:113], v[36:39]
	v_mfma_f32_16x16x32_bf16 v[60:63], v[172:175], v[180:183], v[60:63]
	v_mfma_f32_16x16x32_bf16 v[56:59], v[176:179], v[180:183], v[56:59]
	v_mfma_f32_16x16x32_bf16 v[24:27], v[172:175], v[184:187], v[24:27]
	v_mfma_f32_16x16x32_bf16 v[20:23], v[176:179], v[184:187], v[20:23]
	v_mfma_f32_16x16x32_bf16 v[52:55], v[188:191], v[180:183], v[52:55]
	v_mfma_f32_16x16x32_bf16 v[16:19], v[188:191], v[184:187], v[16:19]
	v_mfma_f32_16x16x32_bf16 v[48:51], v[192:195], v[180:183], v[48:51]
	v_mfma_f32_16x16x32_bf16 v[12:15], v[192:195], v[184:187], v[12:15]
	v_mfma_f32_16x16x32_bf16 v[44:47], v[196:199], v[180:183], v[44:47]
	v_mfma_f32_16x16x32_bf16 v[8:11], v[196:199], v[184:187], v[8:11]
	v_mfma_f32_16x16x32_bf16 v[40:43], v[200:203], v[180:183], v[40:43]
	v_mfma_f32_16x16x32_bf16 v[4:7], v[200:203], v[184:187], v[4:7]
	v_mfma_f32_16x16x32_bf16 v[32:35], v[204:207], v[180:183], v[32:35]
	v_mfma_f32_16x16x32_bf16 v[0:3], v[204:207], v[184:187], v[0:3]
	v_mfma_f32_16x16x32_bf16 v[28:31], v[208:211], v[180:183], v[28:31]
	v_mfma_f32_16x16x32_bf16 v[36:39], v[208:211], v[184:187], v[36:39]
	s_cbranch_scc0 .LBB0_855
	v_add_u32_e32 v80, s44, v88
	v_add_u32_e32 v81, v80, v89
	v_add3_u32 v106, s44, v89, v90
	s_waitcnt vmcnt(0)
	s_barrier
	ds_read_b128 v[72:75], v81 offset:16384
	ds_read_b128 v[76:79], v81 offset:18432
	ds_read_b128 v[102:105], v106
	ds_read_b128 v[106:109], v106 offset:2048
	ds_read_b128 v[110:113], v81 offset:20480
	ds_read_b128 v[114:117], v81 offset:22528
	ds_read_b128 v[118:121], v81 offset:24576
	ds_read_b128 v[122:125], v81 offset:26624
	ds_read_b128 v[126:129], v81 offset:28672
	ds_read_b128 v[130:133], v81 offset:30720
	v_add_u32_e32 v80, v80, v91
	s_waitcnt lgkmcnt(7)
	v_mfma_f32_16x16x32_bf16 v[60:63], v[72:75], v[102:105], v[60:63]
	s_lshl_b32 s42, s42, 7
	v_mfma_f32_16x16x32_bf16 v[56:59], v[76:79], v[102:105], v[56:59]
	s_waitcnt lgkmcnt(4)
	v_mfma_f32_16x16x32_bf16 v[48:51], v[114:117], v[102:105], v[48:51]
	s_waitcnt lgkmcnt(3)
	v_mfma_f32_16x16x32_bf16 v[44:47], v[118:121], v[102:105], v[44:47]
	s_waitcnt lgkmcnt(2)
	v_mfma_f32_16x16x32_bf16 v[40:43], v[122:125], v[102:105], v[40:43]
	s_waitcnt lgkmcnt(1)
	v_mfma_f32_16x16x32_bf16 v[32:35], v[126:129], v[102:105], v[32:35]
	s_waitcnt lgkmcnt(0)
	v_mfma_f32_16x16x32_bf16 v[28:31], v[130:133], v[102:105], v[28:31]
	v_mfma_f32_16x16x32_bf16 v[24:27], v[72:75], v[106:109], v[24:27]
	ds_read_b128 v[72:75], v80 offset:16384
	v_mfma_f32_16x16x32_bf16 v[52:55], v[110:113], v[102:105], v[52:55]
	v_mfma_f32_16x16x32_bf16 v[20:23], v[76:79], v[106:109], v[20:23]
	v_mfma_f32_16x16x32_bf16 v[16:19], v[110:113], v[106:109], v[16:19]
	v_mfma_f32_16x16x32_bf16 v[12:15], v[114:117], v[106:109], v[12:15]
	v_mfma_f32_16x16x32_bf16 v[8:11], v[118:121], v[106:109], v[8:11]
	v_mfma_f32_16x16x32_bf16 v[4:7], v[122:125], v[106:109], v[4:7]
	v_mfma_f32_16x16x32_bf16 v[0:3], v[126:129], v[106:109], v[0:3]
	v_mfma_f32_16x16x32_bf16 v[102:105], v[130:133], v[106:109], v[36:39]
	s_nop 2
	v_add3_u32 v36, s44, v91, v90
	ds_read_b128 v[76:79], v80 offset:18432
	ds_read_b128 v[106:109], v36
	ds_read_b128 v[110:113], v36 offset:2048
	ds_read_b128 v[130:133], v80 offset:28672
	ds_read_b128 v[134:137], v80 offset:30720
	ds_read_b128 v[114:117], v80 offset:20480
	ds_read_b128 v[118:121], v80 offset:22528
	ds_read_b128 v[122:125], v80 offset:24576
	ds_read_b128 v[126:129], v80 offset:26624
	s_waitcnt lgkmcnt(7)
	v_mfma_f32_16x16x32_bf16 v[60:63], v[72:75], v[106:109], v[60:63]
	v_readlane_b32 s44, v252, 5
	v_readlane_b32 s48, v252, 9
	v_readlane_b32 s49, v252, 10
	s_waitcnt lgkmcnt(5)
	v_mfma_f32_16x16x32_bf16 v[36:39], v[130:133], v[106:109], v[32:35]
	v_readlane_b32 s45, v252, 6
	v_readlane_b32 s46, v252, 7
	v_readlane_b32 s47, v252, 8
	s_waitcnt lgkmcnt(4)
	v_mfma_f32_16x16x32_bf16 v[32:35], v[134:137], v[106:109], v[28:31]
	v_readlane_b32 s50, v252, 11
	v_readlane_b32 s51, v252, 12
	v_readlane_b32 s52, v252, 13
	v_mfma_f32_16x16x32_bf16 v[28:31], v[72:75], v[110:113], v[24:27]
	v_add_u32_e32 v72, s42, v82
	v_mul_hi_i32 v73, v72, s36
	v_lshrrev_b32_e32 v74, 31, v73
	v_mfma_f32_16x16x32_bf16 v[24:27], v[76:79], v[110:113], v[20:23]
	v_readlane_b32 s53, v252, 14
	v_readlane_b32 s54, v252, 15
	v_readlane_b32 s55, v252, 16
	s_waitcnt lgkmcnt(3)
	v_mfma_f32_16x16x32_bf16 v[20:23], v[114:117], v[110:113], v[16:19]
	v_readlane_b32 s56, v252, 17
	v_readlane_b32 s57, v252, 18
	v_readlane_b32 s58, v252, 19
	s_waitcnt lgkmcnt(2)
	v_mfma_f32_16x16x32_bf16 v[16:19], v[118:121], v[110:113], v[12:15]
	v_readlane_b32 s59, v252, 20
	s_waitcnt lgkmcnt(1)
	v_mfma_f32_16x16x32_bf16 v[12:15], v[122:125], v[110:113], v[8:11]
	s_waitcnt lgkmcnt(0)
	v_mfma_f32_16x16x32_bf16 v[8:11], v[126:129], v[110:113], v[4:7]
	s_nop 2
	v_ashrrev_i32_e32 v4, 11, v73
	v_mfma_f32_16x16x32_bf16 v[56:59], v[76:79], v[106:109], v[56:59]
	v_add_u32_e32 v73, v4, v74
	v_mad_i32_i24 v75, v73, s37, v72
	v_lshlrev_b32_e32 v78, 13, v73
	v_mfma_f32_16x16x32_bf16 v[52:55], v[114:117], v[106:109], v[52:55]
	v_cmp_lt_i32_e32 vcc, s38, v75
	v_mov_b64_e32 v[76:77], s[48:49]
	v_add3_u32 v74, v78, v75, s39
	v_mfma_f32_16x16x32_bf16 v[48:51], v[118:121], v[106:109], v[48:51]
	v_mfma_f32_16x16x32_bf16 v[44:47], v[122:125], v[106:109], v[44:47]
	v_mfma_f32_16x16x32_bf16 v[40:43], v[126:129], v[106:109], v[40:43]
	v_mfma_f32_16x16x32_bf16 v[0:3], v[130:133], v[110:113], v[0:3]
	v_mfma_f32_16x16x32_bf16 v[4:7], v[134:137], v[110:113], v[102:105]
	s_and_saveexec_b64 s[34:35], vcc
	s_xor_b64 s[34:35], exec, s[34:35]
	s_cbranch_execz .LBB0_858
	v_readlane_b32 s44, v252, 5
	v_readlane_b32 s45, v252, 6
	v_add3_u32 v72, v78, v75, s39
	v_readlane_b32 s46, v252, 7
	v_readlane_b32 s47, v252, 8
	v_readlane_b32 s48, v252, 9
	v_readlane_b32 s49, v252, 10
	v_readlane_b32 s50, v252, 11
	v_readlane_b32 s51, v252, 12
	v_readlane_b32 s52, v252, 13
	v_readlane_b32 s53, v252, 14
	v_readlane_b32 s54, v252, 15
	v_readlane_b32 s55, v252, 16
	v_readlane_b32 s56, v252, 17
	v_readlane_b32 s57, v252, 18
	v_readlane_b32 s58, v252, 19
	v_readlane_b32 s59, v252, 20
	v_mov_b64_e32 v[76:77], s[44:45]
	s_or_saveexec_b64 s[34:35], s[34:35]
	v_lshl_add_u32 v102, v73, 8, v75
	s_xor_b64 exec, exec, s[34:35]
	s_branch .LBB0_859

.LBB0_1005:
	s_ashr_i32 s26, s31, 31
	s_lshr_b32 s26, s26, 29
	s_add_i32 s26, s31, s26
	s_ashr_i32 s27, s26, 3
	s_and_b32 s26, s26, -8
	s_sub_i32 s26, s31, s26
	s_cmp_lt_i32 s26, 0
	s_cselect_b32 s33, s29, 0x210
	s_mul_i32 s26, s33, s26
	s_add_i32 s35, s26, s27
	s_ashr_i32 s26, s35, 31
	s_lshr_b32 s26, s26, 24
	s_add_i32 s26, s35, s26
	s_ashr_i32 s27, s26, 8
	s_lshl_b32 s37, s27, 3
	s_and_b32 s36, s26, 0xffffff00
	s_sub_i32 s26, 0x84, s37
	s_min_u32 s38, s26, 8
	s_sub_i32 s34, s35, s36
	v_cvt_f32_ubyte0_e32 v1, s38
	v_cvt_f32_i32_e32 v0, s34
	v_rcp_iflag_f32_e32 v2, v1
	s_ashr_i32 s26, s34, 30
	s_or_b32 s33, s26, 1
	s_waitcnt lgkmcnt(0)
	v_mul_f32_e32 v2, v0, v2
	v_trunc_f32_e32 v2, v2
	v_fma_f32 v0, -v2, v1, v0
	v_cvt_i32_f32_e32 v2, v2
	v_cmp_ge_f32_e64 s[26:27], |v0|, v1
	s_and_b64 s[26:27], s[26:27], exec
	s_cselect_b32 s26, s33, 0
	v_readfirstlane_b32 s27, v2
	s_add_i32 s26, s27, s26
	s_mul_i32 s38, s26, s38
	s_sext_i32_i16 s33, s26
	s_sub_i32 s26, s34, s38
	s_sext_i32_i16 s26, s26
	s_add_i32 s34, s37, s26
	v_mad_i64_i32 v[0:1], s[26:27], s34, v85, v[66:67]
	v_mad_i64_i32 v[2:3], s[26:27], s33, v85, v[68:69]
	v_readfirstlane_b32 s26, v86
	s_mov_b32 m0, s26
	v_readfirstlane_b32 s26, v87
	s_barrier
	global_load_lds_dwordx4 v[0:1], off
	s_mov_b32 m0, s26
	v_readfirstlane_b32 s26, v88
	global_load_lds_dwordx4 v[2:3], off
	v_lshl_add_u64 v[4:5], v[0:1], 0, s[4:5]
	s_mov_b32 m0, s26
	v_readfirstlane_b32 s26, v89
	global_load_lds_dwordx4 v[4:5], off
	v_lshl_add_u64 v[4:5], v[2:3], 0, s[4:5]
	s_mov_b32 m0, s26
	v_readfirstlane_b32 s26, v90
	global_load_lds_dwordx4 v[4:5], off
	v_lshl_add_u64 v[4:5], v[0:1], 0, s[6:7]
	s_mov_b32 m0, s26
	v_readfirstlane_b32 s26, v91
	global_load_lds_dwordx4 v[4:5], off
	v_lshl_add_u64 v[4:5], v[2:3], 0, s[6:7]
	s_mov_b32 m0, s26
	v_readfirstlane_b32 s26, v92
	global_load_lds_dwordx4 v[4:5], off
	v_lshl_add_u64 v[0:1], v[0:1], 0, s[8:9]
	s_mov_b32 m0, s26
	v_readfirstlane_b32 s26, v93
	global_load_lds_dwordx4 v[0:1], off
	v_lshl_add_u64 v[0:1], v[2:3], 0, s[8:9]
	s_mov_b32 m0, s26
	s_sub_i32 s26, s35, s38
	global_load_lds_dwordx4 v[0:1], off
	s_sub_i32 s26, s26, s36
	s_sext_i32_i16 s26, s26
	s_add_i32 s37, s37, s26
	v_mad_i64_i32 v[74:75], s[26:27], s37, v85, v[70:71]
	v_mad_i64_i32 v[76:77], s[26:27], s33, v85, v[72:73]
	s_mov_b64 s[26:27], 0
	s_mov_b32 s35, 0
	v_mov_b32_e32 v20, 0
	v_mov_b32_e32 v21, v65
	v_mov_b32_e32 v22, v65
	v_mov_b32_e32 v23, v65
	v_mov_b32_e32 v0, 0
	v_mov_b32_e32 v1, v65
	v_mov_b32_e32 v2, v65
	v_mov_b32_e32 v3, v65
	v_mov_b32_e32 v4, 0
	v_mov_b32_e32 v5, v65
	v_mov_b32_e32 v6, v65
	v_mov_b32_e32 v7, v65
	v_mov_b32_e32 v8, 0
	v_mov_b32_e32 v9, v65
	v_mov_b32_e32 v10, v65
	v_mov_b32_e32 v11, v65
	v_mov_b32_e32 v12, 0
	v_mov_b32_e32 v13, v65
	v_mov_b32_e32 v14, v65
	v_mov_b32_e32 v15, v65
	v_mov_b32_e32 v16, 0
	v_mov_b32_e32 v17, v65
	v_mov_b32_e32 v18, v65
	v_mov_b32_e32 v19, v65
	v_mov_b32_e32 v24, 0
	v_mov_b32_e32 v25, v65
	v_mov_b32_e32 v26, v65
	v_mov_b32_e32 v27, v65
	v_mov_b32_e32 v28, 0
	v_mov_b32_e32 v29, v65
	v_mov_b32_e32 v30, v65
	v_mov_b32_e32 v31, v65
	v_mov_b32_e32 v32, 0
	v_mov_b32_e32 v33, v65
	v_mov_b32_e32 v34, v65
	v_mov_b32_e32 v35, v65
	v_mov_b32_e32 v36, 0
	v_mov_b32_e32 v37, v65
	v_mov_b32_e32 v38, v65
	v_mov_b32_e32 v39, v65
	v_mov_b32_e32 v40, 0
	v_mov_b32_e32 v41, v65
	v_mov_b32_e32 v42, v65
	v_mov_b32_e32 v43, v65
	v_mov_b32_e32 v44, 0
	v_mov_b32_e32 v45, v65
	v_mov_b32_e32 v46, v65
	v_mov_b32_e32 v47, v65
	v_mov_b32_e32 v48, 0
	v_mov_b32_e32 v49, v65
	v_mov_b32_e32 v50, v65
	v_mov_b32_e32 v51, v65
	v_mov_b32_e32 v52, 0
	v_mov_b32_e32 v53, v65
	v_mov_b32_e32 v54, v65
	v_mov_b32_e32 v55, v65
	v_mov_b32_e32 v56, 0
	v_mov_b32_e32 v57, v65
	v_mov_b32_e32 v58, v65
	v_mov_b32_e32 v59, v65
	v_mov_b32_e32 v60, 0
	v_mov_b32_e32 v61, v65
	v_mov_b32_e32 v62, v65
	v_mov_b32_e32 v63, v65
	v_readfirstlane_b32 s96, v74
	v_readfirstlane_b32 s97, v75
	v_readfirstlane_b32 s88, v76
	v_readfirstlane_b32 s89, v77
	v_readfirstlane_b32 s87, v78
	s_nop 1
	v_subrev_u32_e32 v244, s96, v74
	v_subrev_u32_e32 v245, s88, v76
	v_add_u32_e32 v246, 0x11000, v244
	v_add_u32_e32 v247, 0x11000, v245
	v_add_u32_e32 v248, 0x22000, v244
	v_add_u32_e32 v249, 0x22000, v245
	v_add_u32_e32 v250, 0x33000, v244
	v_add_u32_e32 v251, 0x33000, v245
	s_add_u32 s96, s96, 0x2200080
	s_addc_u32 s97, s97, 0
	s_add_u32 s88, s88, 0x1090080
	s_addc_u32 s89, s89, 0
	s_add_u32 s86, s87, 0x8000
	s_mov_b32 m0, s86
	s_nop 0
	global_load_lds_dwordx4 v244, s[96:97]
	s_add_u32 m0, s86, 0x4000
	s_nop 0
	global_load_lds_dwordx4 v245, s[88:89]
	s_add_u32 m0, s86, 0x1000
	s_nop 0
	global_load_lds_dwordx4 v246, s[96:97]
	s_add_u32 m0, s86, 0x5000
	s_nop 0
	global_load_lds_dwordx4 v247, s[88:89]
	s_add_u32 m0, s86, 0x2000
	s_nop 0
	global_load_lds_dwordx4 v248, s[96:97]
	s_add_u32 m0, s86, 0x6000
	s_nop 0
	global_load_lds_dwordx4 v249, s[88:89]
	s_add_u32 m0, s86, 0x3000
	s_nop 0
	global_load_lds_dwordx4 v250, s[96:97]
	s_add_u32 m0, s86, 0x7000
	s_nop 0
	global_load_lds_dwordx4 v251, s[88:89]
	s_add_u32 s96, s96, 0x80
	s_addc_u32 s97, s97, 0
	s_add_u32 s88, s88, 0x80
	s_addc_u32 s89, s89, 0
.LBB0_1006:
	s_add_i32 s37, s35, 0x8000
	s_and_b32 s36, s37, 0x8000
	s_add_i32 s36, s36, 0
	s_and_b32 s35, s35, 0x8000
	s_add_i32 s35, s35, 0
	s_add_u32 s86, s35, s87
	s_waitcnt vmcnt(8)
	s_barrier
	v_add3_u32 v143, s35, v80, v81
	v_add3_u32 v145, s35, v81, v82
	v_add3_u32 v206, s35, v80, v83
	v_add3_u32 v207, s35, v82, v83
	ds_read_b128 v[102:105], v145
	ds_read_b128 v[94:97], v143 offset:16384
	ds_read_b128 v[98:101], v143 offset:18432
	ds_read_b128 v[106:109], v145 offset:2048
	ds_read_b128 v[110:113], v143 offset:20480
	ds_read_b128 v[114:117], v143 offset:22528
	ds_read_b128 v[118:121], v143 offset:24576
	ds_read_b128 v[122:125], v143 offset:26624
	ds_read_b128 v[126:129], v143 offset:28672
	ds_read_b128 v[130:133], v143 offset:30720
	ds_read_b128 v[174:177], v207
	ds_read_b128 v[166:169], v206 offset:16384
	ds_read_b128 v[170:173], v206 offset:18432
	ds_read_b128 v[178:181], v207 offset:2048
	ds_read_b128 v[182:185], v206 offset:20480
	ds_read_b128 v[186:189], v206 offset:22528
	ds_read_b128 v[190:193], v206 offset:24576
	ds_read_b128 v[194:197], v206 offset:26624
	ds_read_b128 v[198:201], v206 offset:28672
	ds_read_b128 v[202:205], v206 offset:30720
	s_waitcnt lgkmcnt(0)
	s_barrier
	s_cmpk_eq_i32 s26, 0x700
	s_cbranch_scc1 .Lgskip_1006
	s_mov_b32 m0, s86
	s_nop 0
	global_load_lds_dwordx4 v244, s[96:97]
	s_add_u32 m0, s86, 0x4000
	s_nop 0
	global_load_lds_dwordx4 v245, s[88:89]
	s_add_u32 m0, s86, 0x1000
	s_nop 0
	global_load_lds_dwordx4 v246, s[96:97]
	s_add_u32 m0, s86, 0x5000
	s_nop 0
	global_load_lds_dwordx4 v247, s[88:89]
	s_add_u32 m0, s86, 0x2000
	s_nop 0
	global_load_lds_dwordx4 v248, s[96:97]
	s_add_u32 m0, s86, 0x6000
	s_nop 0
	global_load_lds_dwordx4 v249, s[88:89]
	s_add_u32 m0, s86, 0x3000
	s_nop 0
	global_load_lds_dwordx4 v250, s[96:97]
	s_add_u32 m0, s86, 0x7000
	s_nop 0
	global_load_lds_dwordx4 v251, s[88:89]
	s_add_u32 s96, s96, 0x80
	s_addc_u32 s97, s97, 0
	s_add_u32 s88, s88, 0x80
	s_addc_u32 s89, s89, 0
.Lgskip_1006:
	s_add_u32 s26, s26, 0x80
	s_addc_u32 s27, s27, 0
	s_cmpk_eq_i32 s26, 0x780
	s_mov_b32 s35, s37
	v_mfma_f32_16x16x32_bf16 v[60:63], v[94:97], v[102:105], v[60:63]
	v_mfma_f32_16x16x32_bf16 v[56:59], v[98:101], v[102:105], v[56:59]
	v_mfma_f32_16x16x32_bf16 v[28:31], v[94:97], v[106:109], v[28:31]
	v_mfma_f32_16x16x32_bf16 v[24:27], v[98:101], v[106:109], v[24:27]
	v_mfma_f32_16x16x32_bf16 v[52:55], v[110:113], v[102:105], v[52:55]
	v_mfma_f32_16x16x32_bf16 v[16:19], v[110:113], v[106:109], v[16:19]
	v_mfma_f32_16x16x32_bf16 v[48:51], v[114:117], v[102:105], v[48:51]
	v_mfma_f32_16x16x32_bf16 v[12:15], v[114:117], v[106:109], v[12:15]
	v_mfma_f32_16x16x32_bf16 v[44:47], v[118:121], v[102:105], v[44:47]
	v_mfma_f32_16x16x32_bf16 v[8:11], v[118:121], v[106:109], v[8:11]
	v_mfma_f32_16x16x32_bf16 v[40:43], v[122:125], v[102:105], v[40:43]
	v_mfma_f32_16x16x32_bf16 v[4:7], v[122:125], v[106:109], v[4:7]
	v_mfma_f32_16x16x32_bf16 v[36:39], v[126:129], v[102:105], v[36:39]
	v_mfma_f32_16x16x32_bf16 v[0:3], v[126:129], v[106:109], v[0:3]
	v_mfma_f32_16x16x32_bf16 v[32:35], v[130:133], v[102:105], v[32:35]
	v_mfma_f32_16x16x32_bf16 v[20:23], v[130:133], v[106:109], v[20:23]
	v_mfma_f32_16x16x32_bf16 v[60:63], v[166:169], v[174:177], v[60:63]
	v_mfma_f32_16x16x32_bf16 v[56:59], v[170:173], v[174:177], v[56:59]
	v_mfma_f32_16x16x32_bf16 v[28:31], v[166:169], v[178:181], v[28:31]
	v_mfma_f32_16x16x32_bf16 v[24:27], v[170:173], v[178:181], v[24:27]
	v_mfma_f32_16x16x32_bf16 v[52:55], v[182:185], v[174:177], v[52:55]
	v_mfma_f32_16x16x32_bf16 v[16:19], v[182:185], v[178:181], v[16:19]
	v_mfma_f32_16x16x32_bf16 v[48:51], v[186:189], v[174:177], v[48:51]
	v_mfma_f32_16x16x32_bf16 v[12:15], v[186:189], v[178:181], v[12:15]
	v_mfma_f32_16x16x32_bf16 v[44:47], v[190:193], v[174:177], v[44:47]
	v_mfma_f32_16x16x32_bf16 v[8:11], v[190:193], v[178:181], v[8:11]
	v_mfma_f32_16x16x32_bf16 v[40:43], v[194:197], v[174:177], v[40:43]
	v_mfma_f32_16x16x32_bf16 v[4:7], v[194:197], v[178:181], v[4:7]
	v_mfma_f32_16x16x32_bf16 v[36:39], v[198:201], v[174:177], v[36:39]
	v_mfma_f32_16x16x32_bf16 v[0:3], v[198:201], v[178:181], v[0:3]
	v_mfma_f32_16x16x32_bf16 v[32:35], v[202:205], v[174:177], v[32:35]
	v_mfma_f32_16x16x32_bf16 v[20:23], v[202:205], v[178:181], v[20:23]
	s_cbranch_scc0 .LBB0_1006
	v_add_u32_e32 v138, s36, v80
	v_add_u32_e32 v126, v138, v81
	s_waitcnt vmcnt(0)
	s_barrier
	ds_read_b128 v[74:77], v126 offset:16384
	v_add3_u32 v102, s36, v81, v82
	ds_read_b128 v[94:97], v102
	ds_read_b128 v[98:101], v126 offset:18432
	ds_read_b128 v[102:105], v102 offset:2048
	ds_read_b128 v[106:109], v126 offset:20480
	ds_read_b128 v[110:113], v126 offset:22528
	ds_read_b128 v[114:117], v126 offset:24576
	ds_read_b128 v[118:121], v126 offset:26624
	v_add3_u32 v134, s36, v83, v82
	v_add_u32_e32 v142, v138, v83
	ds_read_b128 v[122:125], v126 offset:28672
	ds_read_b128 v[126:129], v126 offset:30720
	ds_read_b128 v[130:133], v134
	ds_read_b128 v[134:137], v134 offset:2048
	ds_read_b128 v[138:141], v142 offset:16384
	ds_read_b128 v[146:149], v142 offset:18432
	s_waitcnt lgkmcnt(11)
	v_mfma_f32_16x16x32_bf16 v[56:59], v[98:101], v[94:97], v[56:59]
	s_lshl_b32 s36, s34, 7
	s_lshl_b32 s26, s33, 7
	s_ashr_i32 s27, s26, 31
	v_mfma_f32_16x16x32_bf16 v[60:63], v[74:77], v[94:97], v[60:63]
	s_lshl_b64 s[26:27], s[26:27], 1
	s_add_i32 s31, s31, s28
	s_cmpk_gt_i32 s31, 0x107f
	s_waitcnt lgkmcnt(0)
	v_mfma_f32_16x16x32_bf16 v[56:59], v[146:149], v[130:133], v[56:59]
	v_mfma_f32_16x16x32_bf16 v[48:51], v[110:113], v[94:97], v[48:51]
	v_mfma_f32_16x16x32_bf16 v[52:55], v[106:109], v[94:97], v[52:55]
	s_nop 5
	v_max_f32_e32 v56, v56, v56
	v_max_f32_e32 v57, v57, v57
	v_max_f32_e32 v56, 0, v56
	v_mfma_f32_16x16x32_bf16 v[44:47], v[114:117], v[94:97], v[44:47]
	v_max_f32_e32 v57, 0, v57
	v_max_f32_e32 v59, v59, v59
	v_max_f32_e32 v59, 0, v59
	v_mfma_f32_16x16x32_bf16 v[40:43], v[118:121], v[94:97], v[40:43]
	v_mfma_f32_16x16x32_bf16 v[36:39], v[122:125], v[94:97], v[36:39]
	v_mfma_f32_16x16x32_bf16 v[32:35], v[126:129], v[94:97], v[32:35]
	ds_read_b128 v[94:97], v142 offset:20480
	ds_read_b128 v[150:153], v142 offset:22528
	ds_read_b128 v[154:157], v142 offset:24576
	ds_read_b128 v[158:161], v142 offset:26624
	v_mfma_f32_16x16x32_bf16 v[60:63], v[138:141], v[130:133], v[60:63]
	s_waitcnt lgkmcnt(2)
	v_mfma_f32_16x16x32_bf16 v[48:51], v[150:153], v[130:133], v[48:51]
	v_mfma_f32_16x16x32_bf16 v[16:19], v[106:109], v[102:105], v[16:19]
	v_mul_f32_e64 v106, v56, v56
	v_mul_f32_e64 v107, v57, v57
	v_max_f32_e32 v57, v58, v58
	s_nop 1
	v_max_f32_e32 v60, v60, v60
	v_mfma_f32_16x16x32_bf16 v[24:27], v[98:101], v[102:105], v[24:27]
	v_add_u32_e32 v100, s36, v79
	v_mov_b64_e32 v[98:99], s[0:1]
	v_max_f32_e32 v61, v61, v61
	v_max_f32_e32 v56, v62, v62
	v_max_f32_e32 v58, 0, v57
	v_max_f32_e32 v57, v63, v63
	v_mad_i64_i32 v[100:101], s[34:35], v100, s30, v[98:99]
	v_max_f32_e32 v60, 0, v60
	v_max_f32_e32 v61, 0, v61
	v_max_f32_e32 v56, 0, v56
	v_max_f32_e32 v57, 0, v57
	v_mfma_f32_16x16x32_bf16 v[52:55], v[94:97], v[130:133], v[52:55]
	v_lshl_add_u64 v[100:101], v[100:101], 0, s[26:27]
	v_pk_mul_f32 v[60:61], v[60:61], v[60:61]
	v_pk_mul_f32 v[62:63], v[56:57], v[56:57]
	v_mfma_f32_16x16x32_bf16 v[28:31], v[74:77], v[102:105], v[28:31]
	v_max_f32_e32 v48, v48, v48
	v_max_f32_e32 v49, v49, v49
	ds_read_b128 v[74:77], v142 offset:28672
	ds_read_b128 v[162:165], v142 offset:30720
	v_mfma_f32_16x16x32_bf16 v[12:15], v[110:113], v[102:105], v[12:15]
	v_lshl_add_u64 v[100:101], v[100:101], 0, v[64:65]
	v_cvt_pk_bf16_f32 v56, v60, v61
	v_cvt_pk_bf16_f32 v57, v62, v63
	v_mfma_f32_16x16x32_bf16 v[8:11], v[114:117], v[102:105], v[8:11]
	v_max_f32_e32 v48, 0, v48
	v_max_f32_e32 v49, 0, v49
	v_max_f32_e32 v52, v52, v52
	v_mfma_f32_16x16x32_bf16 v[4:7], v[118:121], v[102:105], v[4:7]
	v_max_f32_e32 v53, v53, v53
	v_max_f32_e32 v51, v51, v51
	v_max_f32_e32 v52, 0, v52
	v_mfma_f32_16x16x32_bf16 v[0:3], v[122:125], v[102:105], v[0:3]
	v_max_f32_e32 v53, 0, v53
	v_max_f32_e32 v51, 0, v51
	v_pk_mul_f32 v[52:53], v[52:53], v[52:53]
	v_mfma_f32_16x16x32_bf16 v[20:23], v[126:129], v[102:105], v[20:23]
	v_mul_f32_e64 v102, v58, v58
	v_mul_f32_e64 v103, v59, v59
	v_cvt_pk_bf16_f32 v58, v106, v107
	v_cvt_pk_bf16_f32 v59, v102, v103
	s_waitcnt lgkmcnt(2)
	v_mfma_f32_16x16x32_bf16 v[40:43], v[158:161], v[130:133], v[40:43]
	global_store_dwordx4 v[100:101], v[56:59], off
	s_nop 1
	v_pk_mul_f32 v[56:57], v[48:49], v[48:49]
	v_max_f32_e32 v49, v50, v50
	v_max_f32_e32 v48, v54, v54
	v_max_f32_e32 v50, 0, v49
	v_max_f32_e32 v49, v55, v55
	v_mfma_f32_16x16x32_bf16 v[44:47], v[154:157], v[130:133], v[44:47]
	v_max_f32_e32 v48, 0, v48
	v_max_f32_e32 v49, 0, v49
	v_pk_mul_f32 v[54:55], v[48:49], v[48:49]
	v_pk_mul_f32 v[58:59], v[50:51], v[50:51]
	v_max_f32_e32 v40, v40, v40
	v_max_f32_e32 v41, v41, v41
	s_waitcnt lgkmcnt(0)
	v_mfma_f32_16x16x32_bf16 v[32:35], v[162:165], v[130:133], v[32:35]
	v_cvt_pk_bf16_f32 v48, v52, v53
	v_cvt_pk_bf16_f32 v49, v54, v55
	v_cvt_pk_bf16_f32 v50, v56, v57
	v_cvt_pk_bf16_f32 v51, v58, v59
	v_max_f32_e32 v40, 0, v40
	v_max_f32_e32 v41, 0, v41
	global_store_dwordx4 v[100:101], v[48:51], off offset:64
	v_max_f32_e32 v44, v44, v44
	v_max_f32_e32 v45, v45, v45
	v_pk_mul_f32 v[48:49], v[40:41], v[40:41]
	v_max_f32_e32 v41, v42, v42
	v_max_f32_e32 v40, v46, v46
	v_max_f32_e32 v42, 0, v41
	v_max_f32_e32 v41, v47, v47
	v_max_f32_e32 v43, v43, v43
	v_mfma_f32_16x16x32_bf16 v[36:39], v[74:77], v[130:133], v[36:39]
	v_max_f32_e32 v44, 0, v44
	v_max_f32_e32 v45, 0, v45
	v_max_f32_e32 v40, 0, v40
	v_max_f32_e32 v41, 0, v41
	v_max_f32_e32 v43, 0, v43
	v_pk_mul_f32 v[44:45], v[44:45], v[44:45]
	v_pk_mul_f32 v[46:47], v[40:41], v[40:41]
	v_pk_mul_f32 v[50:51], v[42:43], v[42:43]
	v_max_f32_e32 v32, v32, v32
	v_max_f32_e32 v33, v33, v33
	v_mfma_f32_16x16x32_bf16 v[24:27], v[146:149], v[134:137], v[24:27]
	v_cvt_pk_bf16_f32 v40, v44, v45
	v_cvt_pk_bf16_f32 v41, v46, v47
	v_cvt_pk_bf16_f32 v42, v48, v49
	v_cvt_pk_bf16_f32 v43, v50, v51
	v_max_f32_e32 v32, 0, v32
	v_max_f32_e32 v33, 0, v33
	global_store_dwordx4 v[100:101], v[40:43], off offset:128
	v_max_f32_e32 v36, v36, v36
	v_max_f32_e32 v37, v37, v37
	v_pk_mul_f32 v[40:41], v[32:33], v[32:33]
	v_max_f32_e32 v33, v34, v34
	v_max_f32_e32 v32, v38, v38
	v_max_f32_e32 v34, 0, v33
	v_max_f32_e32 v33, v39, v39
	v_max_f32_e32 v35, v35, v35
	v_mfma_f32_16x16x32_bf16 v[28:31], v[138:141], v[134:137], v[28:31]
	v_max_f32_e32 v36, 0, v36
	v_max_f32_e32 v37, 0, v37
	v_max_f32_e32 v32, 0, v32
	v_max_f32_e32 v33, 0, v33
	v_max_f32_e32 v35, 0, v35
	v_pk_mul_f32 v[36:37], v[36:37], v[36:37]
	v_pk_mul_f32 v[38:39], v[32:33], v[32:33]
	v_pk_mul_f32 v[42:43], v[34:35], v[34:35]
	v_max_f32_e32 v24, v24, v24
	v_max_f32_e32 v25, v25, v25
	v_mfma_f32_16x16x32_bf16 v[12:15], v[150:153], v[134:137], v[12:15]
	v_cvt_pk_bf16_f32 v32, v36, v37
	v_cvt_pk_bf16_f32 v33, v38, v39
	v_cvt_pk_bf16_f32 v34, v40, v41
	v_cvt_pk_bf16_f32 v35, v42, v43
	v_max_f32_e32 v24, 0, v24
	v_max_f32_e32 v25, 0, v25
	global_store_dwordx4 v[100:101], v[32:35], off offset:192
	v_max_f32_e32 v28, v28, v28
	v_max_f32_e32 v29, v29, v29
	v_pk_mul_f32 v[34:35], v[24:25], v[24:25]
	v_max_f32_e32 v25, v26, v26
	v_add_u32_e32 v32, s36, v84
	v_max_f32_e32 v24, v30, v30
	v_max_f32_e32 v26, 0, v25
	v_max_f32_e32 v25, v31, v31
	v_max_f32_e32 v27, v27, v27
	v_mfma_f32_16x16x32_bf16 v[16:19], v[94:97], v[134:137], v[16:19]
	v_mad_i64_i32 v[32:33], s[34:35], v32, s30, v[98:99]
	v_max_f32_e32 v28, 0, v28
	v_max_f32_e32 v29, 0, v29
	v_max_f32_e32 v24, 0, v24
	v_max_f32_e32 v25, 0, v25
	v_max_f32_e32 v27, 0, v27
	v_lshl_add_u64 v[32:33], v[32:33], 0, s[26:27]
	v_pk_mul_f32 v[28:29], v[28:29], v[28:29]
	v_pk_mul_f32 v[30:31], v[24:25], v[24:25]
	v_pk_mul_f32 v[36:37], v[26:27], v[26:27]
	v_max_f32_e32 v12, v12, v12
	v_max_f32_e32 v13, v13, v13
	v_mfma_f32_16x16x32_bf16 v[4:7], v[158:161], v[134:137], v[4:7]
	v_lshl_add_u64 v[32:33], v[32:33], 0, v[64:65]
	v_cvt_pk_bf16_f32 v24, v28, v29
	v_cvt_pk_bf16_f32 v25, v30, v31
	v_cvt_pk_bf16_f32 v26, v34, v35
	v_cvt_pk_bf16_f32 v27, v36, v37
	v_max_f32_e32 v12, 0, v12
	v_max_f32_e32 v13, 0, v13
	global_store_dwordx4 v[32:33], v[24:27], off
	v_max_f32_e32 v16, v16, v16
	v_max_f32_e32 v17, v17, v17
	v_pk_mul_f32 v[24:25], v[12:13], v[12:13]
	v_max_f32_e32 v13, v14, v14
	v_max_f32_e32 v12, v18, v18
	v_max_f32_e32 v14, 0, v13
	v_max_f32_e32 v13, v19, v19
	v_max_f32_e32 v15, v15, v15
	v_mfma_f32_16x16x32_bf16 v[8:11], v[154:157], v[134:137], v[8:11]
	v_max_f32_e32 v16, 0, v16
	v_max_f32_e32 v17, 0, v17
	v_max_f32_e32 v12, 0, v12
	v_max_f32_e32 v13, 0, v13
	v_max_f32_e32 v15, 0, v15
	v_pk_mul_f32 v[16:17], v[16:17], v[16:17]
	v_pk_mul_f32 v[18:19], v[12:13], v[12:13]
	v_pk_mul_f32 v[26:27], v[14:15], v[14:15]
	v_max_f32_e32 v4, v4, v4
	v_max_f32_e32 v5, v5, v5
	v_cvt_pk_bf16_f32 v12, v16, v17
	v_cvt_pk_bf16_f32 v13, v18, v19
	v_cvt_pk_bf16_f32 v14, v24, v25
	v_cvt_pk_bf16_f32 v15, v26, v27
	v_max_f32_e32 v4, 0, v4
	v_max_f32_e32 v5, 0, v5
	global_store_dwordx4 v[32:33], v[12:15], off offset:64
	v_mfma_f32_16x16x32_bf16 v[0:3], v[74:77], v[134:137], v[0:3]
	v_max_f32_e32 v8, v8, v8
	v_pk_mul_f32 v[12:13], v[4:5], v[4:5]
	v_max_f32_e32 v5, v6, v6
	v_mfma_f32_16x16x32_bf16 v[20:23], v[162:165], v[134:137], v[20:23]
	v_max_f32_e32 v9, v9, v9
	v_max_f32_e32 v4, v10, v10
	v_max_f32_e32 v6, 0, v5
	v_max_f32_e32 v5, v11, v11
	v_max_f32_e32 v7, v7, v7
	v_max_f32_e32 v8, 0, v8
	v_max_f32_e32 v9, 0, v9
	v_max_f32_e32 v4, 0, v4
	v_max_f32_e32 v5, 0, v5
	v_max_f32_e32 v7, 0, v7
	v_pk_mul_f32 v[8:9], v[8:9], v[8:9]
	v_pk_mul_f32 v[10:11], v[4:5], v[4:5]
	v_pk_mul_f32 v[14:15], v[6:7], v[6:7]
	v_cvt_pk_bf16_f32 v4, v8, v9
	v_cvt_pk_bf16_f32 v5, v10, v11
	v_cvt_pk_bf16_f32 v6, v12, v13
	v_cvt_pk_bf16_f32 v7, v14, v15
	global_store_dwordx4 v[32:33], v[4:7], off offset:128
	v_max_f32_e32 v0, v0, v0
	v_max_f32_e32 v1, v1, v1
	v_max_f32_e32 v4, v20, v20
	v_max_f32_e32 v5, v21, v21
	v_max_f32_e32 v2, v2, v2
	v_max_f32_e32 v6, v22, v22
	v_max_f32_e32 v3, v3, v3
	v_max_f32_e32 v7, v23, v23
	v_max_f32_e32 v0, 0, v0
	v_max_f32_e32 v4, 0, v4
	v_max_f32_e32 v1, 0, v1
	v_max_f32_e32 v5, 0, v5
	v_max_f32_e32 v2, 0, v2
	v_max_f32_e32 v6, 0, v6
	v_max_f32_e32 v3, 0, v3
	v_max_f32_e32 v7, 0, v7
	v_pk_mul_f32 v[0:1], v[0:1], v[0:1]
	v_pk_mul_f32 v[4:5], v[4:5], v[4:5]
	v_pk_mul_f32 v[2:3], v[2:3], v[2:3]
	v_pk_mul_f32 v[6:7], v[6:7], v[6:7]
	v_cvt_pk_bf16_f32 v0, v0, v1
	v_cvt_pk_bf16_f32 v1, v2, v3
	v_cvt_pk_bf16_f32 v2, v4, v5
	v_cvt_pk_bf16_f32 v3, v6, v7
	global_store_dwordx4 v[32:33], v[0:3], off offset:192
	s_cbranch_scc0 .LBB0_1005

.LBB0_1070:
	s_ashr_i32 s34, s41, 3
	s_add_i32 s34, s43, s34
	s_ashr_i32 s35, s34, 31
	s_lshr_b32 s35, s35, 26
	s_add_i32 s35, s34, s35
	s_ashr_i32 s42, s35, 6
	s_and_b32 s35, s35, 0xffc0
	s_sub_i32 s34, s34, s35
	s_bfe_i32 s35, s34, 0x80000
	s_bfe_u32 s35, s35, 0x3000c
	s_add_i32 s35, s34, s35
	s_bfe_i32 s41, s35, 0x80000
	s_and_b32 s35, s35, 0xf8
	s_sub_i32 s34, s34, s35
	s_lshl_b32 s42, s42, 3
	s_sext_i32_i8 s34, s34
	s_add_i32 s34, s42, s34
	s_ashr_i32 s35, s34, 31
	s_lshr_b32 s35, s35, 26
	s_add_i32 s35, s34, s35
	s_sext_i32_i16 s41, s41
	s_ashr_i32 s42, s35, 6
	s_andn2_b32 s35, s35, 63
	s_ashr_i32 s41, s41, 3
	s_mulk_i32 s42, 0x42
	s_sub_i32 s34, s34, s35
	s_add_i32 s42, s34, s42
	s_mul_i32 s34, s41, 0x82000
	s_add_i32 s42, s42, 2
	s_ashr_i32 s35, s34, 31
	v_readfirstlane_b32 s43, v94
	v_mad_i64_i32 v[0:1], s[44:45], s42, v93, v[64:65]
	s_lshl_b64 s[34:35], s[34:35], 1
	s_mov_b32 m0, s43
	v_readfirstlane_b32 s43, v95
	v_lshl_add_u64 v[2:3], v[66:67], 0, s[34:35]
	s_waitcnt vmcnt(63) expcnt(7) lgkmcnt(15)
	s_barrier
	global_load_lds_dwordx4 v[0:1], off
	s_mov_b32 m0, s43
	v_readfirstlane_b32 s43, v96
	global_load_lds_dwordx4 v[2:3], off
	v_lshl_add_u64 v[4:5], v[0:1], 0, s[8:9]
	s_mov_b32 m0, s43
	v_readfirstlane_b32 s43, v97
	global_load_lds_dwordx4 v[4:5], off
	v_lshl_add_u64 v[4:5], v[2:3], 0, s[8:9]
	s_mov_b32 m0, s43
	v_readfirstlane_b32 s43, v98
	global_load_lds_dwordx4 v[4:5], off
	v_lshl_add_u64 v[4:5], v[0:1], 0, s[10:11]
	s_mov_b32 m0, s43
	v_readfirstlane_b32 s43, v99
	global_load_lds_dwordx4 v[4:5], off
	v_lshl_add_u64 v[4:5], v[2:3], 0, s[10:11]
	s_mov_b32 m0, s43
	v_readfirstlane_b32 s43, v100
	global_load_lds_dwordx4 v[4:5], off
	v_lshl_add_u64 v[0:1], v[0:1], 0, s[12:13]
	s_mov_b32 m0, s43
	v_readfirstlane_b32 s43, v101
	global_load_lds_dwordx4 v[0:1], off
	v_lshl_add_u64 v[0:1], v[2:3], 0, s[12:13]
	s_mov_b32 m0, s43
	v_mov_b32_e32 v36, 0
	global_load_lds_dwordx4 v[0:1], off
	v_mad_i64_i32 v[72:73], s[44:45], s42, v93, v[68:69]
	v_lshl_add_u64 v[74:75], v[70:71], 0, s[34:35]
	s_mov_b64 s[34:35], 0
	s_mov_b32 s43, 0
	v_mov_b32_e32 v37, v36
	v_mov_b32_e32 v38, v36
	v_mov_b32_e32 v39, v36
	v_mov_b32_e32 v0, v36
	v_mov_b32_e32 v1, v36
	v_mov_b32_e32 v2, v36
	v_mov_b32_e32 v3, v36
	v_mov_b32_e32 v4, v36
	v_mov_b32_e32 v5, v36
	v_mov_b32_e32 v6, v36
	v_mov_b32_e32 v7, v36
	v_mov_b32_e32 v8, v36
	v_mov_b32_e32 v9, v36
	v_mov_b32_e32 v10, v36
	v_mov_b32_e32 v11, v36
	v_mov_b32_e32 v12, v36
	v_mov_b32_e32 v13, v36
	v_mov_b32_e32 v14, v36
	v_mov_b32_e32 v15, v36
	v_mov_b32_e32 v16, v36
	v_mov_b32_e32 v17, v36
	v_mov_b32_e32 v18, v36
	v_mov_b32_e32 v19, v36
	v_mov_b32_e32 v20, v36
	v_mov_b32_e32 v21, v36
	v_mov_b32_e32 v22, v36
	v_mov_b32_e32 v23, v36
	v_mov_b32_e32 v24, v36
	v_mov_b32_e32 v25, v36
	v_mov_b32_e32 v26, v36
	v_mov_b32_e32 v27, v36
	v_mov_b32_e32 v28, v36
	v_mov_b32_e32 v29, v36
	v_mov_b32_e32 v30, v36
	v_mov_b32_e32 v31, v36
	v_mov_b32_e32 v32, v36
	v_mov_b32_e32 v33, v36
	v_mov_b32_e32 v34, v36
	v_mov_b32_e32 v35, v36
	v_mov_b32_e32 v40, v36
	v_mov_b32_e32 v41, v36
	v_mov_b32_e32 v42, v36
	v_mov_b32_e32 v43, v36
	v_mov_b32_e32 v44, v36
	v_mov_b32_e32 v45, v36
	v_mov_b32_e32 v46, v36
	v_mov_b32_e32 v47, v36
	v_mov_b32_e32 v48, v36
	v_mov_b32_e32 v49, v36
	v_mov_b32_e32 v50, v36
	v_mov_b32_e32 v51, v36
	v_mov_b32_e32 v52, v36
	v_mov_b32_e32 v53, v36
	v_mov_b32_e32 v54, v36
	v_mov_b32_e32 v55, v36
	v_mov_b32_e32 v56, v36
	v_mov_b32_e32 v57, v36
	v_mov_b32_e32 v58, v36
	v_mov_b32_e32 v59, v36
	v_mov_b32_e32 v60, v36
	v_mov_b32_e32 v61, v36
	v_mov_b32_e32 v62, v36
	v_mov_b32_e32 v63, v36
	v_readfirstlane_b32 s96, v72
	v_readfirstlane_b32 s97, v73
	v_readfirstlane_b32 s88, v74
	v_readfirstlane_b32 s89, v75
	v_readfirstlane_b32 s87, v88
	s_nop 1
	v_subrev_u32_e32 v244, s96, v72
	v_subrev_u32_e32 v245, s88, v74
	v_add_u32_e32 v246, 0x41000, v244
	v_add_u32_e32 v247, 0x41000, v245
	v_add_u32_e32 v248, 0x82000, v244
	v_add_u32_e32 v249, 0x82000, v245
	v_add_u32_e32 v250, 0xc3000, v244
	v_add_u32_e32 v251, 0xc3000, v245
	s_add_u32 s96, s96, 0x4510080
	s_addc_u32 s97, s97, 0
	s_add_u32 s88, s88, 0x1910080
	s_addc_u32 s89, s89, 0
	s_add_u32 s86, s87, 0x8000
	s_mov_b32 m0, s86
	s_nop 0
	global_load_lds_dwordx4 v244, s[96:97]
	s_add_u32 m0, s86, 0x4000
	s_nop 0
	global_load_lds_dwordx4 v245, s[88:89]
	s_add_u32 m0, s86, 0x1000
	s_nop 0
	global_load_lds_dwordx4 v246, s[96:97]
	s_add_u32 m0, s86, 0x5000
	s_nop 0
	global_load_lds_dwordx4 v247, s[88:89]
	s_add_u32 m0, s86, 0x2000
	s_nop 0
	global_load_lds_dwordx4 v248, s[96:97]
	s_add_u32 m0, s86, 0x6000
	s_nop 0
	global_load_lds_dwordx4 v249, s[88:89]
	s_add_u32 m0, s86, 0x3000
	s_nop 0
	global_load_lds_dwordx4 v250, s[96:97]
	s_add_u32 m0, s86, 0x7000
	s_nop 0
	global_load_lds_dwordx4 v251, s[88:89]
	s_add_u32 s96, s96, 0x80
	s_addc_u32 s97, s97, 0
	s_add_u32 s88, s88, 0x80
	s_addc_u32 s89, s89, 0
.LBB0_1071:
	s_add_i32 s45, s43, 0x8000
	s_and_b32 s44, s45, 0x8000
	s_add_i32 s44, s44, 0
	s_and_b32 s43, s43, 0x8000
	s_add_i32 s43, s43, 0
	s_add_u32 s86, s43, s87
	s_waitcnt vmcnt(8)
	s_barrier
	v_add3_u32 v169, s43, v84, v89
	v_add3_u32 v210, s43, v89, v90
	v_add3_u32 v211, s43, v84, v91
	v_add3_u32 v212, s43, v90, v91
	ds_read_b128 v[106:109], v210
	ds_read_b128 v[76:79], v169 offset:16384
	ds_read_b128 v[102:105], v169 offset:18432
	ds_read_b128 v[110:113], v210 offset:2048
	ds_read_b128 v[114:117], v169 offset:20480
	ds_read_b128 v[118:121], v169 offset:22528
	ds_read_b128 v[122:125], v169 offset:24576
	ds_read_b128 v[126:129], v169 offset:26624
	ds_read_b128 v[130:133], v169 offset:28672
	ds_read_b128 v[134:137], v169 offset:30720
	ds_read_b128 v[178:181], v212
	ds_read_b128 v[170:173], v211 offset:16384
	ds_read_b128 v[174:177], v211 offset:18432
	ds_read_b128 v[182:185], v212 offset:2048
	ds_read_b128 v[186:189], v211 offset:20480
	ds_read_b128 v[190:193], v211 offset:22528
	ds_read_b128 v[194:197], v211 offset:24576
	ds_read_b128 v[198:201], v211 offset:26624
	ds_read_b128 v[202:205], v211 offset:28672
	ds_read_b128 v[206:209], v211 offset:30720
	s_waitcnt lgkmcnt(0)
	s_barrier
	s_cmpk_eq_i32 s34, 0x1f00
	s_cbranch_scc1 .Lgskip_1071
	s_mov_b32 m0, s86
	s_nop 0
	global_load_lds_dwordx4 v244, s[96:97]
	s_add_u32 m0, s86, 0x4000
	s_nop 0
	global_load_lds_dwordx4 v245, s[88:89]
	s_add_u32 m0, s86, 0x1000
	s_nop 0
	global_load_lds_dwordx4 v246, s[96:97]
	s_add_u32 m0, s86, 0x5000
	s_nop 0
	global_load_lds_dwordx4 v247, s[88:89]
	s_add_u32 m0, s86, 0x2000
	s_nop 0
	global_load_lds_dwordx4 v248, s[96:97]
	s_add_u32 m0, s86, 0x6000
	s_nop 0
	global_load_lds_dwordx4 v249, s[88:89]
	s_add_u32 m0, s86, 0x3000
	s_nop 0
	global_load_lds_dwordx4 v250, s[96:97]
	s_add_u32 m0, s86, 0x7000
	s_nop 0
	global_load_lds_dwordx4 v251, s[88:89]
	s_add_u32 s96, s96, 0x80
	s_addc_u32 s97, s97, 0
	s_add_u32 s88, s88, 0x80
	s_addc_u32 s89, s89, 0
.Lgskip_1071:
	s_add_u32 s34, s34, 0x80
	s_addc_u32 s35, s35, 0
	s_cmpk_eq_i32 s34, 0x1f80
	s_mov_b32 s43, s45
	v_mfma_f32_16x16x32_bf16 v[60:63], v[76:79], v[106:109], v[60:63]
	v_mfma_f32_16x16x32_bf16 v[56:59], v[102:105], v[106:109], v[56:59]
	v_mfma_f32_16x16x32_bf16 v[24:27], v[76:79], v[110:113], v[24:27]
	v_mfma_f32_16x16x32_bf16 v[20:23], v[102:105], v[110:113], v[20:23]
	v_mfma_f32_16x16x32_bf16 v[52:55], v[114:117], v[106:109], v[52:55]
	v_mfma_f32_16x16x32_bf16 v[16:19], v[114:117], v[110:113], v[16:19]
	v_mfma_f32_16x16x32_bf16 v[48:51], v[118:121], v[106:109], v[48:51]
	v_mfma_f32_16x16x32_bf16 v[12:15], v[118:121], v[110:113], v[12:15]
	v_mfma_f32_16x16x32_bf16 v[44:47], v[122:125], v[106:109], v[44:47]
	v_mfma_f32_16x16x32_bf16 v[8:11], v[122:125], v[110:113], v[8:11]
	v_mfma_f32_16x16x32_bf16 v[40:43], v[126:129], v[106:109], v[40:43]
	v_mfma_f32_16x16x32_bf16 v[4:7], v[126:129], v[110:113], v[4:7]
	v_mfma_f32_16x16x32_bf16 v[32:35], v[130:133], v[106:109], v[32:35]
	v_mfma_f32_16x16x32_bf16 v[0:3], v[130:133], v[110:113], v[0:3]
	v_mfma_f32_16x16x32_bf16 v[28:31], v[134:137], v[106:109], v[28:31]
	v_mfma_f32_16x16x32_bf16 v[36:39], v[134:137], v[110:113], v[36:39]
	v_mfma_f32_16x16x32_bf16 v[60:63], v[170:173], v[178:181], v[60:63]
	v_mfma_f32_16x16x32_bf16 v[56:59], v[174:177], v[178:181], v[56:59]
	v_mfma_f32_16x16x32_bf16 v[24:27], v[170:173], v[182:185], v[24:27]
	v_mfma_f32_16x16x32_bf16 v[20:23], v[174:177], v[182:185], v[20:23]
	v_mfma_f32_16x16x32_bf16 v[52:55], v[186:189], v[178:181], v[52:55]
	v_mfma_f32_16x16x32_bf16 v[16:19], v[186:189], v[182:185], v[16:19]
	v_mfma_f32_16x16x32_bf16 v[48:51], v[190:193], v[178:181], v[48:51]
	v_mfma_f32_16x16x32_bf16 v[12:15], v[190:193], v[182:185], v[12:15]
	v_mfma_f32_16x16x32_bf16 v[44:47], v[194:197], v[178:181], v[44:47]
	v_mfma_f32_16x16x32_bf16 v[8:11], v[194:197], v[182:185], v[8:11]
	v_mfma_f32_16x16x32_bf16 v[40:43], v[198:201], v[178:181], v[40:43]
	v_mfma_f32_16x16x32_bf16 v[4:7], v[198:201], v[182:185], v[4:7]
	v_mfma_f32_16x16x32_bf16 v[32:35], v[202:205], v[178:181], v[32:35]
	v_mfma_f32_16x16x32_bf16 v[0:3], v[202:205], v[182:185], v[0:3]
	v_mfma_f32_16x16x32_bf16 v[28:31], v[206:209], v[178:181], v[28:31]
	v_mfma_f32_16x16x32_bf16 v[36:39], v[206:209], v[182:185], v[36:39]
	s_cbranch_scc0 .LBB0_1071
	v_add_u32_e32 v80, s44, v84
	v_add_u32_e32 v81, v80, v89
	v_add3_u32 v106, s44, v89, v90
	s_waitcnt vmcnt(0)
	s_barrier
	ds_read_b128 v[72:75], v81 offset:16384
	ds_read_b128 v[76:79], v81 offset:18432
	ds_read_b128 v[102:105], v106
	ds_read_b128 v[106:109], v106 offset:2048
	ds_read_b128 v[110:113], v81 offset:20480
	ds_read_b128 v[114:117], v81 offset:22528
	ds_read_b128 v[118:121], v81 offset:24576
	ds_read_b128 v[122:125], v81 offset:26624
	ds_read_b128 v[126:129], v81 offset:28672
	ds_read_b128 v[130:133], v81 offset:30720
	v_add_u32_e32 v80, v80, v91
	s_waitcnt lgkmcnt(7)
	v_mfma_f32_16x16x32_bf16 v[60:63], v[72:75], v[102:105], v[60:63]
	s_lshl_b32 s42, s42, 7
	v_mfma_f32_16x16x32_bf16 v[56:59], v[76:79], v[102:105], v[56:59]
	s_waitcnt lgkmcnt(4)
	v_mfma_f32_16x16x32_bf16 v[48:51], v[114:117], v[102:105], v[48:51]
	s_waitcnt lgkmcnt(3)
	v_mfma_f32_16x16x32_bf16 v[44:47], v[118:121], v[102:105], v[44:47]
	s_waitcnt lgkmcnt(2)
	v_mfma_f32_16x16x32_bf16 v[40:43], v[122:125], v[102:105], v[40:43]
	s_waitcnt lgkmcnt(1)
	v_mfma_f32_16x16x32_bf16 v[32:35], v[126:129], v[102:105], v[32:35]
	s_waitcnt lgkmcnt(0)
	v_mfma_f32_16x16x32_bf16 v[28:31], v[130:133], v[102:105], v[28:31]
	v_mfma_f32_16x16x32_bf16 v[24:27], v[72:75], v[106:109], v[24:27]
	ds_read_b128 v[72:75], v80 offset:16384
	v_mfma_f32_16x16x32_bf16 v[52:55], v[110:113], v[102:105], v[52:55]
	v_mfma_f32_16x16x32_bf16 v[20:23], v[76:79], v[106:109], v[20:23]
	v_mfma_f32_16x16x32_bf16 v[16:19], v[110:113], v[106:109], v[16:19]
	v_mfma_f32_16x16x32_bf16 v[12:15], v[114:117], v[106:109], v[12:15]
	v_mfma_f32_16x16x32_bf16 v[8:11], v[118:121], v[106:109], v[8:11]
	v_mfma_f32_16x16x32_bf16 v[4:7], v[122:125], v[106:109], v[4:7]
	v_mfma_f32_16x16x32_bf16 v[0:3], v[126:129], v[106:109], v[0:3]
	v_mfma_f32_16x16x32_bf16 v[102:105], v[130:133], v[106:109], v[36:39]
	s_nop 2
	v_add3_u32 v36, s44, v91, v90
	ds_read_b128 v[76:79], v80 offset:18432
	ds_read_b128 v[106:109], v36
	ds_read_b128 v[110:113], v36 offset:2048
	ds_read_b128 v[130:133], v80 offset:28672
	ds_read_b128 v[134:137], v80 offset:30720
	ds_read_b128 v[114:117], v80 offset:20480
	ds_read_b128 v[118:121], v80 offset:22528
	ds_read_b128 v[122:125], v80 offset:24576
	ds_read_b128 v[126:129], v80 offset:26624
	s_waitcnt lgkmcnt(7)
	v_mfma_f32_16x16x32_bf16 v[60:63], v[72:75], v[106:109], v[60:63]
	s_waitcnt lgkmcnt(5)
	v_mfma_f32_16x16x32_bf16 v[36:39], v[130:133], v[106:109], v[32:35]
	s_waitcnt lgkmcnt(4)
	v_mfma_f32_16x16x32_bf16 v[32:35], v[134:137], v[106:109], v[28:31]
	v_mfma_f32_16x16x32_bf16 v[28:31], v[72:75], v[110:113], v[24:27]
	v_add_u32_e32 v72, s42, v85
	v_mul_hi_i32 v73, v72, s36
	v_mfma_f32_16x16x32_bf16 v[24:27], v[76:79], v[110:113], v[20:23]
	s_waitcnt lgkmcnt(3)
	v_mfma_f32_16x16x32_bf16 v[20:23], v[114:117], v[110:113], v[16:19]
	s_waitcnt lgkmcnt(2)
	v_mfma_f32_16x16x32_bf16 v[16:19], v[118:121], v[110:113], v[12:15]
	s_waitcnt lgkmcnt(1)
	v_mfma_f32_16x16x32_bf16 v[12:15], v[122:125], v[110:113], v[8:11]
	s_waitcnt lgkmcnt(0)
	v_mfma_f32_16x16x32_bf16 v[8:11], v[126:129], v[110:113], v[4:7]
	s_nop 2
	v_lshrrev_b32_e32 v4, 31, v73
	v_ashrrev_i32_e32 v5, 11, v73
	v_mfma_f32_16x16x32_bf16 v[56:59], v[76:79], v[106:109], v[56:59]
	v_add_u32_e32 v73, v5, v4
	v_mad_i32_i24 v78, v73, s37, v72
	v_lshlrev_b32_e32 v75, 13, v73
	v_mfma_f32_16x16x32_bf16 v[52:55], v[114:117], v[106:109], v[52:55]
	v_cmp_lt_i32_e32 vcc, s38, v78
	v_add3_u32 v74, v75, v78, s39
	v_mfma_f32_16x16x32_bf16 v[48:51], v[118:121], v[106:109], v[48:51]
	v_mfma_f32_16x16x32_bf16 v[44:47], v[122:125], v[106:109], v[44:47]
	v_mfma_f32_16x16x32_bf16 v[40:43], v[126:129], v[106:109], v[40:43]
	v_mfma_f32_16x16x32_bf16 v[4:7], v[130:133], v[110:113], v[0:3]
	v_mfma_f32_16x16x32_bf16 v[0:3], v[134:137], v[110:113], v[102:105]
	s_and_saveexec_b64 s[34:35], vcc
	s_xor_b64 s[34:35], exec, s[34:35]
	v_add3_u32 v72, v75, v78, s39
	s_or_saveexec_b64 s[34:35], s[34:35]
	v_mov_b64_e32 v[76:77], s[92:93]
	v_lshl_add_u32 v75, v73, 8, v78
	s_xor_b64 exec, exec, s[34:35]
	v_lshl_add_u32 v72, v73, 8, v78
	v_mov_b64_e32 v[76:77], s[6:7]
	s_or_b64 exec, exec, s[34:35]
	s_and_saveexec_b64 s[34:35], vcc
	s_xor_b64 s[34:35], exec, s[34:35]
	s_cbranch_execz .LBB0_1078
	v_mul_hi_i32_i24_e32 v79, 0x6000, v73
	v_mul_i32_i24_e32 v78, 0x6000, v73
	s_or_saveexec_b64 s[34:35], s[34:35]
	v_mov_b64_e32 v[80:81], s[92:93]
	s_xor_b64 exec, exec, s[34:35]
	s_cbranch_execnz .LBB0_1079
	s_branch .LBB0_1080

.LBB0_1090:
	s_ashr_i32 s37, s43, 6
	s_and_b32 s8, s42, 3
	s_bfe_u32 s45, s43, 0x30002
	s_mulk_i32 s37, 0x42
	s_bfe_u32 s46, s43, 0x10005
	s_lshl_b32 s36, s8, 11
	s_mul_i32 s47, s45, 0x104000
	s_or_b32 s46, s37, s46
	s_or_b32 s8, s47, s36
	s_and_b32 s44, s43, 3
	s_mul_i32 s52, s46, 0x104000
	s_mul_hi_i32 s37, s46, 0x104000
	s_add_u32 s48, s2, s52
	s_addc_u32 s49, s3, s37
	s_lshl_b32 s50, s44, 11
	s_add_u32 s48, s48, s50
	s_addc_u32 s49, s49, 0
	s_add_u32 s47, s4, s47
	s_addc_u32 s51, s5, 0
	s_add_u32 s50, s47, s50
	s_addc_u32 s51, s51, 0
	v_lshl_add_u64 v[0:1], s[48:49], 0, v[78:79]
	v_readfirstlane_b32 s47, v91
	v_lshl_add_u64 v[0:1], v[0:1], 0, v[80:81]
	v_lshl_add_u64 v[2:3], s[50:51], 0, v[82:83]
	s_mov_b32 m0, s47
	v_readfirstlane_b32 s47, v92
	v_lshl_add_u64 v[2:3], v[2:3], 0, v[80:81]
	s_waitcnt vmcnt(63) expcnt(7) lgkmcnt(15)
	s_barrier
	global_load_lds_dwordx4 v[0:1], off
	s_mov_b32 m0, s47
	v_readfirstlane_b32 s47, v93
	global_load_lds_dwordx4 v[2:3], off
	v_lshl_add_u64 v[4:5], v[0:1], 0, s[10:11]
	s_mov_b32 m0, s47
	v_readfirstlane_b32 s47, v94
	global_load_lds_dwordx4 v[4:5], off
	v_lshl_add_u64 v[4:5], v[2:3], 0, s[10:11]
	s_mov_b32 m0, s47
	v_readfirstlane_b32 s47, v95
	global_load_lds_dwordx4 v[4:5], off
	v_lshl_add_u64 v[4:5], v[0:1], 0, s[12:13]
	s_mov_b32 m0, s47
	v_readfirstlane_b32 s47, v96
	global_load_lds_dwordx4 v[4:5], off
	v_lshl_add_u64 v[4:5], v[2:3], 0, s[12:13]
	s_mov_b32 m0, s47
	v_readfirstlane_b32 s47, v97
	global_load_lds_dwordx4 v[4:5], off
	v_lshl_add_u64 v[0:1], v[0:1], 0, s[14:15]
	s_mov_b32 m0, s47
	v_readfirstlane_b32 s47, v98
	global_load_lds_dwordx4 v[0:1], off
	v_lshl_add_u64 v[0:1], v[2:3], 0, s[14:15]
	s_mov_b32 m0, s47
	s_or_b32 s36, s52, s36
	global_load_lds_dwordx4 v[0:1], off
	v_lshl_add_u64 v[64:65], v[76:77], 0, s[8:9]
	v_lshl_add_u64 v[66:67], v[74:75], 0, s[36:37]
	s_mov_b64 s[36:37], 0
	s_mov_b32 s47, 0
	v_mov_b32_e32 v20, 0
	v_mov_b32_e32 v21, v73
	v_mov_b32_e32 v22, v73
	v_mov_b32_e32 v23, v73
	v_mov_b32_e32 v0, 0
	v_mov_b32_e32 v1, v73
	v_mov_b32_e32 v2, v73
	v_mov_b32_e32 v3, v73
	v_mov_b32_e32 v4, 0
	v_mov_b32_e32 v5, v73
	v_mov_b32_e32 v6, v73
	v_mov_b32_e32 v7, v73
	v_mov_b32_e32 v8, 0
	v_mov_b32_e32 v9, v73
	v_mov_b32_e32 v10, v73
	v_mov_b32_e32 v11, v73
	v_mov_b32_e32 v12, 0
	v_mov_b32_e32 v13, v73
	v_mov_b32_e32 v14, v73
	v_mov_b32_e32 v15, v73
	v_mov_b32_e32 v16, 0
	v_mov_b32_e32 v17, v73
	v_mov_b32_e32 v18, v73
	v_mov_b32_e32 v19, v73
	v_mov_b32_e32 v24, 0
	v_mov_b32_e32 v25, v73
	v_mov_b32_e32 v26, v73
	v_mov_b32_e32 v27, v73
	v_mov_b32_e32 v28, 0
	v_mov_b32_e32 v29, v73
	v_mov_b32_e32 v30, v73
	v_mov_b32_e32 v31, v73
	v_mov_b32_e32 v32, 0
	v_mov_b32_e32 v33, v73
	v_mov_b32_e32 v34, v73
	v_mov_b32_e32 v35, v73
	v_mov_b32_e32 v36, 0
	v_mov_b32_e32 v37, v73
	v_mov_b32_e32 v38, v73
	v_mov_b32_e32 v39, v73
	v_mov_b32_e32 v40, 0
	v_mov_b32_e32 v41, v73
	v_mov_b32_e32 v42, v73
	v_mov_b32_e32 v43, v73
	v_mov_b32_e32 v44, 0
	v_mov_b32_e32 v45, v73
	v_mov_b32_e32 v46, v73
	v_mov_b32_e32 v47, v73
	v_mov_b32_e32 v48, 0
	v_mov_b32_e32 v49, v73
	v_mov_b32_e32 v50, v73
	v_mov_b32_e32 v51, v73
	v_mov_b32_e32 v52, 0
	v_mov_b32_e32 v53, v73
	v_mov_b32_e32 v54, v73
	v_mov_b32_e32 v55, v73
	v_mov_b32_e32 v56, 0
	v_mov_b32_e32 v57, v73
	v_mov_b32_e32 v58, v73
	v_mov_b32_e32 v59, v73
	v_mov_b32_e32 v60, 0
	v_mov_b32_e32 v61, v73
	v_mov_b32_e32 v62, v73
	v_mov_b32_e32 v63, v73
	v_readfirstlane_b32 s84, v66
	v_readfirstlane_b32 s85, v67
	v_readfirstlane_b32 s72, v64
	v_readfirstlane_b32 s73, v65
	v_readfirstlane_b32 s75, v88
	s_nop 1
	v_subrev_u32_e32 v236, s84, v66
	v_subrev_u32_e32 v237, s72, v64
	v_add_u32_e32 v238, 0x41000, v236
	v_add_u32_e32 v239, 0x41000, v237
	v_add_u32_e32 v240, 0x82000, v236
	v_add_u32_e32 v241, 0x82000, v237
	v_add_u32_e32 v242, 0xc3000, v236
	v_add_u32_e32 v243, 0xc3000, v237
	s_add_u32 s84, s84, 0x4510080
	s_addc_u32 s85, s85, 0
	s_add_u32 s72, s72, 0x1910080
	s_addc_u32 s73, s73, 0
	s_add_u32 s71, s75, 0x8000
	s_mov_b32 m0, s71
	s_nop 0
	global_load_lds_dwordx4 v236, s[84:85]
	s_add_u32 m0, s71, 0x4000
	s_nop 0
	global_load_lds_dwordx4 v237, s[72:73]
	s_add_u32 m0, s71, 0x1000
	s_nop 0
	global_load_lds_dwordx4 v238, s[84:85]
	s_add_u32 m0, s71, 0x5000
	s_nop 0
	global_load_lds_dwordx4 v239, s[72:73]
	s_add_u32 m0, s71, 0x2000
	s_nop 0
	global_load_lds_dwordx4 v240, s[84:85]
	s_add_u32 m0, s71, 0x6000
	s_nop 0
	global_load_lds_dwordx4 v241, s[72:73]
	s_add_u32 m0, s71, 0x3000
	s_nop 0
	global_load_lds_dwordx4 v242, s[84:85]
	s_add_u32 m0, s71, 0x7000
	s_nop 0
	global_load_lds_dwordx4 v243, s[72:73]
	s_add_u32 s84, s84, 0x80
	s_addc_u32 s85, s85, 0
	s_add_u32 s72, s72, 0x80
	s_addc_u32 s73, s73, 0
.LBB0_1091:
	s_add_i32 s48, s47, 0x8000
	s_and_b32 s8, s47, 0x8000
	s_and_b32 s47, s48, 0x8000
	s_add_i32 s49, s8, 0
	s_add_i32 s8, s47, 0
	s_add_u32 s71, s49, s75
	s_waitcnt vmcnt(8)
	s_barrier
	v_add3_u32 v169, s49, v84, v87
	v_add3_u32 v210, s49, v87, v89
	v_add3_u32 v211, s49, v84, v90
	v_add3_u32 v212, s49, v89, v90
	ds_read_b128 v[104:107], v210
	ds_read_b128 v[68:71], v169 offset:16384
	ds_read_b128 v[100:103], v169 offset:18432
	ds_read_b128 v[108:111], v210 offset:2048
	ds_read_b128 v[112:115], v169 offset:20480
	ds_read_b128 v[116:119], v169 offset:22528
	ds_read_b128 v[120:123], v169 offset:24576
	ds_read_b128 v[124:127], v169 offset:26624
	ds_read_b128 v[128:131], v169 offset:28672
	ds_read_b128 v[132:135], v169 offset:30720
	ds_read_b128 v[178:181], v212
	ds_read_b128 v[170:173], v211 offset:16384
	ds_read_b128 v[174:177], v211 offset:18432
	ds_read_b128 v[182:185], v212 offset:2048
	ds_read_b128 v[186:189], v211 offset:20480
	ds_read_b128 v[190:193], v211 offset:22528
	ds_read_b128 v[194:197], v211 offset:24576
	ds_read_b128 v[198:201], v211 offset:26624
	ds_read_b128 v[202:205], v211 offset:28672
	ds_read_b128 v[206:209], v211 offset:30720
	s_waitcnt lgkmcnt(0)
	s_barrier
	s_cmpk_eq_i32 s36, 0x700
	s_cbranch_scc1 .Lgskip_1091
	s_mov_b32 m0, s71
	s_nop 0
	global_load_lds_dwordx4 v236, s[84:85]
	s_add_u32 m0, s71, 0x4000
	s_nop 0
	global_load_lds_dwordx4 v237, s[72:73]
	s_add_u32 m0, s71, 0x1000
	s_nop 0
	global_load_lds_dwordx4 v238, s[84:85]
	s_add_u32 m0, s71, 0x5000
	s_nop 0
	global_load_lds_dwordx4 v239, s[72:73]
	s_add_u32 m0, s71, 0x2000
	s_nop 0
	global_load_lds_dwordx4 v240, s[84:85]
	s_add_u32 m0, s71, 0x6000
	s_nop 0
	global_load_lds_dwordx4 v241, s[72:73]
	s_add_u32 m0, s71, 0x3000
	s_nop 0
	global_load_lds_dwordx4 v242, s[84:85]
	s_add_u32 m0, s71, 0x7000
	s_nop 0
	global_load_lds_dwordx4 v243, s[72:73]
	s_add_u32 s84, s84, 0x80
	s_addc_u32 s85, s85, 0
	s_add_u32 s72, s72, 0x80
	s_addc_u32 s73, s73, 0
.Lgskip_1091:
	s_add_u32 s36, s36, 0x80
	s_addc_u32 s37, s37, 0
	s_cmpk_eq_i32 s36, 0x780
	s_mov_b32 s47, s48
	v_mfma_f32_16x16x32_bf16 v[60:63], v[68:71], v[104:107], v[60:63]
	v_mfma_f32_16x16x32_bf16 v[56:59], v[100:103], v[104:107], v[56:59]
	v_mfma_f32_16x16x32_bf16 v[28:31], v[68:71], v[108:111], v[28:31]
	v_mfma_f32_16x16x32_bf16 v[24:27], v[100:103], v[108:111], v[24:27]
	v_mfma_f32_16x16x32_bf16 v[52:55], v[112:115], v[104:107], v[52:55]
	v_mfma_f32_16x16x32_bf16 v[16:19], v[112:115], v[108:111], v[16:19]
	v_mfma_f32_16x16x32_bf16 v[48:51], v[116:119], v[104:107], v[48:51]
	v_mfma_f32_16x16x32_bf16 v[12:15], v[116:119], v[108:111], v[12:15]
	v_mfma_f32_16x16x32_bf16 v[44:47], v[120:123], v[104:107], v[44:47]
	v_mfma_f32_16x16x32_bf16 v[8:11], v[120:123], v[108:111], v[8:11]
	v_mfma_f32_16x16x32_bf16 v[40:43], v[124:127], v[104:107], v[40:43]
	v_mfma_f32_16x16x32_bf16 v[4:7], v[124:127], v[108:111], v[4:7]
	v_mfma_f32_16x16x32_bf16 v[36:39], v[128:131], v[104:107], v[36:39]
	v_mfma_f32_16x16x32_bf16 v[0:3], v[128:131], v[108:111], v[0:3]
	v_mfma_f32_16x16x32_bf16 v[32:35], v[132:135], v[104:107], v[32:35]
	v_mfma_f32_16x16x32_bf16 v[20:23], v[132:135], v[108:111], v[20:23]
	v_mfma_f32_16x16x32_bf16 v[60:63], v[170:173], v[178:181], v[60:63]
	v_mfma_f32_16x16x32_bf16 v[56:59], v[174:177], v[178:181], v[56:59]
	v_mfma_f32_16x16x32_bf16 v[28:31], v[170:173], v[182:185], v[28:31]
	v_mfma_f32_16x16x32_bf16 v[24:27], v[174:177], v[182:185], v[24:27]
	v_mfma_f32_16x16x32_bf16 v[52:55], v[186:189], v[178:181], v[52:55]
	v_mfma_f32_16x16x32_bf16 v[16:19], v[186:189], v[182:185], v[16:19]
	v_mfma_f32_16x16x32_bf16 v[48:51], v[190:193], v[178:181], v[48:51]
	v_mfma_f32_16x16x32_bf16 v[12:15], v[190:193], v[182:185], v[12:15]
	v_mfma_f32_16x16x32_bf16 v[44:47], v[194:197], v[178:181], v[44:47]
	v_mfma_f32_16x16x32_bf16 v[8:11], v[194:197], v[182:185], v[8:11]
	v_mfma_f32_16x16x32_bf16 v[40:43], v[198:201], v[178:181], v[40:43]
	v_mfma_f32_16x16x32_bf16 v[4:7], v[198:201], v[182:185], v[4:7]
	v_mfma_f32_16x16x32_bf16 v[36:39], v[202:205], v[178:181], v[36:39]
	v_mfma_f32_16x16x32_bf16 v[0:3], v[202:205], v[182:185], v[0:3]
	v_mfma_f32_16x16x32_bf16 v[32:35], v[206:209], v[178:181], v[32:35]
	v_mfma_f32_16x16x32_bf16 v[20:23], v[206:209], v[182:185], v[20:23]
	s_cbranch_scc0 .LBB0_1091
	v_lshl_add_u32 v99, s46, 7, v85
	v_mul_hi_i32 v64, v99, s39
	v_lshrrev_b32_e32 v65, 31, v64
	v_ashrrev_i32_e32 v64, 11, v64
	v_add_u32_e32 v64, v64, v65
	v_mad_i32_i24 v65, v64, s40, v99
	v_cmp_lt_i32_e32 vcc, s41, v65
	v_lshl_or_b32 v72, s45, 9, v86
	s_waitcnt vmcnt(0)
	v_cndmask_b32_e32 v64, 2, v64, vcc
	v_mul_hi_i32_i24_e32 v65, 0x6000, v64
	v_mul_i32_i24_e32 v64, 0x6000, v64
	v_lshl_add_u64 v[64:65], s[94:95], 0, v[64:65]
	v_lshl_add_u64 v[150:151], v[64:65], 0, s[34:35]
	v_lshl_add_u64 v[64:65], v[150:151], 0, v[72:73]
	s_barrier
	global_load_dwordx4 v[100:103], v[64:65], off
	v_add3_u32 v64, s8, v87, v89
	v_add_u32_e32 v68, s8, v84
	ds_read_b128 v[104:107], v64
	ds_read_b128 v[108:111], v64 offset:2048
	v_add3_u32 v65, s8, v90, v89
	v_add_u32_e32 v145, v68, v87
	ds_read_b128 v[112:115], v65
	ds_read_b128 v[64:67], v65 offset:2048
	v_add_u32_e32 v168, v68, v90
	ds_read_b128 v[116:119], v145 offset:16384
	ds_read_b128 v[120:123], v145 offset:18432
	ds_read_b128 v[124:127], v168 offset:16384
	ds_read_b128 v[68:71], v168 offset:18432
	v_mul_hi_i32 v128, v99, s38
	s_waitcnt lgkmcnt(3)
	v_mfma_f32_16x16x32_bf16 v[60:63], v[116:119], v[104:107], v[60:63]
	v_lshrrev_b32_e32 v129, 31, v128
	v_lshrrev_b32_e32 v128, 11, v128
	v_add_u32_e32 v128, v128, v129
	v_lshl_add_u32 v128, v128, 13, v99
	s_lshl_b32 s8, s44, 9
	v_ashrrev_i32_e32 v129, 31, v128
	s_waitcnt lgkmcnt(1)
	v_mfma_f32_16x16x32_bf16 v[60:63], v[124:127], v[112:115], v[60:63]
	v_lshl_add_u64 v[128:129], v[128:129], 0, s[8:9]
	v_lshlrev_b64 v[128:129], 12, v[128:129]
	v_lshl_add_u64 v[128:129], s[6:7], 0, v[128:129]
	v_mov_b32_e32 v153, v73
	v_or_b32_e32 v152, 16, v72
	v_lshl_add_u64 v[154:155], v[128:129], 0, v[72:73]
	v_lshl_add_u64 v[128:129], v[150:151], 0, v[152:153]
	v_mfma_f32_16x16x32_bf16 v[56:59], v[120:123], v[104:107], v[56:59]
	v_mov_b32_e32 v157, v73
	v_or_b32_e32 v156, 0x80, v72
	v_mov_b32_e32 v159, v73
	s_waitcnt lgkmcnt(0)
	v_mfma_f32_16x16x32_bf16 v[56:59], v[68:71], v[112:115], v[56:59]
	v_or_b32_e32 v158, 0x90, v72
	v_lshl_add_u64 v[136:137], v[150:151], 0, v[158:159]
	v_mov_b32_e32 v161, v73
	v_or_b32_e32 v160, 0x100, v72
	v_mov_b32_e32 v163, v73
	v_or_b32_e32 v162, 0x110, v72
	v_lshl_add_u64 v[146:147], v[150:151], 0, v[162:163]
	v_mov_b32_e32 v165, v73
	v_or_b32_e32 v164, 0x180, v72
	v_lshl_add_u64 v[166:167], v[150:151], 0, v[164:165]
	v_mfma_f32_16x16x32_bf16 v[28:31], v[116:119], v[108:111], v[28:31]
	v_or_b32_e32 v99, 16, v99
	s_add_i32 s43, s43, s33
	s_add_i32 s42, s42, s33
	v_mfma_f32_16x16x32_bf16 v[28:31], v[124:127], v[64:67], v[28:31]
	s_cmpk_gt_i32 s43, 0x7f
	s_waitcnt vmcnt(0)
	v_pk_mul_f32 v[62:63], v[62:63], v[102:103]
	v_pk_mul_f32 v[60:61], v[60:61], v[100:101]
	global_store_dwordx4 v[154:155], v[60:63], off
	global_load_dwordx4 v[60:63], v[128:129], off
	v_lshl_add_u64 v[100:101], v[150:151], 0, v[156:157]
	v_mfma_f32_16x16x32_bf16 v[24:27], v[120:123], v[108:111], v[24:27]
	s_waitcnt vmcnt(0)
	v_pk_mul_f32 v[58:59], v[58:59], v[62:63]
	v_pk_mul_f32 v[56:57], v[56:57], v[60:61]
	global_store_dwordx4 v[154:155], v[56:59], off offset:16
	global_load_dwordx4 v[56:59], v[100:101], off
	ds_read_b128 v[60:63], v145 offset:20480
	ds_read_b128 v[100:103], v168 offset:20480
	s_waitcnt lgkmcnt(1)
	v_mfma_f32_16x16x32_bf16 v[52:55], v[60:63], v[104:107], v[52:55]
	ds_read_b128 v[128:131], v145 offset:22528
	ds_read_b128 v[132:135], v168 offset:22528
	s_waitcnt lgkmcnt(2)
	v_mfma_f32_16x16x32_bf16 v[52:55], v[100:103], v[112:115], v[52:55]
	s_waitcnt lgkmcnt(1)
	v_mfma_f32_16x16x32_bf16 v[48:51], v[128:131], v[104:107], v[48:51]
	s_waitcnt vmcnt(0)
	s_nop 4
	v_pk_mul_f32 v[54:55], v[54:55], v[58:59]
	v_pk_mul_f32 v[52:53], v[52:53], v[56:57]
	global_store_dwordx4 v[154:155], v[52:55], off offset:128
	global_load_dwordx4 v[52:55], v[136:137], off
	s_waitcnt lgkmcnt(0)
	v_mfma_f32_16x16x32_bf16 v[48:51], v[132:135], v[112:115], v[48:51]
	v_lshl_add_u64 v[56:57], v[150:151], 0, v[160:161]
	v_mfma_f32_16x16x32_bf16 v[24:27], v[68:71], v[64:67], v[24:27]
	v_mfma_f32_16x16x32_bf16 v[16:19], v[60:63], v[108:111], v[16:19]
	s_waitcnt vmcnt(0)
	s_nop 3
	v_pk_mul_f32 v[50:51], v[50:51], v[54:55]
	v_pk_mul_f32 v[48:49], v[48:49], v[52:53]
	global_store_dwordx4 v[154:155], v[48:51], off offset:144
	global_load_dwordx4 v[48:51], v[56:57], off
	ds_read_b128 v[52:55], v145 offset:24576
	ds_read_b128 v[56:59], v168 offset:24576
	s_waitcnt lgkmcnt(1)
	v_mfma_f32_16x16x32_bf16 v[44:47], v[52:55], v[104:107], v[44:47]
	ds_read_b128 v[136:139], v145 offset:26624
	ds_read_b128 v[140:143], v168 offset:26624
	s_waitcnt lgkmcnt(2)
	v_mfma_f32_16x16x32_bf16 v[44:47], v[56:59], v[112:115], v[44:47]
	s_waitcnt lgkmcnt(1)
	v_mfma_f32_16x16x32_bf16 v[40:43], v[136:139], v[104:107], v[40:43]
	s_waitcnt vmcnt(0)
	s_nop 4
	v_pk_mul_f32 v[46:47], v[46:47], v[50:51]
	v_pk_mul_f32 v[44:45], v[44:45], v[48:49]
	global_store_dwordx4 v[154:155], v[44:47], off offset:256
	global_load_dwordx4 v[44:47], v[146:147], off
	s_waitcnt lgkmcnt(0)
	v_mfma_f32_16x16x32_bf16 v[40:43], v[140:143], v[112:115], v[40:43]
	ds_read_b128 v[48:51], v145 offset:28672
	ds_read_b128 v[146:149], v145 offset:30720
	s_waitcnt lgkmcnt(1)
	v_mfma_f32_16x16x32_bf16 v[36:39], v[48:51], v[104:107], v[36:39]
	s_waitcnt vmcnt(0)
	s_nop 2
	v_pk_mul_f32 v[42:43], v[42:43], v[46:47]
	v_pk_mul_f32 v[40:41], v[40:41], v[44:45]
	global_store_dwordx4 v[154:155], v[40:43], off offset:272
	global_load_dwordx4 v[40:43], v[166:167], off
	ds_read_b128 v[44:47], v168 offset:28672
	s_waitcnt lgkmcnt(1)
	v_mfma_f32_16x16x32_bf16 v[32:35], v[146:149], v[104:107], v[32:35]
	ds_read_b128 v[104:107], v168 offset:30720
	v_mov_b32_e32 v167, v73
	v_or_b32_e32 v166, 0x190, v72
	s_waitcnt lgkmcnt(1)
	v_mfma_f32_16x16x32_bf16 v[36:39], v[44:47], v[112:115], v[36:39]
	v_lshl_add_u64 v[116:117], v[150:151], 0, v[166:167]
	s_waitcnt vmcnt(0)
	s_nop 5
	v_pk_mul_f32 v[38:39], v[38:39], v[42:43]
	v_pk_mul_f32 v[36:37], v[36:37], v[40:41]
	global_store_dwordx4 v[154:155], v[36:39], off offset:384
	global_load_dwordx4 v[36:39], v[116:117], off
	v_mul_hi_i32 v40, v99, s39
	v_lshrrev_b32_e32 v41, 31, v40
	v_ashrrev_i32_e32 v40, 11, v40
	v_add_u32_e32 v40, v40, v41
	v_mad_i32_i24 v41, v40, s40, v99
	v_cmp_lt_i32_e32 vcc, s41, v41
	s_waitcnt lgkmcnt(0)
	v_mfma_f32_16x16x32_bf16 v[32:35], v[104:107], v[112:115], v[32:35]
	v_cndmask_b32_e32 v40, 2, v40, vcc
	v_mul_hi_i32_i24_e32 v41, 0x6000, v40
	v_mul_i32_i24_e32 v40, 0x6000, v40
	v_lshl_add_u64 v[40:41], s[94:95], 0, v[40:41]
	v_lshl_add_u64 v[40:41], v[40:41], 0, s[34:35]
	v_lshl_add_u64 v[42:43], v[40:41], 0, v[72:73]
	v_mfma_f32_16x16x32_bf16 v[16:19], v[100:103], v[64:67], v[16:19]
	s_waitcnt vmcnt(0)
	v_pk_mul_f32 v[34:35], v[34:35], v[38:39]
	v_pk_mul_f32 v[32:33], v[32:33], v[36:37]
	global_store_dwordx4 v[154:155], v[32:35], off offset:400
	global_load_dwordx4 v[32:35], v[42:43], off
	v_mul_hi_i32 v36, v99, s38
	v_lshrrev_b32_e32 v37, 31, v36
	v_lshrrev_b32_e32 v36, 11, v36
	v_add_u32_e32 v36, v36, v37
	v_lshl_add_u32 v36, v36, 13, v99
	v_ashrrev_i32_e32 v37, 31, v36
	v_lshl_add_u64 v[36:37], v[36:37], 0, s[8:9]
	v_lshlrev_b64 v[36:37], 12, v[36:37]
	v_lshl_add_u64 v[36:37], s[6:7], 0, v[36:37]
	v_lshl_add_u64 v[36:37], v[36:37], 0, v[72:73]
	v_lshl_add_u64 v[38:39], v[40:41], 0, v[152:153]
	v_mfma_f32_16x16x32_bf16 v[12:15], v[128:131], v[108:111], v[12:15]
	s_waitcnt vmcnt(0)
	v_pk_mul_f32 v[30:31], v[30:31], v[34:35]
	v_pk_mul_f32 v[28:29], v[28:29], v[32:33]
	global_store_dwordx4 v[36:37], v[28:31], off
	global_load_dwordx4 v[28:31], v[38:39], off
	v_lshl_add_u64 v[32:33], v[40:41], 0, v[156:157]
	v_mfma_f32_16x16x32_bf16 v[12:15], v[132:135], v[64:67], v[12:15]
	s_waitcnt vmcnt(0)
	v_pk_mul_f32 v[26:27], v[26:27], v[30:31]
	v_pk_mul_f32 v[24:25], v[24:25], v[28:29]
	global_store_dwordx4 v[36:37], v[24:27], off offset:16
	global_load_dwordx4 v[24:27], v[32:33], off
	v_lshl_add_u64 v[28:29], v[40:41], 0, v[158:159]
	v_mfma_f32_16x16x32_bf16 v[8:11], v[52:55], v[108:111], v[8:11]
	s_waitcnt vmcnt(0)
	v_pk_mul_f32 v[18:19], v[18:19], v[26:27]
	v_pk_mul_f32 v[16:17], v[16:17], v[24:25]
	global_store_dwordx4 v[36:37], v[16:19], off offset:128
	global_load_dwordx4 v[16:19], v[28:29], off
	v_lshl_add_u64 v[24:25], v[40:41], 0, v[160:161]
	v_mfma_f32_16x16x32_bf16 v[8:11], v[56:59], v[64:67], v[8:11]
	s_waitcnt vmcnt(0)
	v_pk_mul_f32 v[14:15], v[14:15], v[18:19]
	v_pk_mul_f32 v[12:13], v[12:13], v[16:17]
	global_store_dwordx4 v[36:37], v[12:15], off offset:144
	global_load_dwordx4 v[12:15], v[24:25], off
	v_lshl_add_u64 v[16:17], v[40:41], 0, v[162:163]
	v_mfma_f32_16x16x32_bf16 v[4:7], v[136:139], v[108:111], v[4:7]
	s_waitcnt vmcnt(0)
	v_pk_mul_f32 v[10:11], v[10:11], v[14:15]
	v_pk_mul_f32 v[8:9], v[8:9], v[12:13]
	global_store_dwordx4 v[36:37], v[8:11], off offset:256
	global_load_dwordx4 v[8:11], v[16:17], off
	v_mfma_f32_16x16x32_bf16 v[4:7], v[140:143], v[64:67], v[4:7]
	v_lshl_add_u64 v[12:13], v[40:41], 0, v[164:165]
	v_mfma_f32_16x16x32_bf16 v[0:3], v[48:51], v[108:111], v[0:3]
	v_mfma_f32_16x16x32_bf16 v[0:3], v[44:47], v[64:67], v[0:3]
	s_waitcnt vmcnt(0)
	s_nop 3
	v_pk_mul_f32 v[6:7], v[6:7], v[10:11]
	v_pk_mul_f32 v[4:5], v[4:5], v[8:9]
	global_store_dwordx4 v[36:37], v[4:7], off offset:272
	global_load_dwordx4 v[4:7], v[12:13], off
	v_lshl_add_u64 v[8:9], v[40:41], 0, v[166:167]
	v_mfma_f32_16x16x32_bf16 v[20:23], v[146:149], v[108:111], v[20:23]
	s_waitcnt vmcnt(0)
	v_pk_mul_f32 v[2:3], v[2:3], v[6:7]
	v_pk_mul_f32 v[0:1], v[0:1], v[4:5]
	global_store_dwordx4 v[36:37], v[0:3], off offset:384
	global_load_dwordx4 v[0:3], v[8:9], off
	v_mfma_f32_16x16x32_bf16 v[4:7], v[104:107], v[64:67], v[20:23]
	s_waitcnt vmcnt(0)
	s_nop 6
	v_pk_mul_f32 v[2:3], v[6:7], v[2:3]
	v_pk_mul_f32 v[0:1], v[4:5], v[0:1]
	global_store_dwordx4 v[36:37], v[0:3], off offset:400
	s_cbranch_scc0 .LBB0_1090

.LBB0_1216:
	s_ashr_i32 s0, s52, 31
	s_lshr_b32 s0, s0, 29
	s_add_i32 s0, s52, s0
	s_ashr_i32 s1, s0, 3
	s_and_b32 s0, s0, -8
	s_sub_i32 s0, s52, s0
	s_cmp_lt_i32 s0, 0
	s_cselect_b32 s2, s47, 0x16b
	s_mul_i32 s0, s2, s0
	s_add_i32 s3, s0, s1
	s_mul_hi_i32 s0, s3, 0x2e8ba2e9
	s_lshr_b32 s1, s0, 31
	s_ashr_i32 s0, s0, 5
	s_add_i32 s0, s0, s1
	s_lshl_b32 s41, s0, 3
	s_mul_i32 s40, s0, 0xb0
	s_sub_i32 s0, 0x84, s41
	s_min_u32 s42, s0, 8
	s_sub_i32 s2, s3, s40
	v_cvt_f32_ubyte0_e32 v1, s42
	v_cvt_f32_i32_e32 v0, s2
	v_rcp_iflag_f32_e32 v2, v1
	s_ashr_i32 s0, s2, 30
	s_or_b32 s38, s0, 1
	s_waitcnt vmcnt(63) expcnt(7) lgkmcnt(15)
	v_mul_f32_e32 v2, v0, v2
	v_trunc_f32_e32 v2, v2
	v_fma_f32 v0, -v2, v1, v0
	v_cvt_i32_f32_e32 v2, v2
	v_cmp_ge_f32_e64 s[0:1], |v0|, v1
	s_and_b64 s[0:1], s[0:1], exec
	s_cselect_b32 s0, s38, 0
	v_readfirstlane_b32 s38, v2
	s_add_i32 s38, s38, s0
	s_mul_i32 s42, s38, s42
	s_sub_i32 s0, s2, s42
	s_sext_i32_i16 s0, s0
	s_sext_i32_i16 s39, s38
	s_add_i32 s2, s41, s0
	v_mad_i64_i32 v[0:1], s[0:1], s2, v93, v[66:67]
	v_mad_i64_i32 v[2:3], s[0:1], s39, v93, v[68:69]
	v_readfirstlane_b32 s0, v94
	s_mov_b32 m0, s0
	v_readfirstlane_b32 s0, v95
	s_barrier
	global_load_lds_dwordx4 v[0:1], off
	s_mov_b32 m0, s0
	v_readfirstlane_b32 s0, v96
	global_load_lds_dwordx4 v[2:3], off
	v_lshl_add_u64 v[4:5], v[0:1], 0, s[12:13]
	s_mov_b32 m0, s0
	v_readfirstlane_b32 s0, v97
	global_load_lds_dwordx4 v[4:5], off
	v_lshl_add_u64 v[4:5], v[2:3], 0, s[12:13]
	s_mov_b32 m0, s0
	v_readfirstlane_b32 s0, v98
	global_load_lds_dwordx4 v[4:5], off
	v_lshl_add_u64 v[4:5], v[0:1], 0, s[14:15]
	s_mov_b32 m0, s0
	v_readfirstlane_b32 s0, v99
	global_load_lds_dwordx4 v[4:5], off
	v_lshl_add_u64 v[4:5], v[2:3], 0, s[14:15]
	s_mov_b32 m0, s0
	v_readfirstlane_b32 s0, v100
	global_load_lds_dwordx4 v[4:5], off
	v_lshl_add_u64 v[0:1], v[0:1], 0, s[16:17]
	s_mov_b32 m0, s0
	v_readfirstlane_b32 s0, v101
	global_load_lds_dwordx4 v[0:1], off
	v_lshl_add_u64 v[0:1], v[2:3], 0, s[16:17]
	s_mov_b32 m0, s0
	s_sub_i32 s0, s3, s42
	global_load_lds_dwordx4 v[0:1], off
	s_sub_i32 s0, s0, s40
	s_sext_i32_i16 s0, s0
	s_add_i32 s41, s41, s0
	v_mad_i64_i32 v[82:83], s[0:1], s41, v93, v[78:79]
	v_mad_i64_i32 v[84:85], s[0:1], s39, v93, v[80:81]
	s_mov_b64 s[0:1], 0
	s_mov_b32 s3, 0
	v_mov_b32_e32 v40, 0
	v_mov_b32_e32 v41, v65
	v_mov_b32_e32 v42, v65
	v_mov_b32_e32 v43, v65
	v_mov_b32_e32 v0, 0
	v_mov_b32_e32 v1, v65
	v_mov_b32_e32 v2, v65
	v_mov_b32_e32 v3, v65
	v_mov_b32_e32 v4, 0
	v_mov_b32_e32 v5, v65
	v_mov_b32_e32 v6, v65
	v_mov_b32_e32 v7, v65
	v_mov_b32_e32 v8, 0
	v_mov_b32_e32 v9, v65
	v_mov_b32_e32 v10, v65
	v_mov_b32_e32 v11, v65
	v_mov_b32_e32 v12, 0
	v_mov_b32_e32 v13, v65
	v_mov_b32_e32 v14, v65
	v_mov_b32_e32 v15, v65
	v_mov_b32_e32 v16, 0
	v_mov_b32_e32 v17, v65
	v_mov_b32_e32 v18, v65
	v_mov_b32_e32 v19, v65
	v_mov_b32_e32 v20, 0
	v_mov_b32_e32 v21, v65
	v_mov_b32_e32 v22, v65
	v_mov_b32_e32 v23, v65
	v_mov_b32_e32 v24, 0
	v_mov_b32_e32 v25, v65
	v_mov_b32_e32 v26, v65
	v_mov_b32_e32 v27, v65
	v_mov_b32_e32 v28, 0
	v_mov_b32_e32 v29, v65
	v_mov_b32_e32 v30, v65
	v_mov_b32_e32 v31, v65
	v_mov_b32_e32 v32, 0
	v_mov_b32_e32 v33, v65
	v_mov_b32_e32 v34, v65
	v_mov_b32_e32 v35, v65
	v_mov_b32_e32 v36, 0
	v_mov_b32_e32 v37, v65
	v_mov_b32_e32 v38, v65
	v_mov_b32_e32 v39, v65
	v_mov_b32_e32 v44, 0
	v_mov_b32_e32 v45, v65
	v_mov_b32_e32 v46, v65
	v_mov_b32_e32 v47, v65
	v_mov_b32_e32 v48, 0
	v_mov_b32_e32 v49, v65
	v_mov_b32_e32 v50, v65
	v_mov_b32_e32 v51, v65
	v_mov_b32_e32 v52, 0
	v_mov_b32_e32 v53, v65
	v_mov_b32_e32 v54, v65
	v_mov_b32_e32 v55, v65
	v_mov_b32_e32 v56, 0
	v_mov_b32_e32 v57, v65
	v_mov_b32_e32 v58, v65
	v_mov_b32_e32 v59, v65
	v_mov_b32_e32 v60, 0
	v_mov_b32_e32 v61, v65
	v_mov_b32_e32 v62, v65
	v_mov_b32_e32 v63, v65
	v_readfirstlane_b32 s96, v82
	v_readfirstlane_b32 s97, v83
	v_readfirstlane_b32 s88, v84
	v_readfirstlane_b32 s89, v85
	v_readfirstlane_b32 s87, v86
	s_nop 1
	v_subrev_u32_e32 v244, s96, v82
	v_subrev_u32_e32 v245, s88, v84
	v_add_u32_e32 v246, 0x11000, v244
	v_add_u32_e32 v247, 0x11000, v245
	v_add_u32_e32 v248, 0x22000, v244
	v_add_u32_e32 v249, 0x22000, v245
	v_add_u32_e32 v250, 0x33000, v244
	v_add_u32_e32 v251, 0x33000, v245
	s_add_u32 s96, s96, 0x2200080
	s_addc_u32 s97, s97, 0
	s_add_u32 s88, s88, 0xd990080
	s_addc_u32 s89, s89, 0
	s_add_u32 s86, s87, 0x8000
	s_mov_b32 m0, s86
	s_nop 0
	global_load_lds_dwordx4 v244, s[96:97]
	s_add_u32 m0, s86, 0x4000
	s_nop 0
	global_load_lds_dwordx4 v245, s[88:89]
	s_add_u32 m0, s86, 0x1000
	s_nop 0
	global_load_lds_dwordx4 v246, s[96:97]
	s_add_u32 m0, s86, 0x5000
	s_nop 0
	global_load_lds_dwordx4 v247, s[88:89]
	s_add_u32 m0, s86, 0x2000
	s_nop 0
	global_load_lds_dwordx4 v248, s[96:97]
	s_add_u32 m0, s86, 0x6000
	s_nop 0
	global_load_lds_dwordx4 v249, s[88:89]
	s_add_u32 m0, s86, 0x3000
	s_nop 0
	global_load_lds_dwordx4 v250, s[96:97]
	s_add_u32 m0, s86, 0x7000
	s_nop 0
	global_load_lds_dwordx4 v251, s[88:89]
	s_add_u32 s96, s96, 0x80
	s_addc_u32 s97, s97, 0
	s_add_u32 s88, s88, 0x80
	s_addc_u32 s89, s89, 0
.LBB0_1217:
	s_add_i32 s41, s3, 0x8000
	s_and_b32 s40, s41, 0x8000
	s_add_i32 s40, s40, 0
	s_and_b32 s3, s3, 0x8000
	s_add_i32 s3, s3, 0
	s_add_u32 s86, s3, s87
	s_waitcnt vmcnt(8)
	s_barrier
	v_add3_u32 v145, s3, v87, v88
	v_add3_u32 v186, s3, v88, v89
	v_add3_u32 v187, s3, v87, v90
	v_add3_u32 v188, s3, v89, v90
	ds_read_b128 v[112:115], v186
	ds_read_b128 v[104:107], v145 offset:16384
	ds_read_b128 v[108:111], v145 offset:18432
	ds_read_b128 v[116:119], v186 offset:2048
	ds_read_b128 v[120:123], v145 offset:20480
	ds_read_b128 v[124:127], v145 offset:22528
	ds_read_b128 v[128:131], v145 offset:24576
	ds_read_b128 v[132:135], v145 offset:26624
	ds_read_b128 v[136:139], v145 offset:28672
	ds_read_b128 v[140:143], v145 offset:30720
	ds_read_b128 v[154:157], v188
	ds_read_b128 v[146:149], v187 offset:16384
	ds_read_b128 v[150:153], v187 offset:18432
	ds_read_b128 v[158:161], v188 offset:2048
	ds_read_b128 v[162:165], v187 offset:20480
	ds_read_b128 v[166:169], v187 offset:22528
	ds_read_b128 v[170:173], v187 offset:24576
	ds_read_b128 v[174:177], v187 offset:26624
	ds_read_b128 v[178:181], v187 offset:28672
	ds_read_b128 v[182:185], v187 offset:30720
	s_waitcnt lgkmcnt(0)
	s_barrier
	s_cmpk_eq_i32 s0, 0x700
	s_cbranch_scc1 .Lgskip_1217
	s_mov_b32 m0, s86
	s_nop 0
	global_load_lds_dwordx4 v244, s[96:97]
	s_add_u32 m0, s86, 0x4000
	s_nop 0
	global_load_lds_dwordx4 v245, s[88:89]
	s_add_u32 m0, s86, 0x1000
	s_nop 0
	global_load_lds_dwordx4 v246, s[96:97]
	s_add_u32 m0, s86, 0x5000
	s_nop 0
	global_load_lds_dwordx4 v247, s[88:89]
	s_add_u32 m0, s86, 0x2000
	s_nop 0
	global_load_lds_dwordx4 v248, s[96:97]
	s_add_u32 m0, s86, 0x6000
	s_nop 0
	global_load_lds_dwordx4 v249, s[88:89]
	s_add_u32 m0, s86, 0x3000
	s_nop 0
	global_load_lds_dwordx4 v250, s[96:97]
	s_add_u32 m0, s86, 0x7000
	s_nop 0
	global_load_lds_dwordx4 v251, s[88:89]
	s_add_u32 s96, s96, 0x80
	s_addc_u32 s97, s97, 0
	s_add_u32 s88, s88, 0x80
	s_addc_u32 s89, s89, 0
.Lgskip_1217:
	s_add_u32 s0, s0, 0x80
	s_addc_u32 s1, s1, 0
	s_cmpk_eq_i32 s0, 0x780
	s_mov_b32 s3, s41
	v_mfma_f32_16x16x32_bf16 v[60:63], v[104:107], v[112:115], v[60:63]
	v_mfma_f32_16x16x32_bf16 v[56:59], v[108:111], v[112:115], v[56:59]
	v_mfma_f32_16x16x32_bf16 v[24:27], v[104:107], v[116:119], v[24:27]
	v_mfma_f32_16x16x32_bf16 v[20:23], v[108:111], v[116:119], v[20:23]
	v_mfma_f32_16x16x32_bf16 v[52:55], v[120:123], v[112:115], v[52:55]
	v_mfma_f32_16x16x32_bf16 v[16:19], v[120:123], v[116:119], v[16:19]
	v_mfma_f32_16x16x32_bf16 v[48:51], v[124:127], v[112:115], v[48:51]
	v_mfma_f32_16x16x32_bf16 v[12:15], v[124:127], v[116:119], v[12:15]
	v_mfma_f32_16x16x32_bf16 v[44:47], v[128:131], v[112:115], v[44:47]
	v_mfma_f32_16x16x32_bf16 v[8:11], v[128:131], v[116:119], v[8:11]
	v_mfma_f32_16x16x32_bf16 v[36:39], v[132:135], v[112:115], v[36:39]
	v_mfma_f32_16x16x32_bf16 v[4:7], v[132:135], v[116:119], v[4:7]
	v_mfma_f32_16x16x32_bf16 v[32:35], v[136:139], v[112:115], v[32:35]
	v_mfma_f32_16x16x32_bf16 v[0:3], v[136:139], v[116:119], v[0:3]
	v_mfma_f32_16x16x32_bf16 v[28:31], v[140:143], v[112:115], v[28:31]
	v_mfma_f32_16x16x32_bf16 v[40:43], v[140:143], v[116:119], v[40:43]
	v_mfma_f32_16x16x32_bf16 v[60:63], v[146:149], v[154:157], v[60:63]
	v_mfma_f32_16x16x32_bf16 v[56:59], v[150:153], v[154:157], v[56:59]
	v_mfma_f32_16x16x32_bf16 v[24:27], v[146:149], v[158:161], v[24:27]
	v_mfma_f32_16x16x32_bf16 v[20:23], v[150:153], v[158:161], v[20:23]
	v_mfma_f32_16x16x32_bf16 v[52:55], v[162:165], v[154:157], v[52:55]
	v_mfma_f32_16x16x32_bf16 v[16:19], v[162:165], v[158:161], v[16:19]
	v_mfma_f32_16x16x32_bf16 v[48:51], v[166:169], v[154:157], v[48:51]
	v_mfma_f32_16x16x32_bf16 v[12:15], v[166:169], v[158:161], v[12:15]
	v_mfma_f32_16x16x32_bf16 v[44:47], v[170:173], v[154:157], v[44:47]
	v_mfma_f32_16x16x32_bf16 v[8:11], v[170:173], v[158:161], v[8:11]
	v_mfma_f32_16x16x32_bf16 v[36:39], v[174:177], v[154:157], v[36:39]
	v_mfma_f32_16x16x32_bf16 v[4:7], v[174:177], v[158:161], v[4:7]
	v_mfma_f32_16x16x32_bf16 v[32:35], v[178:181], v[154:157], v[32:35]
	v_mfma_f32_16x16x32_bf16 v[0:3], v[178:181], v[158:161], v[0:3]
	v_mfma_f32_16x16x32_bf16 v[28:31], v[182:185], v[154:157], v[28:31]
	v_mfma_f32_16x16x32_bf16 v[40:43], v[182:185], v[158:161], v[40:43]
	s_cbranch_scc0 .LBB0_1217
	v_add_u32_e32 v64, s40, v87
	v_add_u32_e32 v103, v64, v88
	v_add3_u32 v112, s40, v88, v89
	s_waitcnt vmcnt(0)
	s_barrier
	ds_read_b128 v[82:85], v103 offset:16384
	ds_read_b128 v[104:107], v103 offset:18432
	ds_read_b128 v[108:111], v112
	ds_read_b128 v[112:115], v112 offset:2048
	ds_read_b128 v[116:119], v103 offset:20480
	ds_read_b128 v[120:123], v103 offset:22528
	ds_read_b128 v[124:127], v103 offset:24576
	ds_read_b128 v[128:131], v103 offset:26624
	ds_read_b128 v[132:135], v103 offset:28672
	ds_read_b128 v[136:139], v103 offset:30720
	v_add_u32_e32 v64, v64, v90
	s_waitcnt lgkmcnt(7)
	v_mfma_f32_16x16x32_bf16 v[60:63], v[82:85], v[108:111], v[60:63]
	s_mul_hi_i32 s0, s2, 0x3e0f83e1
	s_lshr_b32 s1, s0, 31
	s_ashr_i32 s56, s0, 4
	v_mfma_f32_16x16x32_bf16 v[56:59], v[104:107], v[108:111], v[56:59]
	s_add_i32 s56, s56, s1
	s_cmp_gt_i32 s39, 11
	s_cselect_b64 s[0:1], -1, 0
	s_waitcnt lgkmcnt(4)
	v_mfma_f32_16x16x32_bf16 v[48:51], v[120:123], v[108:111], v[48:51]
	s_lshl_b32 s53, s2, 7
	s_cmp_lt_i32 s39, 12
	s_mul_i32 s54, s56, 0xffffdf00
	s_waitcnt lgkmcnt(3)
	v_mfma_f32_16x16x32_bf16 v[44:47], v[124:127], v[108:111], v[44:47]
	s_waitcnt lgkmcnt(2)
	v_mfma_f32_16x16x32_bf16 v[36:39], v[128:131], v[108:111], v[36:39]
	s_waitcnt lgkmcnt(1)
	v_mfma_f32_16x16x32_bf16 v[32:35], v[132:135], v[108:111], v[32:35]
	s_waitcnt lgkmcnt(0)
	v_mfma_f32_16x16x32_bf16 v[28:31], v[136:139], v[108:111], v[28:31]
	v_mfma_f32_16x16x32_bf16 v[24:27], v[82:85], v[112:115], v[24:27]
	ds_read_b128 v[82:85], v64 offset:16384
	v_mfma_f32_16x16x32_bf16 v[52:55], v[116:119], v[108:111], v[52:55]
	v_mfma_f32_16x16x32_bf16 v[20:23], v[104:107], v[112:115], v[20:23]
	v_mfma_f32_16x16x32_bf16 v[16:19], v[116:119], v[112:115], v[16:19]
	v_mfma_f32_16x16x32_bf16 v[12:15], v[120:123], v[112:115], v[12:15]
	v_mfma_f32_16x16x32_bf16 v[8:11], v[124:127], v[112:115], v[8:11]
	v_mfma_f32_16x16x32_bf16 v[4:7], v[128:131], v[112:115], v[4:7]
	v_mfma_f32_16x16x32_bf16 v[0:3], v[132:135], v[112:115], v[0:3]
	v_mfma_f32_16x16x32_bf16 v[104:107], v[136:139], v[112:115], v[40:43]
	s_nop 2
	v_add3_u32 v40, s40, v90, v89
	ds_read_b128 v[108:111], v64 offset:18432
	ds_read_b128 v[112:115], v40
	ds_read_b128 v[116:119], v40 offset:2048
	ds_read_b128 v[120:123], v64 offset:20480
	ds_read_b128 v[124:127], v64 offset:22528
	ds_read_b128 v[128:131], v64 offset:24576
	ds_read_b128 v[132:135], v64 offset:26624
	ds_read_b128 v[136:139], v64 offset:28672
	ds_read_b128 v[140:143], v64 offset:30720
	s_waitcnt lgkmcnt(7)
	v_mfma_f32_16x16x32_bf16 v[60:63], v[82:85], v[112:115], v[60:63]
	v_mfma_f32_16x16x32_bf16 v[56:59], v[108:111], v[112:115], v[56:59]
	s_waitcnt lgkmcnt(5)
	v_mfma_f32_16x16x32_bf16 v[52:55], v[120:123], v[112:115], v[52:55]
	s_waitcnt lgkmcnt(4)
	v_mfma_f32_16x16x32_bf16 v[48:51], v[124:127], v[112:115], v[48:51]
	s_waitcnt lgkmcnt(3)
	v_mfma_f32_16x16x32_bf16 v[44:47], v[128:131], v[112:115], v[44:47]
	s_waitcnt lgkmcnt(2)
	v_mfma_f32_16x16x32_bf16 v[40:43], v[132:135], v[112:115], v[36:39]
	s_waitcnt lgkmcnt(1)
	v_mfma_f32_16x16x32_bf16 v[36:39], v[136:139], v[112:115], v[32:35]
	s_waitcnt lgkmcnt(0)
	v_mfma_f32_16x16x32_bf16 v[32:35], v[140:143], v[112:115], v[28:31]
	v_mfma_f32_16x16x32_bf16 v[28:31], v[82:85], v[116:119], v[24:27]
	v_mfma_f32_16x16x32_bf16 v[24:27], v[108:111], v[116:119], v[20:23]
	v_mfma_f32_16x16x32_bf16 v[20:23], v[120:123], v[116:119], v[16:19]
	v_mfma_f32_16x16x32_bf16 v[16:19], v[124:127], v[116:119], v[12:15]
	v_mfma_f32_16x16x32_bf16 v[12:15], v[128:131], v[116:119], v[8:11]
	v_mfma_f32_16x16x32_bf16 v[8:11], v[132:135], v[116:119], v[4:7]
	v_mfma_f32_16x16x32_bf16 v[4:7], v[136:139], v[116:119], v[0:3]
	v_mfma_f32_16x16x32_bf16 v[0:3], v[140:143], v[116:119], v[104:107]
	s_cbranch_scc0 .LBB0_1224
	s_add_i32 s40, s54, s53
	v_add_u32_e32 v64, s40, v70
	v_cmp_lt_i32_e32 vcc, s48, v64
	s_and_saveexec_b64 s[2:3], vcc
	s_cbranch_execz .LBB0_1221
	v_lshl_add_u32 v64, v64, 5, v102
	v_lshlrev_b64 v[108:109], 2, v[64:65]
	v_lshl_add_u64 v[104:105], v[76:77], 0, v[108:109]
	global_load_dwordx4 v[82:85], v[104:105], off
	s_nop 0
	global_load_dwordx4 v[104:107], v[104:105], off offset:16
	v_lshl_add_u64 v[112:113], v[74:75], 0, v[108:109]
	global_load_dwordx4 v[108:111], v[112:113], off
	s_nop 0
	global_load_dwordx4 v[112:115], v[112:113], off offset:16
	s_waitcnt vmcnt(3)
	v_pk_mul_f32 v[116:117], v[54:55], v[84:85]
	v_pk_mul_f32 v[118:119], v[52:53], v[82:83]
	v_pk_mul_f32 v[120:121], v[62:63], v[84:85]
	v_pk_mul_f32 v[122:123], v[60:61], v[82:83]
	s_waitcnt vmcnt(2)
	v_pk_mul_f32 v[124:125], v[50:51], v[106:107]
	v_pk_mul_f32 v[126:127], v[48:49], v[104:105]
	v_pk_mul_f32 v[128:129], v[58:59], v[106:107]
	v_pk_mul_f32 v[130:131], v[56:57], v[104:105]
	v_pk_mul_f32 v[132:133], v[38:39], v[84:85]
	v_pk_mul_f32 v[134:135], v[36:37], v[82:83]
	v_pk_mul_f32 v[84:85], v[46:47], v[84:85]
	v_pk_mul_f32 v[82:83], v[44:45], v[82:83]
	v_pk_mul_f32 v[136:137], v[34:35], v[106:107]
	v_pk_mul_f32 v[138:139], v[32:33], v[104:105]
	v_pk_mul_f32 v[106:107], v[42:43], v[106:107]
	v_pk_mul_f32 v[104:105], v[40:41], v[104:105]
	s_waitcnt vmcnt(1)
	v_pk_fma_f32 v[62:63], v[62:63], v[110:111], v[116:117] neg_lo:[0,0,1] neg_hi:[0,0,1]
	v_pk_fma_f32 v[60:61], v[60:61], v[108:109], v[118:119] neg_lo:[0,0,1] neg_hi:[0,0,1]
	v_pk_fma_f32 v[54:55], v[54:55], v[110:111], v[120:121]
	v_pk_fma_f32 v[52:53], v[52:53], v[108:109], v[122:123]
	s_waitcnt vmcnt(0)
	v_pk_fma_f32 v[58:59], v[58:59], v[114:115], v[124:125] neg_lo:[0,0,1] neg_hi:[0,0,1]
	v_pk_fma_f32 v[56:57], v[56:57], v[112:113], v[126:127] neg_lo:[0,0,1] neg_hi:[0,0,1]
	v_pk_fma_f32 v[50:51], v[50:51], v[114:115], v[128:129]
	v_pk_fma_f32 v[48:49], v[48:49], v[112:113], v[130:131]
	v_pk_fma_f32 v[46:47], v[46:47], v[110:111], v[132:133] neg_lo:[0,0,1] neg_hi:[0,0,1]
	v_pk_fma_f32 v[44:45], v[44:45], v[108:109], v[134:135] neg_lo:[0,0,1] neg_hi:[0,0,1]
	v_pk_fma_f32 v[38:39], v[38:39], v[110:111], v[84:85]
	v_pk_fma_f32 v[36:37], v[36:37], v[108:109], v[82:83]
	v_pk_fma_f32 v[42:43], v[42:43], v[114:115], v[136:137] neg_lo:[0,0,1] neg_hi:[0,0,1]
	v_pk_fma_f32 v[40:41], v[40:41], v[112:113], v[138:139] neg_lo:[0,0,1] neg_hi:[0,0,1]
	v_pk_fma_f32 v[34:35], v[34:35], v[114:115], v[106:107]
	v_pk_fma_f32 v[32:33], v[32:33], v[112:113], v[104:105]

.LBB0_1614:
	s_ashr_i32 s28, s37, 3
	s_add_i32 s28, s39, s28
	s_ashr_i32 s29, s28, 31
	s_lshr_b32 s29, s29, 26
	s_add_i32 s29, s28, s29
	s_ashr_i32 s38, s29, 6
	s_and_b32 s29, s29, 0xffc0
	s_sub_i32 s28, s28, s29
	s_bfe_i32 s29, s28, 0x80000
	s_bfe_u32 s29, s29, 0x3000c
	s_add_i32 s29, s28, s29
	s_bfe_i32 s37, s29, 0x80000
	s_and_b32 s29, s29, 0xf8
	s_sub_i32 s28, s28, s29
	s_lshl_b32 s38, s38, 3
	s_sext_i32_i8 s28, s28
	s_add_i32 s28, s38, s28
	s_ashr_i32 s29, s28, 31
	s_lshr_b32 s29, s29, 26
	s_add_i32 s29, s28, s29
	s_sext_i32_i16 s37, s37
	s_ashr_i32 s38, s29, 6
	s_andn2_b32 s29, s29, 63
	s_ashr_i32 s37, s37, 3
	s_mulk_i32 s38, 0x42
	s_sub_i32 s28, s28, s29
	s_add_i32 s38, s28, s38
	s_mul_i32 s28, s37, 0x22000
	s_add_i32 s38, s38, 2
	s_ashr_i32 s29, s28, 31
	v_readfirstlane_b32 s39, v91
	v_mad_i64_i32 v[0:1], s[40:41], s38, v90, v[64:65]
	s_lshl_b64 s[28:29], s[28:29], 1
	s_mov_b32 m0, s39
	v_readfirstlane_b32 s39, v92
	v_lshl_add_u64 v[2:3], v[66:67], 0, s[28:29]
	s_waitcnt lgkmcnt(0)
	s_barrier
	global_load_lds_dwordx4 v[0:1], off
	s_mov_b32 m0, s39
	v_readfirstlane_b32 s39, v93
	global_load_lds_dwordx4 v[2:3], off
	v_lshl_add_u64 v[4:5], v[0:1], 0, s[4:5]
	s_mov_b32 m0, s39
	v_readfirstlane_b32 s39, v94
	global_load_lds_dwordx4 v[4:5], off
	v_lshl_add_u64 v[4:5], v[2:3], 0, s[4:5]
	s_mov_b32 m0, s39
	v_readfirstlane_b32 s39, v95
	global_load_lds_dwordx4 v[4:5], off
	v_lshl_add_u64 v[4:5], v[0:1], 0, s[6:7]
	s_mov_b32 m0, s39
	v_readfirstlane_b32 s39, v96
	global_load_lds_dwordx4 v[4:5], off
	v_lshl_add_u64 v[4:5], v[2:3], 0, s[6:7]
	s_mov_b32 m0, s39
	v_readfirstlane_b32 s39, v97
	global_load_lds_dwordx4 v[4:5], off
	v_lshl_add_u64 v[0:1], v[0:1], 0, s[8:9]
	s_mov_b32 m0, s39
	v_readfirstlane_b32 s39, v98
	global_load_lds_dwordx4 v[0:1], off
	v_lshl_add_u64 v[0:1], v[2:3], 0, s[8:9]
	s_mov_b32 m0, s39
	v_mov_b32_e32 v36, 0
	global_load_lds_dwordx4 v[0:1], off
	v_mad_i64_i32 v[72:73], s[40:41], s38, v90, v[68:69]
	v_lshl_add_u64 v[74:75], v[70:71], 0, s[28:29]
	s_mov_b64 s[28:29], 0
	s_mov_b32 s39, 0
	v_mov_b32_e32 v37, v36
	v_mov_b32_e32 v38, v36
	v_mov_b32_e32 v39, v36
	v_mov_b32_e32 v0, v36
	v_mov_b32_e32 v1, v36
	v_mov_b32_e32 v2, v36
	v_mov_b32_e32 v3, v36
	v_mov_b32_e32 v4, v36
	v_mov_b32_e32 v5, v36
	v_mov_b32_e32 v6, v36
	v_mov_b32_e32 v7, v36
	v_mov_b32_e32 v8, v36
	v_mov_b32_e32 v9, v36
	v_mov_b32_e32 v10, v36
	v_mov_b32_e32 v11, v36
	v_mov_b32_e32 v12, v36
	v_mov_b32_e32 v13, v36
	v_mov_b32_e32 v14, v36
	v_mov_b32_e32 v15, v36
	v_mov_b32_e32 v16, v36
	v_mov_b32_e32 v17, v36
	v_mov_b32_e32 v18, v36
	v_mov_b32_e32 v19, v36
	v_mov_b32_e32 v20, v36
	v_mov_b32_e32 v21, v36
	v_mov_b32_e32 v22, v36
	v_mov_b32_e32 v23, v36
	v_mov_b32_e32 v24, v36
	v_mov_b32_e32 v25, v36
	v_mov_b32_e32 v26, v36
	v_mov_b32_e32 v27, v36
	v_mov_b32_e32 v28, v36
	v_mov_b32_e32 v29, v36
	v_mov_b32_e32 v30, v36
	v_mov_b32_e32 v31, v36
	v_mov_b32_e32 v32, v36
	v_mov_b32_e32 v33, v36
	v_mov_b32_e32 v34, v36
	v_mov_b32_e32 v35, v36
	v_mov_b32_e32 v40, v36
	v_mov_b32_e32 v41, v36
	v_mov_b32_e32 v42, v36
	v_mov_b32_e32 v43, v36
	v_mov_b32_e32 v44, v36
	v_mov_b32_e32 v45, v36
	v_mov_b32_e32 v46, v36
	v_mov_b32_e32 v47, v36
	v_mov_b32_e32 v48, v36
	v_mov_b32_e32 v49, v36
	v_mov_b32_e32 v50, v36
	v_mov_b32_e32 v51, v36
	v_mov_b32_e32 v52, v36
	v_mov_b32_e32 v53, v36
	v_mov_b32_e32 v54, v36
	v_mov_b32_e32 v55, v36
	v_mov_b32_e32 v56, v36
	v_mov_b32_e32 v57, v36
	v_mov_b32_e32 v58, v36
	v_mov_b32_e32 v59, v36
	v_mov_b32_e32 v60, v36
	v_mov_b32_e32 v61, v36
	v_mov_b32_e32 v62, v36
	v_mov_b32_e32 v63, v36
	v_readfirstlane_b32 s96, v72
	v_readfirstlane_b32 s97, v73
	v_readfirstlane_b32 s88, v74
	v_readfirstlane_b32 s89, v75
	v_readfirstlane_b32 s87, v82
	s_nop 1
	v_subrev_u32_e32 v244, s96, v72
	v_subrev_u32_e32 v245, s88, v74
	v_add_u32_e32 v246, 0x11000, v244
	v_add_u32_e32 v247, 0x11000, v245
	v_add_u32_e32 v248, 0x22000, v244
	v_add_u32_e32 v249, 0x22000, v245
	v_add_u32_e32 v250, 0x33000, v244
	v_add_u32_e32 v251, 0x33000, v245
	s_add_u32 s96, s96, 0x2200080
	s_addc_u32 s97, s97, 0
	s_add_u32 s88, s88, 0xe100080
	s_addc_u32 s89, s89, 0
	s_add_u32 s86, s87, 0x8000
	s_mov_b32 m0, s86
	s_nop 0
	global_load_lds_dwordx4 v244, s[96:97]
	s_add_u32 m0, s86, 0x4000
	s_nop 0
	global_load_lds_dwordx4 v245, s[88:89]
	s_add_u32 m0, s86, 0x1000
	s_nop 0
	global_load_lds_dwordx4 v246, s[96:97]
	s_add_u32 m0, s86, 0x5000
	s_nop 0
	global_load_lds_dwordx4 v247, s[88:89]
	s_add_u32 m0, s86, 0x2000
	s_nop 0
	global_load_lds_dwordx4 v248, s[96:97]
	s_add_u32 m0, s86, 0x6000
	s_nop 0
	global_load_lds_dwordx4 v249, s[88:89]
	s_add_u32 m0, s86, 0x3000
	s_nop 0
	global_load_lds_dwordx4 v250, s[96:97]
	s_add_u32 m0, s86, 0x7000
	s_nop 0
	global_load_lds_dwordx4 v251, s[88:89]
	s_add_u32 s96, s96, 0x80
	s_addc_u32 s97, s97, 0
	s_add_u32 s88, s88, 0x80
	s_addc_u32 s89, s89, 0
.LBB0_1615:
	s_add_i32 s41, s39, 0x8000
	s_and_b32 s40, s41, 0x8000
	s_add_i32 s40, s40, 0
	s_and_b32 s39, s39, 0x8000
	s_add_i32 s39, s39, 0
	s_add_u32 s86, s39, s87
	s_waitcnt vmcnt(8)
	s_barrier
	v_add3_u32 v145, s39, v84, v85
	v_add3_u32 v178, s39, v85, v86
	v_add3_u32 v179, s39, v84, v87
	v_add3_u32 v180, s39, v86, v87
	ds_read_b128 v[104:107], v178
	ds_read_b128 v[76:79], v145 offset:16384
	ds_read_b128 v[100:103], v145 offset:18432
	ds_read_b128 v[108:111], v178 offset:2048
	ds_read_b128 v[112:115], v145 offset:20480
	ds_read_b128 v[116:119], v145 offset:22528
	ds_read_b128 v[120:123], v145 offset:24576
	ds_read_b128 v[124:127], v145 offset:26624
	ds_read_b128 v[128:131], v145 offset:28672
	ds_read_b128 v[132:135], v145 offset:30720
	ds_read_b128 v[146:149], v180
	ds_read_b128 v[136:139], v179 offset:16384
	ds_read_b128 v[140:143], v179 offset:18432
	ds_read_b128 v[150:153], v180 offset:2048
	ds_read_b128 v[154:157], v179 offset:20480
	ds_read_b128 v[158:161], v179 offset:22528
	ds_read_b128 v[162:165], v179 offset:24576
	ds_read_b128 v[166:169], v179 offset:26624
	ds_read_b128 v[170:173], v179 offset:28672
	ds_read_b128 v[174:177], v179 offset:30720
	s_waitcnt lgkmcnt(0)
	s_barrier
	s_cmpk_eq_i32 s28, 0x700
	s_cbranch_scc1 .Lgskip_1615
	s_mov_b32 m0, s86
	s_nop 0
	global_load_lds_dwordx4 v244, s[96:97]
	s_add_u32 m0, s86, 0x4000
	s_nop 0
	global_load_lds_dwordx4 v245, s[88:89]
	s_add_u32 m0, s86, 0x1000
	s_nop 0
	global_load_lds_dwordx4 v246, s[96:97]
	s_add_u32 m0, s86, 0x5000
	s_nop 0
	global_load_lds_dwordx4 v247, s[88:89]
	s_add_u32 m0, s86, 0x2000
	s_nop 0
	global_load_lds_dwordx4 v248, s[96:97]
	s_add_u32 m0, s86, 0x6000
	s_nop 0
	global_load_lds_dwordx4 v249, s[88:89]
	s_add_u32 m0, s86, 0x3000
	s_nop 0
	global_load_lds_dwordx4 v250, s[96:97]
	s_add_u32 m0, s86, 0x7000
	s_nop 0
	global_load_lds_dwordx4 v251, s[88:89]
	s_add_u32 s96, s96, 0x80
	s_addc_u32 s97, s97, 0
	s_add_u32 s88, s88, 0x80
	s_addc_u32 s89, s89, 0
.Lgskip_1615:
	s_add_u32 s28, s28, 0x80
	s_addc_u32 s29, s29, 0
	s_cmpk_eq_i32 s28, 0x780
	s_mov_b32 s39, s41
	v_mfma_f32_16x16x32_bf16 v[60:63], v[76:79], v[104:107], v[60:63]
	v_mfma_f32_16x16x32_bf16 v[56:59], v[100:103], v[104:107], v[56:59]
	v_mfma_f32_16x16x32_bf16 v[24:27], v[76:79], v[108:111], v[24:27]
	v_mfma_f32_16x16x32_bf16 v[20:23], v[100:103], v[108:111], v[20:23]
	v_mfma_f32_16x16x32_bf16 v[52:55], v[112:115], v[104:107], v[52:55]
	v_mfma_f32_16x16x32_bf16 v[16:19], v[112:115], v[108:111], v[16:19]
	v_mfma_f32_16x16x32_bf16 v[48:51], v[116:119], v[104:107], v[48:51]
	v_mfma_f32_16x16x32_bf16 v[12:15], v[116:119], v[108:111], v[12:15]
	v_mfma_f32_16x16x32_bf16 v[44:47], v[120:123], v[104:107], v[44:47]
	v_mfma_f32_16x16x32_bf16 v[8:11], v[120:123], v[108:111], v[8:11]
	v_mfma_f32_16x16x32_bf16 v[40:43], v[124:127], v[104:107], v[40:43]
	v_mfma_f32_16x16x32_bf16 v[4:7], v[124:127], v[108:111], v[4:7]
	v_mfma_f32_16x16x32_bf16 v[32:35], v[128:131], v[104:107], v[32:35]
	v_mfma_f32_16x16x32_bf16 v[0:3], v[128:131], v[108:111], v[0:3]
	v_mfma_f32_16x16x32_bf16 v[28:31], v[132:135], v[104:107], v[28:31]
	v_mfma_f32_16x16x32_bf16 v[36:39], v[132:135], v[108:111], v[36:39]
	v_mfma_f32_16x16x32_bf16 v[60:63], v[136:139], v[146:149], v[60:63]
	v_mfma_f32_16x16x32_bf16 v[56:59], v[140:143], v[146:149], v[56:59]
	v_mfma_f32_16x16x32_bf16 v[24:27], v[136:139], v[150:153], v[24:27]
	v_mfma_f32_16x16x32_bf16 v[20:23], v[140:143], v[150:153], v[20:23]
	v_mfma_f32_16x16x32_bf16 v[52:55], v[154:157], v[146:149], v[52:55]
	v_mfma_f32_16x16x32_bf16 v[16:19], v[154:157], v[150:153], v[16:19]
	v_mfma_f32_16x16x32_bf16 v[48:51], v[158:161], v[146:149], v[48:51]
	v_mfma_f32_16x16x32_bf16 v[12:15], v[158:161], v[150:153], v[12:15]
	v_mfma_f32_16x16x32_bf16 v[44:47], v[162:165], v[146:149], v[44:47]
	v_mfma_f32_16x16x32_bf16 v[8:11], v[162:165], v[150:153], v[8:11]
	v_mfma_f32_16x16x32_bf16 v[40:43], v[166:169], v[146:149], v[40:43]
	v_mfma_f32_16x16x32_bf16 v[4:7], v[166:169], v[150:153], v[4:7]
	v_mfma_f32_16x16x32_bf16 v[32:35], v[170:173], v[146:149], v[32:35]
	v_mfma_f32_16x16x32_bf16 v[0:3], v[170:173], v[150:153], v[0:3]
	v_mfma_f32_16x16x32_bf16 v[28:31], v[174:177], v[146:149], v[28:31]
	v_mfma_f32_16x16x32_bf16 v[36:39], v[174:177], v[150:153], v[36:39]
	s_cbranch_scc0 .LBB0_1615
	v_add_u32_e32 v80, s40, v84
	v_add_u32_e32 v81, v80, v85
	s_waitcnt vmcnt(0)
	s_barrier
	ds_read_b128 v[72:75], v81 offset:16384
	v_add3_u32 v99, s40, v85, v86
	ds_read_b128 v[76:79], v81 offset:18432
	ds_read_b128 v[100:103], v99
	ds_read_b128 v[104:107], v99 offset:2048
	ds_read_b128 v[108:111], v81 offset:20480
	ds_read_b128 v[112:115], v81 offset:22528
	ds_read_b128 v[116:119], v81 offset:24576
	ds_read_b128 v[120:123], v81 offset:26624
	ds_read_b128 v[124:127], v81 offset:28672
	ds_read_b128 v[128:131], v81 offset:30720
	v_add_u32_e32 v80, v80, v87
	s_waitcnt lgkmcnt(7)
	v_mfma_f32_16x16x32_bf16 v[60:63], v[72:75], v[100:103], v[60:63]
	s_lshl_b32 s38, s38, 7
	v_mfma_f32_16x16x32_bf16 v[56:59], v[76:79], v[100:103], v[56:59]
	s_waitcnt lgkmcnt(4)
	v_mfma_f32_16x16x32_bf16 v[48:51], v[112:115], v[100:103], v[48:51]
	s_waitcnt lgkmcnt(3)
	v_mfma_f32_16x16x32_bf16 v[44:47], v[116:119], v[100:103], v[44:47]
	s_waitcnt lgkmcnt(2)
	v_mfma_f32_16x16x32_bf16 v[40:43], v[120:123], v[100:103], v[40:43]
	s_waitcnt lgkmcnt(1)
	v_mfma_f32_16x16x32_bf16 v[32:35], v[124:127], v[100:103], v[32:35]
	s_waitcnt lgkmcnt(0)
	v_mfma_f32_16x16x32_bf16 v[28:31], v[128:131], v[100:103], v[28:31]
	v_mfma_f32_16x16x32_bf16 v[24:27], v[72:75], v[104:107], v[24:27]
	ds_read_b128 v[72:75], v80 offset:16384
	v_mfma_f32_16x16x32_bf16 v[52:55], v[108:111], v[100:103], v[52:55]
	v_mfma_f32_16x16x32_bf16 v[20:23], v[76:79], v[104:107], v[20:23]
	v_mfma_f32_16x16x32_bf16 v[16:19], v[108:111], v[104:107], v[16:19]
	v_mfma_f32_16x16x32_bf16 v[12:15], v[112:115], v[104:107], v[12:15]
	v_mfma_f32_16x16x32_bf16 v[8:11], v[116:119], v[104:107], v[8:11]
	v_mfma_f32_16x16x32_bf16 v[4:7], v[120:123], v[104:107], v[4:7]
	v_mfma_f32_16x16x32_bf16 v[0:3], v[124:127], v[104:107], v[0:3]
	v_mfma_f32_16x16x32_bf16 v[100:103], v[128:131], v[104:107], v[36:39]
	s_nop 2
	v_add3_u32 v36, s40, v87, v86
	ds_read_b128 v[76:79], v80 offset:18432
	ds_read_b128 v[104:107], v36
	ds_read_b128 v[108:111], v36 offset:2048
	ds_read_b128 v[128:131], v80 offset:28672
	ds_read_b128 v[132:135], v80 offset:30720
	ds_read_b128 v[112:115], v80 offset:20480
	ds_read_b128 v[116:119], v80 offset:22528
	ds_read_b128 v[120:123], v80 offset:24576
	ds_read_b128 v[124:127], v80 offset:26624
	s_waitcnt lgkmcnt(7)
	v_mfma_f32_16x16x32_bf16 v[60:63], v[72:75], v[104:107], v[60:63]
	s_waitcnt lgkmcnt(5)
	v_mfma_f32_16x16x32_bf16 v[36:39], v[128:131], v[104:107], v[32:35]
	s_waitcnt lgkmcnt(4)
	v_mfma_f32_16x16x32_bf16 v[32:35], v[132:135], v[104:107], v[28:31]
	v_mfma_f32_16x16x32_bf16 v[28:31], v[72:75], v[108:111], v[24:27]
	v_add_u32_e32 v72, s38, v83
	v_mul_hi_i32 v73, v72, s31
	v_mfma_f32_16x16x32_bf16 v[24:27], v[76:79], v[108:111], v[20:23]
	s_waitcnt lgkmcnt(3)
	v_mfma_f32_16x16x32_bf16 v[20:23], v[112:115], v[108:111], v[16:19]
	s_waitcnt lgkmcnt(2)
	v_mfma_f32_16x16x32_bf16 v[16:19], v[116:119], v[108:111], v[12:15]
	s_waitcnt lgkmcnt(1)
	v_mfma_f32_16x16x32_bf16 v[12:15], v[120:123], v[108:111], v[8:11]
	s_waitcnt lgkmcnt(0)
	v_mfma_f32_16x16x32_bf16 v[8:11], v[124:127], v[108:111], v[4:7]
	s_nop 2
	v_lshrrev_b32_e32 v4, 31, v73
	v_ashrrev_i32_e32 v5, 11, v73
	v_mfma_f32_16x16x32_bf16 v[56:59], v[76:79], v[104:107], v[56:59]
	v_add_u32_e32 v73, v5, v4
	v_mad_i32_i24 v78, v73, s33, v72
	v_lshlrev_b32_e32 v75, 13, v73
	v_mfma_f32_16x16x32_bf16 v[52:55], v[112:115], v[104:107], v[52:55]
	v_cmp_lt_i32_e32 vcc, s34, v78
	v_add3_u32 v74, v75, v78, s35
	v_mfma_f32_16x16x32_bf16 v[48:51], v[116:119], v[104:107], v[48:51]
	v_mfma_f32_16x16x32_bf16 v[44:47], v[120:123], v[104:107], v[44:47]
	v_mfma_f32_16x16x32_bf16 v[40:43], v[124:127], v[104:107], v[40:43]
	v_mfma_f32_16x16x32_bf16 v[4:7], v[128:131], v[108:111], v[0:3]
	v_mfma_f32_16x16x32_bf16 v[0:3], v[132:135], v[108:111], v[100:103]
	s_and_saveexec_b64 s[28:29], vcc
	s_xor_b64 s[28:29], exec, s[28:29]
	v_add3_u32 v72, v75, v78, s35
	s_or_saveexec_b64 s[28:29], s[28:29]
	v_mov_b64_e32 v[76:77], s[92:93]
	v_lshl_add_u32 v75, v73, 8, v78
	s_xor_b64 exec, exec, s[28:29]
	v_lshl_add_u32 v72, v73, 8, v78
	v_mov_b64_e32 v[76:77], s[2:3]
	s_or_b64 exec, exec, s[28:29]
	s_and_saveexec_b64 s[28:29], vcc
	s_xor_b64 s[28:29], exec, s[28:29]
	s_cbranch_execz .LBB0_1622
	v_add_u32_e32 v73, 3, v73
	v_mul_hi_i32_i24_e32 v79, 0x6000, v73
	v_mul_i32_i24_e32 v78, 0x6000, v73
	s_or_saveexec_b64 s[28:29], s[28:29]
	v_mov_b64_e32 v[80:81], s[92:93]
	s_xor_b64 exec, exec, s[28:29]
	s_cbranch_execnz .LBB0_1623
	s_branch .LBB0_1624

.LBB0_1758:
	s_ashr_i32 s26, s31, 3
	s_add_i32 s26, s34, s26
	s_ashr_i32 s27, s26, 31
	s_lshr_b32 s27, s27, 24
	s_add_i32 s27, s26, s27
	s_ashr_i32 s33, s27, 8
	s_and_b32 s27, s27, 0xff00
	s_sub_i32 s26, s26, s27
	s_sext_i32_i16 s27, s26
	s_bfe_u32 s27, s27, 0x3001c
	s_add_i32 s27, s26, s27
	s_sext_i32_i16 s31, s27
	s_and_b32 s27, s27, 0xfff8
	s_sub_i32 s26, s26, s27
	s_lshl_b32 s33, s33, 3
	s_sext_i32_i16 s26, s26
	s_add_i32 s26, s33, s26
	s_ashr_i32 s27, s26, 31
	s_lshr_b32 s27, s27, 26
	s_add_i32 s27, s26, s27
	s_ashr_i32 s33, s27, 6
	s_andn2_b32 s27, s27, 63
	s_mulk_i32 s33, 0x42
	s_sub_i32 s26, s26, s27
	s_add_i32 s33, s26, s33
	s_ashr_i32 s31, s31, 3
	s_add_i32 s33, s33, 2
	s_mul_i32 s26, s31, 0x22000
	v_mad_i64_i32 v[0:1], s[34:35], s33, v85, v[66:67]
	s_ashr_i32 s27, s26, 31
	v_readfirstlane_b32 s34, v86
	s_lshl_b64 s[26:27], s[26:27], 1
	s_mov_b32 m0, s34
	v_readfirstlane_b32 s34, v87
	v_lshl_add_u64 v[2:3], v[68:69], 0, s[26:27]
	s_waitcnt lgkmcnt(0)
	s_barrier
	global_load_lds_dwordx4 v[0:1], off
	s_mov_b32 m0, s34
	v_readfirstlane_b32 s34, v88
	global_load_lds_dwordx4 v[2:3], off
	v_lshl_add_u64 v[4:5], v[0:1], 0, s[4:5]
	s_mov_b32 m0, s34
	v_readfirstlane_b32 s34, v89
	global_load_lds_dwordx4 v[4:5], off
	v_lshl_add_u64 v[4:5], v[2:3], 0, s[4:5]
	s_mov_b32 m0, s34
	v_readfirstlane_b32 s34, v90
	global_load_lds_dwordx4 v[4:5], off
	v_lshl_add_u64 v[4:5], v[0:1], 0, s[6:7]
	s_mov_b32 m0, s34
	v_readfirstlane_b32 s34, v91
	global_load_lds_dwordx4 v[4:5], off
	v_lshl_add_u64 v[4:5], v[2:3], 0, s[6:7]
	s_mov_b32 m0, s34
	v_readfirstlane_b32 s34, v92
	global_load_lds_dwordx4 v[4:5], off
	v_lshl_add_u64 v[0:1], v[0:1], 0, s[8:9]
	s_mov_b32 m0, s34
	v_readfirstlane_b32 s34, v93
	global_load_lds_dwordx4 v[0:1], off
	v_lshl_add_u64 v[0:1], v[2:3], 0, s[8:9]
	s_mov_b32 m0, s34
	v_mad_i64_i32 v[74:75], s[34:35], s33, v85, v[70:71]
	global_load_lds_dwordx4 v[0:1], off
	v_mov_b32_e32 v16, 0
	v_lshl_add_u64 v[76:77], v[72:73], 0, s[26:27]
	s_mov_b64 s[26:27], 0
	s_mov_b32 s34, 0
	v_mov_b32_e32 v17, v16
	v_mov_b32_e32 v18, v16
	v_mov_b32_e32 v19, v16
	v_mov_b32_e32 v0, v16
	v_mov_b32_e32 v1, v16
	v_mov_b32_e32 v2, v16
	v_mov_b32_e32 v3, v16
	v_mov_b32_e32 v4, v16
	v_mov_b32_e32 v5, v16
	v_mov_b32_e32 v6, v16
	v_mov_b32_e32 v7, v16
	v_mov_b32_e32 v8, v16
	v_mov_b32_e32 v9, v16
	v_mov_b32_e32 v10, v16
	v_mov_b32_e32 v11, v16
	v_mov_b32_e32 v12, v16
	v_mov_b32_e32 v13, v16
	v_mov_b32_e32 v14, v16
	v_mov_b32_e32 v15, v16
	v_mov_b32_e32 v20, v16
	v_mov_b32_e32 v21, v16
	v_mov_b32_e32 v22, v16
	v_mov_b32_e32 v23, v16
	v_mov_b32_e32 v24, v16
	v_mov_b32_e32 v25, v16
	v_mov_b32_e32 v26, v16
	v_mov_b32_e32 v27, v16
	v_mov_b32_e32 v28, v16
	v_mov_b32_e32 v29, v16
	v_mov_b32_e32 v30, v16
	v_mov_b32_e32 v31, v16
	v_mov_b32_e32 v32, v16
	v_mov_b32_e32 v33, v16
	v_mov_b32_e32 v34, v16
	v_mov_b32_e32 v35, v16
	v_mov_b32_e32 v36, v16
	v_mov_b32_e32 v37, v16
	v_mov_b32_e32 v38, v16
	v_mov_b32_e32 v39, v16
	v_mov_b32_e32 v40, v16
	v_mov_b32_e32 v41, v16
	v_mov_b32_e32 v42, v16
	v_mov_b32_e32 v43, v16
	v_mov_b32_e32 v44, v16
	v_mov_b32_e32 v45, v16
	v_mov_b32_e32 v46, v16
	v_mov_b32_e32 v47, v16
	v_mov_b32_e32 v48, v16
	v_mov_b32_e32 v49, v16
	v_mov_b32_e32 v50, v16
	v_mov_b32_e32 v51, v16
	v_mov_b32_e32 v52, v16
	v_mov_b32_e32 v53, v16
	v_mov_b32_e32 v54, v16
	v_mov_b32_e32 v55, v16
	v_mov_b32_e32 v56, v16
	v_mov_b32_e32 v57, v16
	v_mov_b32_e32 v58, v16
	v_mov_b32_e32 v59, v16
	v_mov_b32_e32 v60, v16
	v_mov_b32_e32 v61, v16
	v_mov_b32_e32 v62, v16
	v_mov_b32_e32 v63, v16
	v_readfirstlane_b32 s96, v74
	v_readfirstlane_b32 s97, v75
	v_readfirstlane_b32 s88, v76
	v_readfirstlane_b32 s89, v77
	v_readfirstlane_b32 s87, v78
	s_nop 1
	v_subrev_u32_e32 v244, s96, v74
	v_subrev_u32_e32 v245, s88, v76
	v_add_u32_e32 v246, 0x11000, v244
	v_add_u32_e32 v247, 0x11000, v245
	v_add_u32_e32 v248, 0x22000, v244
	v_add_u32_e32 v249, 0x22000, v245
	v_add_u32_e32 v250, 0x33000, v244
	v_add_u32_e32 v251, 0x33000, v245
	s_add_u32 s96, s96, 0x2200080
	s_addc_u32 s97, s97, 0
	s_add_u32 s88, s88, 0xe320080
	s_addc_u32 s89, s89, 0
	s_add_u32 s86, s87, 0x8000
	s_mov_b32 m0, s86
	s_nop 0
	global_load_lds_dwordx4 v244, s[96:97]
	s_add_u32 m0, s86, 0x4000
	s_nop 0
	global_load_lds_dwordx4 v245, s[88:89]
	s_add_u32 m0, s86, 0x1000
	s_nop 0
	global_load_lds_dwordx4 v246, s[96:97]
	s_add_u32 m0, s86, 0x5000
	s_nop 0
	global_load_lds_dwordx4 v247, s[88:89]
	s_add_u32 m0, s86, 0x2000
	s_nop 0
	global_load_lds_dwordx4 v248, s[96:97]
	s_add_u32 m0, s86, 0x6000
	s_nop 0
	global_load_lds_dwordx4 v249, s[88:89]
	s_add_u32 m0, s86, 0x3000
	s_nop 0
	global_load_lds_dwordx4 v250, s[96:97]
	s_add_u32 m0, s86, 0x7000
	s_nop 0
	global_load_lds_dwordx4 v251, s[88:89]
	s_add_u32 s96, s96, 0x80
	s_addc_u32 s97, s97, 0
	s_add_u32 s88, s88, 0x80
	s_addc_u32 s89, s89, 0
.LBB0_1759:
	s_add_i32 s36, s34, 0x8000
	s_and_b32 s35, s36, 0x8000
	s_add_i32 s35, s35, 0
	s_and_b32 s34, s34, 0x8000
	s_add_i32 s34, s34, 0
	s_add_u32 s86, s34, s87
	s_waitcnt vmcnt(8)
	s_barrier
	v_add3_u32 v143, s34, v80, v81
	v_add3_u32 v145, s34, v81, v82
	v_add3_u32 v206, s34, v80, v83
	v_add3_u32 v207, s34, v82, v83
	ds_read_b128 v[102:105], v145
	ds_read_b128 v[94:97], v143 offset:16384
	ds_read_b128 v[98:101], v143 offset:18432
	ds_read_b128 v[106:109], v145 offset:2048
	ds_read_b128 v[110:113], v143 offset:20480
	ds_read_b128 v[114:117], v143 offset:22528
	ds_read_b128 v[118:121], v143 offset:24576
	ds_read_b128 v[122:125], v143 offset:26624
	ds_read_b128 v[126:129], v143 offset:28672
	ds_read_b128 v[130:133], v143 offset:30720
	ds_read_b128 v[174:177], v207
	ds_read_b128 v[166:169], v206 offset:16384
	ds_read_b128 v[170:173], v206 offset:18432
	ds_read_b128 v[178:181], v207 offset:2048
	ds_read_b128 v[182:185], v206 offset:20480
	ds_read_b128 v[186:189], v206 offset:22528
	ds_read_b128 v[190:193], v206 offset:24576
	ds_read_b128 v[194:197], v206 offset:26624
	ds_read_b128 v[198:201], v206 offset:28672
	ds_read_b128 v[202:205], v206 offset:30720
	s_waitcnt lgkmcnt(0)
	s_barrier
	s_cmpk_eq_i32 s26, 0x700
	s_cbranch_scc1 .Lgskip_1759
	s_mov_b32 m0, s86
	s_nop 0
	global_load_lds_dwordx4 v244, s[96:97]
	s_add_u32 m0, s86, 0x4000
	s_nop 0
	global_load_lds_dwordx4 v245, s[88:89]
	s_add_u32 m0, s86, 0x1000
	s_nop 0
	global_load_lds_dwordx4 v246, s[96:97]
	s_add_u32 m0, s86, 0x5000
	s_nop 0
	global_load_lds_dwordx4 v247, s[88:89]
	s_add_u32 m0, s86, 0x2000
	s_nop 0
	global_load_lds_dwordx4 v248, s[96:97]
	s_add_u32 m0, s86, 0x6000
	s_nop 0
	global_load_lds_dwordx4 v249, s[88:89]
	s_add_u32 m0, s86, 0x3000
	s_nop 0
	global_load_lds_dwordx4 v250, s[96:97]
	s_add_u32 m0, s86, 0x7000
	s_nop 0
	global_load_lds_dwordx4 v251, s[88:89]
	s_add_u32 s96, s96, 0x80
	s_addc_u32 s97, s97, 0
	s_add_u32 s88, s88, 0x80
	s_addc_u32 s89, s89, 0
.Lgskip_1759:
	s_add_u32 s26, s26, 0x80
	s_addc_u32 s27, s27, 0
	s_cmpk_eq_i32 s26, 0x780
	s_mov_b32 s34, s36
	v_mfma_f32_16x16x32_bf16 v[60:63], v[94:97], v[102:105], v[60:63]
	v_mfma_f32_16x16x32_bf16 v[56:59], v[98:101], v[102:105], v[56:59]
	v_mfma_f32_16x16x32_bf16 v[28:31], v[94:97], v[106:109], v[28:31]
	v_mfma_f32_16x16x32_bf16 v[24:27], v[98:101], v[106:109], v[24:27]
	v_mfma_f32_16x16x32_bf16 v[52:55], v[110:113], v[102:105], v[52:55]
	v_mfma_f32_16x16x32_bf16 v[20:23], v[110:113], v[106:109], v[20:23]
	v_mfma_f32_16x16x32_bf16 v[48:51], v[114:117], v[102:105], v[48:51]
	v_mfma_f32_16x16x32_bf16 v[12:15], v[114:117], v[106:109], v[12:15]
	v_mfma_f32_16x16x32_bf16 v[44:47], v[118:121], v[102:105], v[44:47]
	v_mfma_f32_16x16x32_bf16 v[8:11], v[118:121], v[106:109], v[8:11]
	v_mfma_f32_16x16x32_bf16 v[40:43], v[122:125], v[102:105], v[40:43]
	v_mfma_f32_16x16x32_bf16 v[4:7], v[122:125], v[106:109], v[4:7]
	v_mfma_f32_16x16x32_bf16 v[36:39], v[126:129], v[102:105], v[36:39]
	v_mfma_f32_16x16x32_bf16 v[0:3], v[126:129], v[106:109], v[0:3]
	v_mfma_f32_16x16x32_bf16 v[32:35], v[130:133], v[102:105], v[32:35]
	v_mfma_f32_16x16x32_bf16 v[16:19], v[130:133], v[106:109], v[16:19]
	v_mfma_f32_16x16x32_bf16 v[60:63], v[166:169], v[174:177], v[60:63]
	v_mfma_f32_16x16x32_bf16 v[56:59], v[170:173], v[174:177], v[56:59]
	v_mfma_f32_16x16x32_bf16 v[28:31], v[166:169], v[178:181], v[28:31]
	v_mfma_f32_16x16x32_bf16 v[24:27], v[170:173], v[178:181], v[24:27]
	v_mfma_f32_16x16x32_bf16 v[52:55], v[182:185], v[174:177], v[52:55]
	v_mfma_f32_16x16x32_bf16 v[20:23], v[182:185], v[178:181], v[20:23]
	v_mfma_f32_16x16x32_bf16 v[48:51], v[186:189], v[174:177], v[48:51]
	v_mfma_f32_16x16x32_bf16 v[12:15], v[186:189], v[178:181], v[12:15]
	v_mfma_f32_16x16x32_bf16 v[44:47], v[190:193], v[174:177], v[44:47]
	v_mfma_f32_16x16x32_bf16 v[8:11], v[190:193], v[178:181], v[8:11]
	v_mfma_f32_16x16x32_bf16 v[40:43], v[194:197], v[174:177], v[40:43]
	v_mfma_f32_16x16x32_bf16 v[4:7], v[194:197], v[178:181], v[4:7]
	v_mfma_f32_16x16x32_bf16 v[36:39], v[198:201], v[174:177], v[36:39]
	v_mfma_f32_16x16x32_bf16 v[0:3], v[198:201], v[178:181], v[0:3]
	v_mfma_f32_16x16x32_bf16 v[32:35], v[202:205], v[174:177], v[32:35]
	v_mfma_f32_16x16x32_bf16 v[16:19], v[202:205], v[178:181], v[16:19]
	s_cbranch_scc0 .LBB0_1759
	v_add_u32_e32 v138, s35, v80
	v_add_u32_e32 v126, v138, v81
	s_waitcnt vmcnt(0)
	s_barrier
	ds_read_b128 v[74:77], v126 offset:16384
	v_add3_u32 v102, s35, v81, v82
	ds_read_b128 v[94:97], v102
	ds_read_b128 v[98:101], v126 offset:18432
	ds_read_b128 v[102:105], v102 offset:2048
	ds_read_b128 v[106:109], v126 offset:20480
	ds_read_b128 v[110:113], v126 offset:22528
	ds_read_b128 v[114:117], v126 offset:24576
	ds_read_b128 v[118:121], v126 offset:26624
	v_add3_u32 v134, s35, v83, v82
	v_add_u32_e32 v142, v138, v83
	ds_read_b128 v[122:125], v126 offset:28672
	ds_read_b128 v[126:129], v126 offset:30720
	ds_read_b128 v[130:133], v134
	ds_read_b128 v[134:137], v134 offset:2048
	ds_read_b128 v[138:141], v142 offset:16384
	ds_read_b128 v[146:149], v142 offset:18432
	s_waitcnt lgkmcnt(11)
	v_mfma_f32_16x16x32_bf16 v[56:59], v[98:101], v[94:97], v[56:59]
	s_lshl_b32 s33, s33, 7
	s_lshl_b32 s26, s31, 7
	s_ashr_i32 s27, s26, 31
	v_mfma_f32_16x16x32_bf16 v[60:63], v[74:77], v[94:97], v[60:63]
	s_lshl_b64 s[26:27], s[26:27], 1
	s_add_i32 s30, s30, s28
	s_cmpk_gt_i32 s30, 0xfff
	s_waitcnt lgkmcnt(0)
	v_mfma_f32_16x16x32_bf16 v[56:59], v[146:149], v[130:133], v[56:59]
	v_mfma_f32_16x16x32_bf16 v[48:51], v[110:113], v[94:97], v[48:51]
	v_mfma_f32_16x16x32_bf16 v[52:55], v[106:109], v[94:97], v[52:55]
	s_nop 5
	v_max_f32_e32 v56, v56, v56
	v_max_f32_e32 v57, v57, v57
	v_max_f32_e32 v56, 0, v56
	v_mfma_f32_16x16x32_bf16 v[44:47], v[114:117], v[94:97], v[44:47]
	v_max_f32_e32 v57, 0, v57
	v_max_f32_e32 v59, v59, v59
	v_max_f32_e32 v59, 0, v59
	v_mfma_f32_16x16x32_bf16 v[40:43], v[118:121], v[94:97], v[40:43]
	v_mfma_f32_16x16x32_bf16 v[36:39], v[122:125], v[94:97], v[36:39]
	v_mfma_f32_16x16x32_bf16 v[32:35], v[126:129], v[94:97], v[32:35]
	ds_read_b128 v[94:97], v142 offset:20480
	ds_read_b128 v[150:153], v142 offset:22528
	ds_read_b128 v[154:157], v142 offset:24576
	ds_read_b128 v[158:161], v142 offset:26624
	v_mfma_f32_16x16x32_bf16 v[60:63], v[138:141], v[130:133], v[60:63]
	s_waitcnt lgkmcnt(2)
	v_mfma_f32_16x16x32_bf16 v[48:51], v[150:153], v[130:133], v[48:51]
	v_mfma_f32_16x16x32_bf16 v[20:23], v[106:109], v[102:105], v[20:23]
	v_mul_f32_e64 v106, v56, v56
	v_mul_f32_e64 v107, v57, v57
	v_max_f32_e32 v57, v58, v58
	s_nop 1
	v_max_f32_e32 v60, v60, v60
	v_mfma_f32_16x16x32_bf16 v[24:27], v[98:101], v[102:105], v[24:27]
	v_add_u32_e32 v100, s33, v79
	v_mov_b64_e32 v[98:99], s[0:1]
	v_max_f32_e32 v61, v61, v61
	v_max_f32_e32 v56, v62, v62
	v_max_f32_e32 v58, 0, v57
	v_max_f32_e32 v57, v63, v63
	v_mad_i64_i32 v[100:101], s[34:35], v100, s29, v[98:99]
	v_max_f32_e32 v60, 0, v60
	v_max_f32_e32 v61, 0, v61
	v_max_f32_e32 v56, 0, v56
	v_max_f32_e32 v57, 0, v57
	v_mfma_f32_16x16x32_bf16 v[52:55], v[94:97], v[130:133], v[52:55]
	v_lshl_add_u64 v[100:101], v[100:101], 0, s[26:27]
	v_pk_mul_f32 v[60:61], v[60:61], v[60:61]
	v_pk_mul_f32 v[62:63], v[56:57], v[56:57]
	v_mfma_f32_16x16x32_bf16 v[28:31], v[74:77], v[102:105], v[28:31]
	v_max_f32_e32 v48, v48, v48
	v_max_f32_e32 v49, v49, v49
	ds_read_b128 v[74:77], v142 offset:28672
	ds_read_b128 v[162:165], v142 offset:30720
	v_mfma_f32_16x16x32_bf16 v[12:15], v[110:113], v[102:105], v[12:15]
	v_lshl_add_u64 v[100:101], v[100:101], 0, v[64:65]
	v_cvt_pk_bf16_f32 v56, v60, v61
	v_cvt_pk_bf16_f32 v57, v62, v63
	v_mfma_f32_16x16x32_bf16 v[8:11], v[114:117], v[102:105], v[8:11]
	v_max_f32_e32 v48, 0, v48
	v_max_f32_e32 v49, 0, v49
	v_max_f32_e32 v52, v52, v52
	v_mfma_f32_16x16x32_bf16 v[4:7], v[118:121], v[102:105], v[4:7]
	v_max_f32_e32 v53, v53, v53
	v_max_f32_e32 v51, v51, v51
	v_max_f32_e32 v52, 0, v52
	v_mfma_f32_16x16x32_bf16 v[0:3], v[122:125], v[102:105], v[0:3]
	v_max_f32_e32 v53, 0, v53
	v_max_f32_e32 v51, 0, v51
	v_pk_mul_f32 v[52:53], v[52:53], v[52:53]
	v_mfma_f32_16x16x32_bf16 v[16:19], v[126:129], v[102:105], v[16:19]
	v_mul_f32_e64 v102, v58, v58
	v_mul_f32_e64 v103, v59, v59
	v_cvt_pk_bf16_f32 v58, v106, v107
	v_cvt_pk_bf16_f32 v59, v102, v103
	s_waitcnt lgkmcnt(2)
	v_mfma_f32_16x16x32_bf16 v[40:43], v[158:161], v[130:133], v[40:43]
	global_store_dwordx4 v[100:101], v[56:59], off
	s_nop 1
	v_pk_mul_f32 v[56:57], v[48:49], v[48:49]
	v_max_f32_e32 v49, v50, v50
	v_max_f32_e32 v48, v54, v54
	v_max_f32_e32 v50, 0, v49
	v_max_f32_e32 v49, v55, v55
	v_mfma_f32_16x16x32_bf16 v[44:47], v[154:157], v[130:133], v[44:47]
	v_max_f32_e32 v48, 0, v48
	v_max_f32_e32 v49, 0, v49
	v_pk_mul_f32 v[54:55], v[48:49], v[48:49]
	v_pk_mul_f32 v[58:59], v[50:51], v[50:51]
	v_max_f32_e32 v40, v40, v40
	v_max_f32_e32 v41, v41, v41
	s_waitcnt lgkmcnt(0)
	v_mfma_f32_16x16x32_bf16 v[32:35], v[162:165], v[130:133], v[32:35]
	v_cvt_pk_bf16_f32 v48, v52, v53
	v_cvt_pk_bf16_f32 v49, v54, v55
	v_cvt_pk_bf16_f32 v50, v56, v57
	v_cvt_pk_bf16_f32 v51, v58, v59
	v_max_f32_e32 v40, 0, v40
	v_max_f32_e32 v41, 0, v41
	global_store_dwordx4 v[100:101], v[48:51], off offset:64
	v_max_f32_e32 v44, v44, v44
	v_max_f32_e32 v45, v45, v45
	v_pk_mul_f32 v[48:49], v[40:41], v[40:41]
	v_max_f32_e32 v41, v42, v42
	v_max_f32_e32 v40, v46, v46
	v_max_f32_e32 v42, 0, v41
	v_max_f32_e32 v41, v47, v47
	v_max_f32_e32 v43, v43, v43
	v_mfma_f32_16x16x32_bf16 v[36:39], v[74:77], v[130:133], v[36:39]
	v_max_f32_e32 v44, 0, v44
	v_max_f32_e32 v45, 0, v45
	v_max_f32_e32 v40, 0, v40
	v_max_f32_e32 v41, 0, v41
	v_max_f32_e32 v43, 0, v43
	v_pk_mul_f32 v[44:45], v[44:45], v[44:45]
	v_pk_mul_f32 v[46:47], v[40:41], v[40:41]
	v_pk_mul_f32 v[50:51], v[42:43], v[42:43]
	v_max_f32_e32 v32, v32, v32
	v_max_f32_e32 v33, v33, v33
	v_mfma_f32_16x16x32_bf16 v[24:27], v[146:149], v[134:137], v[24:27]
	v_cvt_pk_bf16_f32 v40, v44, v45
	v_cvt_pk_bf16_f32 v41, v46, v47
	v_cvt_pk_bf16_f32 v42, v48, v49
	v_cvt_pk_bf16_f32 v43, v50, v51
	v_max_f32_e32 v32, 0, v32
	v_max_f32_e32 v33, 0, v33
	global_store_dwordx4 v[100:101], v[40:43], off offset:128
	v_max_f32_e32 v36, v36, v36
	v_max_f32_e32 v37, v37, v37
	v_pk_mul_f32 v[40:41], v[32:33], v[32:33]
	v_max_f32_e32 v33, v34, v34
	v_max_f32_e32 v32, v38, v38
	v_max_f32_e32 v34, 0, v33
	v_max_f32_e32 v33, v39, v39
	v_max_f32_e32 v35, v35, v35
	v_mfma_f32_16x16x32_bf16 v[28:31], v[138:141], v[134:137], v[28:31]
	v_max_f32_e32 v36, 0, v36
	v_max_f32_e32 v37, 0, v37
	v_max_f32_e32 v32, 0, v32
	v_max_f32_e32 v33, 0, v33
	v_max_f32_e32 v35, 0, v35
	v_pk_mul_f32 v[36:37], v[36:37], v[36:37]
	v_pk_mul_f32 v[38:39], v[32:33], v[32:33]
	v_pk_mul_f32 v[42:43], v[34:35], v[34:35]
	v_max_f32_e32 v24, v24, v24
	v_max_f32_e32 v25, v25, v25
	v_mfma_f32_16x16x32_bf16 v[12:15], v[150:153], v[134:137], v[12:15]
	v_cvt_pk_bf16_f32 v32, v36, v37
	v_cvt_pk_bf16_f32 v33, v38, v39
	v_cvt_pk_bf16_f32 v34, v40, v41
	v_cvt_pk_bf16_f32 v35, v42, v43
	v_max_f32_e32 v24, 0, v24
	v_max_f32_e32 v25, 0, v25
	global_store_dwordx4 v[100:101], v[32:35], off offset:192
	v_max_f32_e32 v28, v28, v28
	v_max_f32_e32 v29, v29, v29
	v_pk_mul_f32 v[34:35], v[24:25], v[24:25]
	v_max_f32_e32 v25, v26, v26
	v_add_u32_e32 v32, s33, v84
	v_max_f32_e32 v24, v30, v30
	v_max_f32_e32 v26, 0, v25
	v_max_f32_e32 v25, v31, v31
	v_max_f32_e32 v27, v27, v27
	v_mfma_f32_16x16x32_bf16 v[20:23], v[94:97], v[134:137], v[20:23]
	v_mad_i64_i32 v[32:33], s[34:35], v32, s29, v[98:99]
	v_max_f32_e32 v28, 0, v28
	v_max_f32_e32 v29, 0, v29
	v_max_f32_e32 v24, 0, v24
	v_max_f32_e32 v25, 0, v25
	v_max_f32_e32 v27, 0, v27
	v_lshl_add_u64 v[32:33], v[32:33], 0, s[26:27]
	v_pk_mul_f32 v[28:29], v[28:29], v[28:29]
	v_pk_mul_f32 v[30:31], v[24:25], v[24:25]
	v_pk_mul_f32 v[36:37], v[26:27], v[26:27]
	v_max_f32_e32 v12, v12, v12
	v_max_f32_e32 v13, v13, v13
	v_mfma_f32_16x16x32_bf16 v[4:7], v[158:161], v[134:137], v[4:7]
	v_lshl_add_u64 v[32:33], v[32:33], 0, v[64:65]
	v_cvt_pk_bf16_f32 v24, v28, v29
	v_cvt_pk_bf16_f32 v25, v30, v31
	v_cvt_pk_bf16_f32 v26, v34, v35
	v_cvt_pk_bf16_f32 v27, v36, v37
	v_max_f32_e32 v12, 0, v12
	v_max_f32_e32 v13, 0, v13
	global_store_dwordx4 v[32:33], v[24:27], off
	v_max_f32_e32 v20, v20, v20
	v_max_f32_e32 v21, v21, v21
	v_pk_mul_f32 v[24:25], v[12:13], v[12:13]
	v_max_f32_e32 v13, v14, v14
	v_max_f32_e32 v12, v22, v22
	v_max_f32_e32 v14, 0, v13
	v_max_f32_e32 v13, v23, v23
	v_max_f32_e32 v15, v15, v15
	v_mfma_f32_16x16x32_bf16 v[8:11], v[154:157], v[134:137], v[8:11]
	v_max_f32_e32 v20, 0, v20
	v_max_f32_e32 v21, 0, v21
	v_max_f32_e32 v12, 0, v12
	v_max_f32_e32 v13, 0, v13
	v_max_f32_e32 v15, 0, v15
	v_pk_mul_f32 v[20:21], v[20:21], v[20:21]
	v_pk_mul_f32 v[22:23], v[12:13], v[12:13]
	v_pk_mul_f32 v[26:27], v[14:15], v[14:15]
	v_max_f32_e32 v4, v4, v4
	v_max_f32_e32 v5, v5, v5
	v_cvt_pk_bf16_f32 v12, v20, v21
	v_cvt_pk_bf16_f32 v13, v22, v23
	v_cvt_pk_bf16_f32 v14, v24, v25
	v_cvt_pk_bf16_f32 v15, v26, v27
	v_max_f32_e32 v4, 0, v4
	v_max_f32_e32 v5, 0, v5
	global_store_dwordx4 v[32:33], v[12:15], off offset:64
	v_mfma_f32_16x16x32_bf16 v[0:3], v[74:77], v[134:137], v[0:3]
	v_max_f32_e32 v8, v8, v8
	v_pk_mul_f32 v[12:13], v[4:5], v[4:5]
	v_max_f32_e32 v5, v6, v6
	v_mfma_f32_16x16x32_bf16 v[16:19], v[162:165], v[134:137], v[16:19]
	v_max_f32_e32 v9, v9, v9
	v_max_f32_e32 v4, v10, v10
	v_max_f32_e32 v6, 0, v5
	v_max_f32_e32 v5, v11, v11
	v_max_f32_e32 v7, v7, v7
	v_max_f32_e32 v8, 0, v8
	v_max_f32_e32 v9, 0, v9
	v_max_f32_e32 v4, 0, v4
	v_max_f32_e32 v5, 0, v5
	v_max_f32_e32 v7, 0, v7
	v_pk_mul_f32 v[8:9], v[8:9], v[8:9]
	v_pk_mul_f32 v[10:11], v[4:5], v[4:5]
	v_pk_mul_f32 v[14:15], v[6:7], v[6:7]
	v_cvt_pk_bf16_f32 v4, v8, v9
	v_cvt_pk_bf16_f32 v5, v10, v11
	v_cvt_pk_bf16_f32 v6, v12, v13
	v_cvt_pk_bf16_f32 v7, v14, v15
	global_store_dwordx4 v[32:33], v[4:7], off offset:128
	v_max_f32_e32 v0, v0, v0
	v_max_f32_e32 v1, v1, v1
	v_max_f32_e32 v4, v16, v16
	v_max_f32_e32 v5, v17, v17
	v_max_f32_e32 v2, v2, v2
	v_max_f32_e32 v6, v18, v18
	v_max_f32_e32 v3, v3, v3
	v_max_f32_e32 v7, v19, v19
	v_max_f32_e32 v0, 0, v0
	v_max_f32_e32 v4, 0, v4
	v_max_f32_e32 v1, 0, v1
	v_max_f32_e32 v5, 0, v5
	v_max_f32_e32 v2, 0, v2
	v_max_f32_e32 v6, 0, v6
	v_max_f32_e32 v3, 0, v3
	v_max_f32_e32 v7, 0, v7
	v_pk_mul_f32 v[0:1], v[0:1], v[0:1]
	v_pk_mul_f32 v[4:5], v[4:5], v[4:5]
	v_pk_mul_f32 v[2:3], v[2:3], v[2:3]
	v_pk_mul_f32 v[6:7], v[6:7], v[6:7]
	v_cvt_pk_bf16_f32 v0, v0, v1
	v_cvt_pk_bf16_f32 v1, v2, v3
	v_cvt_pk_bf16_f32 v2, v4, v5
	v_cvt_pk_bf16_f32 v3, v6, v7
	global_store_dwordx4 v[32:33], v[0:3], off offset:192
	s_cbranch_scc0 .LBB0_1754

.LBB0_1823:
	s_ashr_i32 s28, s37, 3
	s_add_i32 s28, s39, s28
	s_ashr_i32 s29, s28, 31
	s_lshr_b32 s29, s29, 26
	s_add_i32 s29, s28, s29
	s_ashr_i32 s38, s29, 6
	s_and_b32 s29, s29, 0xffc0
	s_sub_i32 s28, s28, s29
	s_bfe_i32 s29, s28, 0x80000
	s_bfe_u32 s29, s29, 0x3000c
	s_add_i32 s29, s28, s29
	s_bfe_i32 s37, s29, 0x80000
	s_and_b32 s29, s29, 0xf8
	s_sub_i32 s28, s28, s29
	s_lshl_b32 s38, s38, 3
	s_sext_i32_i8 s28, s28
	s_add_i32 s28, s38, s28
	s_ashr_i32 s29, s28, 31
	s_lshr_b32 s29, s29, 26
	s_add_i32 s29, s28, s29
	s_sext_i32_i16 s37, s37
	s_ashr_i32 s38, s29, 6
	s_andn2_b32 s29, s29, 63
	s_ashr_i32 s37, s37, 3
	s_mulk_i32 s38, 0x42
	s_sub_i32 s28, s28, s29
	s_add_i32 s38, s28, s38
	s_mul_i32 s28, s37, 0x82000
	s_add_i32 s38, s38, 2
	s_ashr_i32 s29, s28, 31
	v_readfirstlane_b32 s39, v91
	v_mad_i64_i32 v[0:1], s[40:41], s38, v90, v[64:65]
	s_lshl_b64 s[28:29], s[28:29], 1
	s_mov_b32 m0, s39
	v_readfirstlane_b32 s39, v92
	v_lshl_add_u64 v[2:3], v[66:67], 0, s[28:29]
	s_waitcnt lgkmcnt(0)
	s_barrier
	global_load_lds_dwordx4 v[0:1], off
	s_mov_b32 m0, s39
	v_readfirstlane_b32 s39, v93
	global_load_lds_dwordx4 v[2:3], off
	v_lshl_add_u64 v[4:5], v[0:1], 0, s[4:5]
	s_mov_b32 m0, s39
	v_readfirstlane_b32 s39, v94
	global_load_lds_dwordx4 v[4:5], off
	v_lshl_add_u64 v[4:5], v[2:3], 0, s[4:5]
	s_mov_b32 m0, s39
	v_readfirstlane_b32 s39, v95
	global_load_lds_dwordx4 v[4:5], off
	v_lshl_add_u64 v[4:5], v[0:1], 0, s[6:7]
	s_mov_b32 m0, s39
	v_readfirstlane_b32 s39, v96
	global_load_lds_dwordx4 v[4:5], off
	v_lshl_add_u64 v[4:5], v[2:3], 0, s[6:7]
	s_mov_b32 m0, s39
	v_readfirstlane_b32 s39, v97
	global_load_lds_dwordx4 v[4:5], off
	v_lshl_add_u64 v[0:1], v[0:1], 0, s[8:9]
	s_mov_b32 m0, s39
	v_readfirstlane_b32 s39, v98
	global_load_lds_dwordx4 v[0:1], off
	v_lshl_add_u64 v[0:1], v[2:3], 0, s[8:9]
	s_mov_b32 m0, s39
	v_mov_b32_e32 v36, 0
	global_load_lds_dwordx4 v[0:1], off
	v_mad_i64_i32 v[72:73], s[40:41], s38, v90, v[68:69]
	v_lshl_add_u64 v[74:75], v[70:71], 0, s[28:29]
	s_mov_b64 s[28:29], 0
	s_mov_b32 s39, 0
	v_mov_b32_e32 v37, v36
	v_mov_b32_e32 v38, v36
	v_mov_b32_e32 v39, v36
	v_mov_b32_e32 v0, v36
	v_mov_b32_e32 v1, v36
	v_mov_b32_e32 v2, v36
	v_mov_b32_e32 v3, v36
	v_mov_b32_e32 v4, v36
	v_mov_b32_e32 v5, v36
	v_mov_b32_e32 v6, v36
	v_mov_b32_e32 v7, v36
	v_mov_b32_e32 v8, v36
	v_mov_b32_e32 v9, v36
	v_mov_b32_e32 v10, v36
	v_mov_b32_e32 v11, v36
	v_mov_b32_e32 v12, v36
	v_mov_b32_e32 v13, v36
	v_mov_b32_e32 v14, v36
	v_mov_b32_e32 v15, v36
	v_mov_b32_e32 v16, v36
	v_mov_b32_e32 v17, v36
	v_mov_b32_e32 v18, v36
	v_mov_b32_e32 v19, v36
	v_mov_b32_e32 v20, v36
	v_mov_b32_e32 v21, v36
	v_mov_b32_e32 v22, v36
	v_mov_b32_e32 v23, v36
	v_mov_b32_e32 v24, v36
	v_mov_b32_e32 v25, v36
	v_mov_b32_e32 v26, v36
	v_mov_b32_e32 v27, v36
	v_mov_b32_e32 v28, v36
	v_mov_b32_e32 v29, v36
	v_mov_b32_e32 v30, v36
	v_mov_b32_e32 v31, v36
	v_mov_b32_e32 v32, v36
	v_mov_b32_e32 v33, v36
	v_mov_b32_e32 v34, v36
	v_mov_b32_e32 v35, v36
	v_mov_b32_e32 v40, v36
	v_mov_b32_e32 v41, v36
	v_mov_b32_e32 v42, v36
	v_mov_b32_e32 v43, v36
	v_mov_b32_e32 v44, v36
	v_mov_b32_e32 v45, v36
	v_mov_b32_e32 v46, v36
	v_mov_b32_e32 v47, v36
	v_mov_b32_e32 v48, v36
	v_mov_b32_e32 v49, v36
	v_mov_b32_e32 v50, v36
	v_mov_b32_e32 v51, v36
	v_mov_b32_e32 v52, v36
	v_mov_b32_e32 v53, v36
	v_mov_b32_e32 v54, v36
	v_mov_b32_e32 v55, v36
	v_mov_b32_e32 v56, v36
	v_mov_b32_e32 v57, v36
	v_mov_b32_e32 v58, v36
	v_mov_b32_e32 v59, v36
	v_mov_b32_e32 v60, v36
	v_mov_b32_e32 v61, v36
	v_mov_b32_e32 v62, v36
	v_mov_b32_e32 v63, v36
	v_readfirstlane_b32 s96, v72
	v_readfirstlane_b32 s97, v73
	v_readfirstlane_b32 s88, v74
	v_readfirstlane_b32 s89, v75
	v_readfirstlane_b32 s87, v82
	s_nop 1
	v_subrev_u32_e32 v244, s96, v72
	v_subrev_u32_e32 v245, s88, v74
	v_add_u32_e32 v246, 0x41000, v244
	v_add_u32_e32 v247, 0x41000, v245
	v_add_u32_e32 v248, 0x82000, v244
	v_add_u32_e32 v249, 0x82000, v245
	v_add_u32_e32 v250, 0xc3000, v244
	v_add_u32_e32 v251, 0xc3000, v245
	s_add_u32 s96, s96, 0x4510080
	s_addc_u32 s97, s97, 0
	s_add_u32 s88, s88, 0xeba0080
	s_addc_u32 s89, s89, 0
	s_add_u32 s86, s87, 0x8000
	s_mov_b32 m0, s86
	s_nop 0
	global_load_lds_dwordx4 v244, s[96:97]
	s_add_u32 m0, s86, 0x4000
	s_nop 0
	global_load_lds_dwordx4 v245, s[88:89]
	s_add_u32 m0, s86, 0x1000
	s_nop 0
	global_load_lds_dwordx4 v246, s[96:97]
	s_add_u32 m0, s86, 0x5000
	s_nop 0
	global_load_lds_dwordx4 v247, s[88:89]
	s_add_u32 m0, s86, 0x2000
	s_nop 0
	global_load_lds_dwordx4 v248, s[96:97]
	s_add_u32 m0, s86, 0x6000
	s_nop 0
	global_load_lds_dwordx4 v249, s[88:89]
	s_add_u32 m0, s86, 0x3000
	s_nop 0
	global_load_lds_dwordx4 v250, s[96:97]
	s_add_u32 m0, s86, 0x7000
	s_nop 0
	global_load_lds_dwordx4 v251, s[88:89]
	s_add_u32 s96, s96, 0x80
	s_addc_u32 s97, s97, 0
	s_add_u32 s88, s88, 0x80
	s_addc_u32 s89, s89, 0
.LBB0_1824:
	s_add_i32 s41, s39, 0x8000
	s_and_b32 s40, s41, 0x8000
	s_add_i32 s40, s40, 0
	s_and_b32 s39, s39, 0x8000
	s_add_i32 s39, s39, 0
	s_add_u32 s86, s39, s87
	s_waitcnt vmcnt(8)
	s_barrier
	v_add3_u32 v145, s39, v84, v85
	v_add3_u32 v178, s39, v85, v86
	v_add3_u32 v179, s39, v84, v87
	v_add3_u32 v180, s39, v86, v87
	ds_read_b128 v[104:107], v178
	ds_read_b128 v[76:79], v145 offset:16384
	ds_read_b128 v[100:103], v145 offset:18432
	ds_read_b128 v[108:111], v178 offset:2048
	ds_read_b128 v[112:115], v145 offset:20480
	ds_read_b128 v[116:119], v145 offset:22528
	ds_read_b128 v[120:123], v145 offset:24576
	ds_read_b128 v[124:127], v145 offset:26624
	ds_read_b128 v[128:131], v145 offset:28672
	ds_read_b128 v[132:135], v145 offset:30720
	ds_read_b128 v[146:149], v180
	ds_read_b128 v[136:139], v179 offset:16384
	ds_read_b128 v[140:143], v179 offset:18432
	ds_read_b128 v[150:153], v180 offset:2048
	ds_read_b128 v[154:157], v179 offset:20480
	ds_read_b128 v[158:161], v179 offset:22528
	ds_read_b128 v[162:165], v179 offset:24576
	ds_read_b128 v[166:169], v179 offset:26624
	ds_read_b128 v[170:173], v179 offset:28672
	ds_read_b128 v[174:177], v179 offset:30720
	s_waitcnt lgkmcnt(0)
	s_barrier
	s_cmpk_eq_i32 s28, 0x1f00
	s_cbranch_scc1 .Lgskip_1824
	s_mov_b32 m0, s86
	s_nop 0
	global_load_lds_dwordx4 v244, s[96:97]
	s_add_u32 m0, s86, 0x4000
	s_nop 0
	global_load_lds_dwordx4 v245, s[88:89]
	s_add_u32 m0, s86, 0x1000
	s_nop 0
	global_load_lds_dwordx4 v246, s[96:97]
	s_add_u32 m0, s86, 0x5000
	s_nop 0
	global_load_lds_dwordx4 v247, s[88:89]
	s_add_u32 m0, s86, 0x2000
	s_nop 0
	global_load_lds_dwordx4 v248, s[96:97]
	s_add_u32 m0, s86, 0x6000
	s_nop 0
	global_load_lds_dwordx4 v249, s[88:89]
	s_add_u32 m0, s86, 0x3000
	s_nop 0
	global_load_lds_dwordx4 v250, s[96:97]
	s_add_u32 m0, s86, 0x7000
	s_nop 0
	global_load_lds_dwordx4 v251, s[88:89]
	s_add_u32 s96, s96, 0x80
	s_addc_u32 s97, s97, 0
	s_add_u32 s88, s88, 0x80
	s_addc_u32 s89, s89, 0
.Lgskip_1824:
	s_add_u32 s28, s28, 0x80
	s_addc_u32 s29, s29, 0
	s_cmpk_eq_i32 s28, 0x1f80
	s_mov_b32 s39, s41
	v_mfma_f32_16x16x32_bf16 v[60:63], v[76:79], v[104:107], v[60:63]
	v_mfma_f32_16x16x32_bf16 v[56:59], v[100:103], v[104:107], v[56:59]
	v_mfma_f32_16x16x32_bf16 v[24:27], v[76:79], v[108:111], v[24:27]
	v_mfma_f32_16x16x32_bf16 v[20:23], v[100:103], v[108:111], v[20:23]
	v_mfma_f32_16x16x32_bf16 v[52:55], v[112:115], v[104:107], v[52:55]
	v_mfma_f32_16x16x32_bf16 v[16:19], v[112:115], v[108:111], v[16:19]
	v_mfma_f32_16x16x32_bf16 v[48:51], v[116:119], v[104:107], v[48:51]
	v_mfma_f32_16x16x32_bf16 v[12:15], v[116:119], v[108:111], v[12:15]
	v_mfma_f32_16x16x32_bf16 v[44:47], v[120:123], v[104:107], v[44:47]
	v_mfma_f32_16x16x32_bf16 v[8:11], v[120:123], v[108:111], v[8:11]
	v_mfma_f32_16x16x32_bf16 v[40:43], v[124:127], v[104:107], v[40:43]
	v_mfma_f32_16x16x32_bf16 v[4:7], v[124:127], v[108:111], v[4:7]
	v_mfma_f32_16x16x32_bf16 v[32:35], v[128:131], v[104:107], v[32:35]
	v_mfma_f32_16x16x32_bf16 v[0:3], v[128:131], v[108:111], v[0:3]
	v_mfma_f32_16x16x32_bf16 v[28:31], v[132:135], v[104:107], v[28:31]
	v_mfma_f32_16x16x32_bf16 v[36:39], v[132:135], v[108:111], v[36:39]
	v_mfma_f32_16x16x32_bf16 v[60:63], v[136:139], v[146:149], v[60:63]
	v_mfma_f32_16x16x32_bf16 v[56:59], v[140:143], v[146:149], v[56:59]
	v_mfma_f32_16x16x32_bf16 v[24:27], v[136:139], v[150:153], v[24:27]
	v_mfma_f32_16x16x32_bf16 v[20:23], v[140:143], v[150:153], v[20:23]
	v_mfma_f32_16x16x32_bf16 v[52:55], v[154:157], v[146:149], v[52:55]
	v_mfma_f32_16x16x32_bf16 v[16:19], v[154:157], v[150:153], v[16:19]
	v_mfma_f32_16x16x32_bf16 v[48:51], v[158:161], v[146:149], v[48:51]
	v_mfma_f32_16x16x32_bf16 v[12:15], v[158:161], v[150:153], v[12:15]
	v_mfma_f32_16x16x32_bf16 v[44:47], v[162:165], v[146:149], v[44:47]
	v_mfma_f32_16x16x32_bf16 v[8:11], v[162:165], v[150:153], v[8:11]
	v_mfma_f32_16x16x32_bf16 v[40:43], v[166:169], v[146:149], v[40:43]
	v_mfma_f32_16x16x32_bf16 v[4:7], v[166:169], v[150:153], v[4:7]
	v_mfma_f32_16x16x32_bf16 v[32:35], v[170:173], v[146:149], v[32:35]
	v_mfma_f32_16x16x32_bf16 v[0:3], v[170:173], v[150:153], v[0:3]
	v_mfma_f32_16x16x32_bf16 v[28:31], v[174:177], v[146:149], v[28:31]
	v_mfma_f32_16x16x32_bf16 v[36:39], v[174:177], v[150:153], v[36:39]
	s_cbranch_scc0 .LBB0_1824
	v_add_u32_e32 v80, s40, v84
	v_add_u32_e32 v81, v80, v85
	s_waitcnt vmcnt(0)
	s_barrier
	ds_read_b128 v[72:75], v81 offset:16384
	v_add3_u32 v99, s40, v85, v86
	ds_read_b128 v[76:79], v81 offset:18432
	ds_read_b128 v[100:103], v99
	ds_read_b128 v[104:107], v99 offset:2048
	ds_read_b128 v[108:111], v81 offset:20480
	ds_read_b128 v[112:115], v81 offset:22528
	ds_read_b128 v[116:119], v81 offset:24576
	ds_read_b128 v[120:123], v81 offset:26624
	ds_read_b128 v[124:127], v81 offset:28672
	ds_read_b128 v[128:131], v81 offset:30720
	v_add_u32_e32 v80, v80, v87
	s_waitcnt lgkmcnt(7)
	v_mfma_f32_16x16x32_bf16 v[60:63], v[72:75], v[100:103], v[60:63]
	s_lshl_b32 s38, s38, 7
	v_mfma_f32_16x16x32_bf16 v[56:59], v[76:79], v[100:103], v[56:59]
	s_waitcnt lgkmcnt(4)
	v_mfma_f32_16x16x32_bf16 v[48:51], v[112:115], v[100:103], v[48:51]
	s_waitcnt lgkmcnt(3)
	v_mfma_f32_16x16x32_bf16 v[44:47], v[116:119], v[100:103], v[44:47]
	s_waitcnt lgkmcnt(2)
	v_mfma_f32_16x16x32_bf16 v[40:43], v[120:123], v[100:103], v[40:43]
	s_waitcnt lgkmcnt(1)
	v_mfma_f32_16x16x32_bf16 v[32:35], v[124:127], v[100:103], v[32:35]
	s_waitcnt lgkmcnt(0)
	v_mfma_f32_16x16x32_bf16 v[28:31], v[128:131], v[100:103], v[28:31]
	v_mfma_f32_16x16x32_bf16 v[24:27], v[72:75], v[104:107], v[24:27]
	ds_read_b128 v[72:75], v80 offset:16384
	v_mfma_f32_16x16x32_bf16 v[52:55], v[108:111], v[100:103], v[52:55]
	v_mfma_f32_16x16x32_bf16 v[20:23], v[76:79], v[104:107], v[20:23]
	v_mfma_f32_16x16x32_bf16 v[16:19], v[108:111], v[104:107], v[16:19]
	v_mfma_f32_16x16x32_bf16 v[12:15], v[112:115], v[104:107], v[12:15]
	v_mfma_f32_16x16x32_bf16 v[8:11], v[116:119], v[104:107], v[8:11]
	v_mfma_f32_16x16x32_bf16 v[4:7], v[120:123], v[104:107], v[4:7]
	v_mfma_f32_16x16x32_bf16 v[0:3], v[124:127], v[104:107], v[0:3]
	v_mfma_f32_16x16x32_bf16 v[100:103], v[128:131], v[104:107], v[36:39]
	s_nop 2
	v_add3_u32 v36, s40, v87, v86
	ds_read_b128 v[76:79], v80 offset:18432
	ds_read_b128 v[104:107], v36
	ds_read_b128 v[108:111], v36 offset:2048
	ds_read_b128 v[128:131], v80 offset:28672
	ds_read_b128 v[132:135], v80 offset:30720
	ds_read_b128 v[112:115], v80 offset:20480
	ds_read_b128 v[116:119], v80 offset:22528
	ds_read_b128 v[120:123], v80 offset:24576
	ds_read_b128 v[124:127], v80 offset:26624
	s_waitcnt lgkmcnt(7)
	v_mfma_f32_16x16x32_bf16 v[60:63], v[72:75], v[104:107], v[60:63]
	s_waitcnt lgkmcnt(5)
	v_mfma_f32_16x16x32_bf16 v[36:39], v[128:131], v[104:107], v[32:35]
	s_waitcnt lgkmcnt(4)
	v_mfma_f32_16x16x32_bf16 v[32:35], v[132:135], v[104:107], v[28:31]
	v_mfma_f32_16x16x32_bf16 v[28:31], v[72:75], v[108:111], v[24:27]
	v_add_u32_e32 v72, s38, v83
	v_mul_hi_i32 v73, v72, s31
	v_mfma_f32_16x16x32_bf16 v[24:27], v[76:79], v[108:111], v[20:23]
	s_waitcnt lgkmcnt(3)
	v_mfma_f32_16x16x32_bf16 v[20:23], v[112:115], v[108:111], v[16:19]
	s_waitcnt lgkmcnt(2)
	v_mfma_f32_16x16x32_bf16 v[16:19], v[116:119], v[108:111], v[12:15]
	s_waitcnt lgkmcnt(1)
	v_mfma_f32_16x16x32_bf16 v[12:15], v[120:123], v[108:111], v[8:11]
	s_waitcnt lgkmcnt(0)
	v_mfma_f32_16x16x32_bf16 v[8:11], v[124:127], v[108:111], v[4:7]
	s_nop 2
	v_lshrrev_b32_e32 v4, 31, v73
	v_ashrrev_i32_e32 v5, 11, v73
	v_mfma_f32_16x16x32_bf16 v[56:59], v[76:79], v[104:107], v[56:59]
	v_add_u32_e32 v73, v5, v4
	v_mad_i32_i24 v78, v73, s33, v72
	v_lshlrev_b32_e32 v75, 13, v73
	v_mfma_f32_16x16x32_bf16 v[52:55], v[112:115], v[104:107], v[52:55]
	v_cmp_lt_i32_e32 vcc, s34, v78
	v_add3_u32 v74, v75, v78, s35
	v_mfma_f32_16x16x32_bf16 v[48:51], v[116:119], v[104:107], v[48:51]
	v_mfma_f32_16x16x32_bf16 v[44:47], v[120:123], v[104:107], v[44:47]
	v_mfma_f32_16x16x32_bf16 v[40:43], v[124:127], v[104:107], v[40:43]
	v_mfma_f32_16x16x32_bf16 v[4:7], v[128:131], v[108:111], v[0:3]
	v_mfma_f32_16x16x32_bf16 v[0:3], v[132:135], v[108:111], v[100:103]
	s_and_saveexec_b64 s[28:29], vcc
	s_xor_b64 s[28:29], exec, s[28:29]
	v_add3_u32 v72, v75, v78, s35
	s_or_saveexec_b64 s[28:29], s[28:29]
	v_mov_b64_e32 v[76:77], s[92:93]
	v_lshl_add_u32 v75, v73, 8, v78
	s_xor_b64 exec, exec, s[28:29]
	v_lshl_add_u32 v72, v73, 8, v78
	v_mov_b64_e32 v[76:77], s[2:3]
	s_or_b64 exec, exec, s[28:29]
	s_and_saveexec_b64 s[28:29], vcc
	s_xor_b64 s[28:29], exec, s[28:29]
	s_cbranch_execz .LBB0_1831
	v_add_u32_e32 v73, 3, v73
	v_mul_hi_i32_i24_e32 v79, 0x6000, v73
	v_mul_i32_i24_e32 v78, 0x6000, v73
	s_or_saveexec_b64 s[28:29], s[28:29]
	v_mov_b64_e32 v[80:81], s[92:93]
	s_xor_b64 exec, exec, s[28:29]
	s_cbranch_execnz .LBB0_1832
	s_branch .LBB0_1833
